# v79 + K-loops: M0 wait states filled by a moved ds_read instead of s_nop (30 sites)
# speedup vs baseline: 1.0058x; 1.0022x over previous
.LBB0_266:
	s_xor_b64 s[2:3], s[2:3], -1
	s_mov_b32 s34, s74
	s_add_i32 s74, s74, 1
	s_cmp_lt_u32 s34, 5
	s_mov_b64 s[4:5], s[10:11]
	s_mov_b32 s10, s75
	s_cselect_b64 s[14:15], -1, 0
	s_add_i32 s75, s74, s16
	s_mov_b64 s[12:13], s[8:9]
	s_and_b64 s[8:9], s[14:15], exec
	s_cselect_b32 s8, s75, s10
	s_cselect_b32 s10, s6, s6
	s_ashr_i32 s11, s10, 31
	s_lshl_b64 s[10:11], s[10:11], 19
	s_add_u32 s10, s80, s10
	s_addc_u32 s11, s81, s11
	s_and_b64 s[44:45], s[14:15], exec
	s_cselect_b32 s44, s11, s5
	s_cselect_b32 s45, s10, s4
	s_ashr_i32 s9, s8, 31
	s_lshl_b64 s[8:9], s[8:9], 19
	v_readlane_b32 s47, v255, 14
	s_add_u32 s8, s47, s8
	v_readlane_b32 s47, v255, 15
	s_addc_u32 s9, s47, s9
	s_and_b64 s[14:15], s[14:15], exec
	s_cselect_b32 s47, s9, s13
	s_cselect_b32 s55, s8, s12
	s_add_u32 s4, s4, 0x40080
	s_addc_u32 s5, s5, 0
	s_add_u32 s78, s12, 0x100
	s_addc_u32 s79, s13, 0
	s_mov_b32 s85, -2
	s_waitcnt lgkmcnt(0)
	s_add_i32 s86, 0, 0x10000
	v_add_u32_e32 v0, s86, v150
	v_add_u32_e32 v189, 0x10000, v150
	ds_read_b128 v[142:145], v0
	ds_read_b128 v[146:149], v0 offset:1024
	ds_read_b128 v[152:155], v0 offset:2048
	ds_read_b128 v[156:159], v0 offset:3072
	s_add_u32 s12, s4, 0xfffc0080
	s_addc_u32 s13, s5, -1
	s_cmp_eq_u32 s85, 12
	s_cselect_b32 s15, s44, s13
	s_cselect_b32 s14, s45, s12
	s_cselect_b32 s13, s47, s79
	s_cselect_b32 s12, s55, s78
	s_add_i32 m0, s7, 0xc000
	ds_read_b128 v[160:163], v151
	ds_read_b128 v[164:167], v151 offset:1024
	ds_read_b128 v[168:171], v151 offset:2048
	ds_read_b128 v[172:175], v151 offset:3072
	ds_read_b128 v[176:179], v151 offset:4096
	ds_read_b128 v[180:183], v151 offset:5120
	ds_read_b128 v[184:187], v151 offset:6144
	global_load_lds_dwordx4 v138, s[4:5]
	s_add_i32 m0, s7, 0xe000
	ds_read_b128 v[190:193], v151 offset:7168
	global_load_lds_dwordx4 v140, s[4:5]
	s_waitcnt lgkmcnt(8)
	s_barrier
	s_waitcnt lgkmcnt(0)
	v_mfma_f32_16x16x32_bf16 v[126:129], v[142:145], v[160:163], 0
	v_mfma_f32_16x16x32_bf16 v[122:125], v[152:155], v[160:163], 0
	v_mfma_f32_16x16x32_bf16 v[110:113], v[142:145], v[168:171], 0
	v_mfma_f32_16x16x32_bf16 v[106:109], v[152:155], v[168:171], 0
	v_mfma_f32_16x16x32_bf16 v[94:97], v[142:145], v[176:179], 0
	v_mfma_f32_16x16x32_bf16 v[90:93], v[152:155], v[176:179], 0
	v_mfma_f32_16x16x32_bf16 v[78:81], v[142:145], v[184:187], 0
	v_mfma_f32_16x16x32_bf16 v[74:77], v[152:155], v[184:187], 0
	v_mfma_f32_16x16x32_bf16 v[126:129], v[146:149], v[164:167], v[126:129]
	v_mfma_f32_16x16x32_bf16 v[122:125], v[156:159], v[164:167], v[122:125]
	v_mfma_f32_16x16x32_bf16 v[110:113], v[146:149], v[172:175], v[110:113]
	v_mfma_f32_16x16x32_bf16 v[106:109], v[156:159], v[172:175], v[106:109]
	v_mfma_f32_16x16x32_bf16 v[94:97], v[146:149], v[180:183], v[94:97]
	v_mfma_f32_16x16x32_bf16 v[90:93], v[156:159], v[180:183], v[90:93]
	v_mfma_f32_16x16x32_bf16 v[78:81], v[146:149], v[190:193], v[78:81]
	v_mfma_f32_16x16x32_bf16 v[74:77], v[156:159], v[190:193], v[74:77]
	s_barrier
	s_add_i32 m0, s22, 0x10000
	ds_read_b128 v[194:197], v189 offset:16384
	ds_read_b128 v[198:201], v189 offset:17408
	ds_read_b128 v[202:205], v189 offset:18432
	global_load_lds_dwordx4 v134, s[12:13]
	s_add_i32 m0, s22, 0x12000
	ds_read_b128 v[206:209], v189 offset:19456
	global_load_lds_dwordx4 v130, s[12:13]
	s_barrier
	s_waitcnt lgkmcnt(0)
	v_mfma_f32_16x16x32_bf16 v[118:121], v[194:197], v[160:163], 0
	v_mfma_f32_16x16x32_bf16 v[114:117], v[202:205], v[160:163], 0
	v_mfma_f32_16x16x32_bf16 v[102:105], v[194:197], v[168:171], 0
	v_mfma_f32_16x16x32_bf16 v[98:101], v[202:205], v[168:171], 0
	v_mfma_f32_16x16x32_bf16 v[86:89], v[194:197], v[176:179], 0
	v_mfma_f32_16x16x32_bf16 v[82:85], v[202:205], v[176:179], 0
	v_mfma_f32_16x16x32_bf16 v[70:73], v[194:197], v[184:187], 0
	v_mfma_f32_16x16x32_bf16 v[66:69], v[202:205], v[184:187], 0
	v_mfma_f32_16x16x32_bf16 v[118:121], v[198:201], v[164:167], v[118:121]
	v_mfma_f32_16x16x32_bf16 v[114:117], v[206:209], v[164:167], v[114:117]
	v_mfma_f32_16x16x32_bf16 v[102:105], v[198:201], v[172:175], v[102:105]
	v_mfma_f32_16x16x32_bf16 v[98:101], v[206:209], v[172:175], v[98:101]
	v_mfma_f32_16x16x32_bf16 v[86:89], v[198:201], v[180:183], v[86:89]
	v_mfma_f32_16x16x32_bf16 v[82:85], v[206:209], v[180:183], v[82:85]
	v_mfma_f32_16x16x32_bf16 v[70:73], v[198:201], v[190:193], v[70:73]
	v_mfma_f32_16x16x32_bf16 v[66:69], v[206:209], v[190:193], v[66:69]
	s_mov_b32 m0, s7
	s_mov_b64 s[100:101], s[14:15]
	s_barrier
	ds_read_b128 v[160:163], v151 offset:16384
	ds_read_b128 v[164:167], v151 offset:17408
	ds_read_b128 v[168:171], v151 offset:18432
	ds_read_b128 v[172:175], v151 offset:19456
	ds_read_b128 v[176:179], v151 offset:20480
	ds_read_b128 v[180:183], v151 offset:21504
	ds_read_b128 v[184:187], v151 offset:22528
	global_load_lds_dwordx4 v136, s[100:101]
	s_mov_b32 m0, s23
	ds_read_b128 v[190:193], v151 offset:23552
	global_load_lds_dwordx4 v132, s[100:101]
	s_waitcnt vmcnt(10)
	s_barrier
	s_waitcnt lgkmcnt(0)
	v_mfma_f32_16x16x32_bf16 v[62:65], v[142:145], v[160:163], 0
	v_mfma_f32_16x16x32_bf16 v[58:61], v[152:155], v[160:163], 0
	v_mfma_f32_16x16x32_bf16 v[46:49], v[142:145], v[168:171], 0
	v_mfma_f32_16x16x32_bf16 v[42:45], v[152:155], v[168:171], 0
	v_mfma_f32_16x16x32_bf16 v[30:33], v[142:145], v[176:179], 0
	v_mfma_f32_16x16x32_bf16 v[26:29], v[152:155], v[176:179], 0
	v_mfma_f32_16x16x32_bf16 v[14:17], v[142:145], v[184:187], 0
	v_mfma_f32_16x16x32_bf16 v[10:13], v[152:155], v[184:187], 0
	v_mfma_f32_16x16x32_bf16 v[62:65], v[146:149], v[164:167], v[62:65]
	v_mfma_f32_16x16x32_bf16 v[58:61], v[156:159], v[164:167], v[58:61]
	v_mfma_f32_16x16x32_bf16 v[46:49], v[146:149], v[172:175], v[46:49]
	v_mfma_f32_16x16x32_bf16 v[42:45], v[156:159], v[172:175], v[42:45]
	v_mfma_f32_16x16x32_bf16 v[30:33], v[146:149], v[180:183], v[30:33]
	v_mfma_f32_16x16x32_bf16 v[26:29], v[156:159], v[180:183], v[26:29]
	v_mfma_f32_16x16x32_bf16 v[14:17], v[146:149], v[190:193], v[14:17]
	v_mfma_f32_16x16x32_bf16 v[10:13], v[156:159], v[190:193], v[10:13]
	s_barrier
	s_add_u32 s86, s12, 0x40000
	s_addc_u32 s87, s13, 0
	s_add_i32 m0, s22, 0x14000
	s_nop 0
	global_load_lds_dwordx4 v134, s[86:87]
	s_add_i32 m0, s22, 0x16000
	s_nop 0
	global_load_lds_dwordx4 v130, s[86:87]
	ds_read_b128 v[142:145], v189 offset:32768
	ds_read_b128 v[146:149], v189 offset:33792
	ds_read_b128 v[152:155], v189 offset:34816
	ds_read_b128 v[156:159], v189 offset:35840
	s_waitcnt vmcnt(6)
	s_barrier
	v_mfma_f32_16x16x32_bf16 v[54:57], v[194:197], v[160:163], 0
	v_mfma_f32_16x16x32_bf16 v[50:53], v[202:205], v[160:163], 0
	v_mfma_f32_16x16x32_bf16 v[38:41], v[194:197], v[168:171], 0
	v_mfma_f32_16x16x32_bf16 v[34:37], v[202:205], v[168:171], 0
	v_mfma_f32_16x16x32_bf16 v[22:25], v[194:197], v[176:179], 0
	v_mfma_f32_16x16x32_bf16 v[18:21], v[202:205], v[176:179], 0
	v_mfma_f32_16x16x32_bf16 v[6:9], v[194:197], v[184:187], 0
	v_mfma_f32_16x16x32_bf16 v[2:5], v[202:205], v[184:187], 0
	v_mfma_f32_16x16x32_bf16 v[54:57], v[198:201], v[164:167], v[54:57]
	v_mfma_f32_16x16x32_bf16 v[50:53], v[206:209], v[164:167], v[50:53]
	v_mfma_f32_16x16x32_bf16 v[38:41], v[198:201], v[172:175], v[38:41]
	v_mfma_f32_16x16x32_bf16 v[34:37], v[206:209], v[172:175], v[34:37]
	v_mfma_f32_16x16x32_bf16 v[22:25], v[198:201], v[180:183], v[22:25]
	v_mfma_f32_16x16x32_bf16 v[18:21], v[206:209], v[180:183], v[18:21]
	v_mfma_f32_16x16x32_bf16 v[6:9], v[198:201], v[190:193], v[6:9]
	v_mfma_f32_16x16x32_bf16 v[2:5], v[206:209], v[190:193], v[2:5]
	s_barrier
	s_add_u32 s14, s14, 0x40000
	s_addc_u32 s15, s15, 0
	s_mov_b32 m0, s28
	ds_read_b128 v[160:163], v151 offset:32768
	ds_read_b128 v[164:167], v151 offset:33792
	ds_read_b128 v[168:171], v151 offset:34816
	ds_read_b128 v[172:175], v151 offset:35840
	ds_read_b128 v[176:179], v151 offset:36864
	ds_read_b128 v[180:183], v151 offset:37888
	ds_read_b128 v[184:187], v151 offset:38912
	global_load_lds_dwordx4 v136, s[14:15]
	s_mov_b32 m0, s29
	ds_read_b128 v[190:193], v151 offset:39936
	global_load_lds_dwordx4 v132, s[14:15]
	s_waitcnt lgkmcnt(8)
	s_barrier
	s_waitcnt lgkmcnt(0)
	v_mfma_f32_16x16x32_bf16 v[126:129], v[142:145], v[160:163], v[126:129]
	v_mfma_f32_16x16x32_bf16 v[122:125], v[152:155], v[160:163], v[122:125]
	v_mfma_f32_16x16x32_bf16 v[110:113], v[142:145], v[168:171], v[110:113]
	v_mfma_f32_16x16x32_bf16 v[106:109], v[152:155], v[168:171], v[106:109]
	v_mfma_f32_16x16x32_bf16 v[94:97], v[142:145], v[176:179], v[94:97]
	v_mfma_f32_16x16x32_bf16 v[90:93], v[152:155], v[176:179], v[90:93]
	v_mfma_f32_16x16x32_bf16 v[78:81], v[142:145], v[184:187], v[78:81]
	v_mfma_f32_16x16x32_bf16 v[74:77], v[152:155], v[184:187], v[74:77]
	v_mfma_f32_16x16x32_bf16 v[126:129], v[146:149], v[164:167], v[126:129]
	v_mfma_f32_16x16x32_bf16 v[122:125], v[156:159], v[164:167], v[122:125]
	v_mfma_f32_16x16x32_bf16 v[110:113], v[146:149], v[172:175], v[110:113]
	v_mfma_f32_16x16x32_bf16 v[106:109], v[156:159], v[172:175], v[106:109]
	v_mfma_f32_16x16x32_bf16 v[94:97], v[146:149], v[180:183], v[94:97]
	v_mfma_f32_16x16x32_bf16 v[90:93], v[156:159], v[180:183], v[90:93]
	v_mfma_f32_16x16x32_bf16 v[78:81], v[146:149], v[190:193], v[78:81]
	v_mfma_f32_16x16x32_bf16 v[74:77], v[156:159], v[190:193], v[74:77]
	s_barrier
	s_add_i32 m0, s22, 0x18000
	ds_read_b128 v[194:197], v189 offset:49152
	ds_read_b128 v[198:201], v189 offset:50176
	ds_read_b128 v[202:205], v189 offset:51200
	ds_read_b128 v[206:209], v189 offset:52224
	s_add_u32 s98, s12, s40
	s_addc_u32 s99, s13, s41
	global_load_lds_dwordx4 v134, s[98:99]
	s_add_i32 m0, s22, 0x1a000
	s_nop 0
	global_load_lds_dwordx4 v130, s[98:99]
	s_barrier
	s_waitcnt lgkmcnt(0)
	v_mfma_f32_16x16x32_bf16 v[118:121], v[194:197], v[160:163], v[118:121]
	v_mfma_f32_16x16x32_bf16 v[114:117], v[202:205], v[160:163], v[114:117]
	v_mfma_f32_16x16x32_bf16 v[102:105], v[194:197], v[168:171], v[102:105]
	v_mfma_f32_16x16x32_bf16 v[98:101], v[202:205], v[168:171], v[98:101]
	v_mfma_f32_16x16x32_bf16 v[86:89], v[194:197], v[176:179], v[86:89]
	v_mfma_f32_16x16x32_bf16 v[82:85], v[202:205], v[176:179], v[82:85]
	v_mfma_f32_16x16x32_bf16 v[70:73], v[194:197], v[184:187], v[70:73]
	v_mfma_f32_16x16x32_bf16 v[66:69], v[202:205], v[184:187], v[66:69]
	v_mfma_f32_16x16x32_bf16 v[118:121], v[198:201], v[164:167], v[118:121]
	v_mfma_f32_16x16x32_bf16 v[114:117], v[206:209], v[164:167], v[114:117]
	v_mfma_f32_16x16x32_bf16 v[102:105], v[198:201], v[172:175], v[102:105]
	v_mfma_f32_16x16x32_bf16 v[98:101], v[206:209], v[172:175], v[98:101]
	v_mfma_f32_16x16x32_bf16 v[86:89], v[198:201], v[180:183], v[86:89]
	v_mfma_f32_16x16x32_bf16 v[82:85], v[206:209], v[180:183], v[82:85]
	v_mfma_f32_16x16x32_bf16 v[70:73], v[198:201], v[190:193], v[70:73]
	v_mfma_f32_16x16x32_bf16 v[66:69], v[206:209], v[190:193], v[66:69]
	s_mov_b32 m0, s38
	s_barrier
	ds_read_b128 v[160:163], v151 offset:49152
	ds_read_b128 v[164:167], v151 offset:50176
	ds_read_b128 v[168:171], v151 offset:51200
	ds_read_b128 v[172:175], v151 offset:52224
	ds_read_b128 v[176:179], v151 offset:53248
	ds_read_b128 v[180:183], v151 offset:54272
	ds_read_b128 v[184:187], v151 offset:55296
	ds_read_b128 v[190:193], v151 offset:56320
	s_add_u32 s98, s100, s40
	s_addc_u32 s99, s101, s41
	global_load_lds_dwordx4 v136, s[98:99]
	s_mov_b32 m0, s39
	s_nop 0
	global_load_lds_dwordx4 v132, s[98:99]
	s_waitcnt vmcnt(10)
	s_barrier
	s_waitcnt lgkmcnt(0)
	v_mfma_f32_16x16x32_bf16 v[62:65], v[142:145], v[160:163], v[62:65]
	v_mfma_f32_16x16x32_bf16 v[58:61], v[152:155], v[160:163], v[58:61]
	v_mfma_f32_16x16x32_bf16 v[46:49], v[142:145], v[168:171], v[46:49]
	v_mfma_f32_16x16x32_bf16 v[42:45], v[152:155], v[168:171], v[42:45]
	v_mfma_f32_16x16x32_bf16 v[30:33], v[142:145], v[176:179], v[30:33]
	v_mfma_f32_16x16x32_bf16 v[26:29], v[152:155], v[176:179], v[26:29]
	v_mfma_f32_16x16x32_bf16 v[14:17], v[142:145], v[184:187], v[14:17]
	v_mfma_f32_16x16x32_bf16 v[10:13], v[152:155], v[184:187], v[10:13]
	v_mfma_f32_16x16x32_bf16 v[62:65], v[146:149], v[164:167], v[62:65]
	v_mfma_f32_16x16x32_bf16 v[58:61], v[156:159], v[164:167], v[58:61]
	v_mfma_f32_16x16x32_bf16 v[46:49], v[146:149], v[172:175], v[46:49]
	v_mfma_f32_16x16x32_bf16 v[42:45], v[156:159], v[172:175], v[42:45]
	v_mfma_f32_16x16x32_bf16 v[30:33], v[146:149], v[180:183], v[30:33]
	v_mfma_f32_16x16x32_bf16 v[26:29], v[156:159], v[180:183], v[26:29]
	v_mfma_f32_16x16x32_bf16 v[14:17], v[146:149], v[190:193], v[14:17]
	v_mfma_f32_16x16x32_bf16 v[10:13], v[156:159], v[190:193], v[10:13]
	s_barrier
	s_add_u32 s12, s12, 0x40080
	s_addc_u32 s13, s13, 0
	s_add_i32 m0, s22, 0x1c000
	s_nop 0
	global_load_lds_dwordx4 v134, s[12:13]
	s_add_i32 m0, s22, 0x1e000
	s_nop 0
	global_load_lds_dwordx4 v130, s[12:13]
	ds_read_b128 v[142:145], v189
	ds_read_b128 v[146:149], v189 offset:1024
	ds_read_b128 v[152:155], v189 offset:2048
	ds_read_b128 v[156:159], v189 offset:3072
	s_waitcnt vmcnt(6)
	s_barrier
	v_mfma_f32_16x16x32_bf16 v[54:57], v[194:197], v[160:163], v[54:57]
	v_mfma_f32_16x16x32_bf16 v[50:53], v[202:205], v[160:163], v[50:53]
	v_mfma_f32_16x16x32_bf16 v[38:41], v[194:197], v[168:171], v[38:41]
	v_mfma_f32_16x16x32_bf16 v[34:37], v[202:205], v[168:171], v[34:37]
	v_mfma_f32_16x16x32_bf16 v[22:25], v[194:197], v[176:179], v[22:25]
	v_mfma_f32_16x16x32_bf16 v[18:21], v[202:205], v[176:179], v[18:21]
	v_mfma_f32_16x16x32_bf16 v[6:9], v[194:197], v[184:187], v[6:9]
	v_mfma_f32_16x16x32_bf16 v[2:5], v[202:205], v[184:187], v[2:5]
	v_mfma_f32_16x16x32_bf16 v[54:57], v[198:201], v[164:167], v[54:57]
	v_mfma_f32_16x16x32_bf16 v[50:53], v[206:209], v[164:167], v[50:53]
	v_mfma_f32_16x16x32_bf16 v[38:41], v[198:201], v[172:175], v[38:41]
	v_mfma_f32_16x16x32_bf16 v[34:37], v[206:209], v[172:175], v[34:37]
	v_mfma_f32_16x16x32_bf16 v[22:25], v[198:201], v[180:183], v[22:25]
	v_mfma_f32_16x16x32_bf16 v[18:21], v[206:209], v[180:183], v[18:21]
	v_mfma_f32_16x16x32_bf16 v[6:9], v[198:201], v[190:193], v[6:9]
	v_mfma_f32_16x16x32_bf16 v[2:5], v[206:209], v[190:193], v[2:5]
	s_add_i32 s85, s85, 2
	s_add_u32 s4, s4, 0x100
	s_addc_u32 s5, s5, 0
	s_add_u32 s78, s78, 0x100
	s_addc_u32 s79, s79, 0
	s_add_u32 s12, s4, 0xfffc0080
	s_addc_u32 s13, s5, -1
	s_cmp_eq_u32 s85, 12
	s_cselect_b32 s15, s44, s13
	s_cselect_b32 s14, s45, s12
	s_cselect_b32 s13, s47, s79
	s_cselect_b32 s12, s55, s78
	s_cmp_gt_u32 s85, 13
	s_barrier
.LBB0_267:
	s_add_i32 m0, s7, 0xc000
	ds_read_b128 v[160:163], v151
	ds_read_b128 v[164:167], v151 offset:1024
	ds_read_b128 v[168:171], v151 offset:2048
	ds_read_b128 v[172:175], v151 offset:3072
	ds_read_b128 v[176:179], v151 offset:4096
	ds_read_b128 v[180:183], v151 offset:5120
	ds_read_b128 v[184:187], v151 offset:6144
	global_load_lds_dwordx4 v138, s[4:5]
	s_add_i32 m0, s7, 0xe000
	ds_read_b128 v[190:193], v151 offset:7168
	global_load_lds_dwordx4 v140, s[4:5]
	s_waitcnt lgkmcnt(8)
	s_barrier
	s_waitcnt lgkmcnt(0)
	v_mfma_f32_16x16x32_bf16 v[126:129], v[142:145], v[160:163], v[126:129]
	v_mfma_f32_16x16x32_bf16 v[122:125], v[152:155], v[160:163], v[122:125]
	v_mfma_f32_16x16x32_bf16 v[110:113], v[142:145], v[168:171], v[110:113]
	v_mfma_f32_16x16x32_bf16 v[106:109], v[152:155], v[168:171], v[106:109]
	v_mfma_f32_16x16x32_bf16 v[94:97], v[142:145], v[176:179], v[94:97]
	v_mfma_f32_16x16x32_bf16 v[90:93], v[152:155], v[176:179], v[90:93]
	v_mfma_f32_16x16x32_bf16 v[78:81], v[142:145], v[184:187], v[78:81]
	v_mfma_f32_16x16x32_bf16 v[74:77], v[152:155], v[184:187], v[74:77]
	v_mfma_f32_16x16x32_bf16 v[126:129], v[146:149], v[164:167], v[126:129]
	v_mfma_f32_16x16x32_bf16 v[122:125], v[156:159], v[164:167], v[122:125]
	v_mfma_f32_16x16x32_bf16 v[110:113], v[146:149], v[172:175], v[110:113]
	v_mfma_f32_16x16x32_bf16 v[106:109], v[156:159], v[172:175], v[106:109]
	v_mfma_f32_16x16x32_bf16 v[94:97], v[146:149], v[180:183], v[94:97]
	v_mfma_f32_16x16x32_bf16 v[90:93], v[156:159], v[180:183], v[90:93]
	v_mfma_f32_16x16x32_bf16 v[78:81], v[146:149], v[190:193], v[78:81]
	v_mfma_f32_16x16x32_bf16 v[74:77], v[156:159], v[190:193], v[74:77]
	s_barrier
	s_add_i32 m0, s22, 0x10000
	ds_read_b128 v[194:197], v189 offset:16384
	ds_read_b128 v[198:201], v189 offset:17408
	ds_read_b128 v[202:205], v189 offset:18432
	global_load_lds_dwordx4 v134, s[12:13]
	s_add_i32 m0, s22, 0x12000
	ds_read_b128 v[206:209], v189 offset:19456
	global_load_lds_dwordx4 v130, s[12:13]
	s_barrier
	s_waitcnt lgkmcnt(0)
	v_mfma_f32_16x16x32_bf16 v[118:121], v[194:197], v[160:163], v[118:121]
	v_mfma_f32_16x16x32_bf16 v[114:117], v[202:205], v[160:163], v[114:117]
	v_mfma_f32_16x16x32_bf16 v[102:105], v[194:197], v[168:171], v[102:105]
	v_mfma_f32_16x16x32_bf16 v[98:101], v[202:205], v[168:171], v[98:101]
	v_mfma_f32_16x16x32_bf16 v[86:89], v[194:197], v[176:179], v[86:89]
	v_mfma_f32_16x16x32_bf16 v[82:85], v[202:205], v[176:179], v[82:85]
	v_mfma_f32_16x16x32_bf16 v[70:73], v[194:197], v[184:187], v[70:73]
	v_mfma_f32_16x16x32_bf16 v[66:69], v[202:205], v[184:187], v[66:69]
	v_mfma_f32_16x16x32_bf16 v[118:121], v[198:201], v[164:167], v[118:121]
	v_mfma_f32_16x16x32_bf16 v[114:117], v[206:209], v[164:167], v[114:117]
	v_mfma_f32_16x16x32_bf16 v[102:105], v[198:201], v[172:175], v[102:105]
	v_mfma_f32_16x16x32_bf16 v[98:101], v[206:209], v[172:175], v[98:101]
	v_mfma_f32_16x16x32_bf16 v[86:89], v[198:201], v[180:183], v[86:89]
	v_mfma_f32_16x16x32_bf16 v[82:85], v[206:209], v[180:183], v[82:85]
	v_mfma_f32_16x16x32_bf16 v[70:73], v[198:201], v[190:193], v[70:73]
	v_mfma_f32_16x16x32_bf16 v[66:69], v[206:209], v[190:193], v[66:69]
	s_mov_b32 m0, s7
	s_mov_b64 s[100:101], s[14:15]
	s_barrier
	ds_read_b128 v[160:163], v151 offset:16384
	ds_read_b128 v[164:167], v151 offset:17408
	ds_read_b128 v[168:171], v151 offset:18432
	ds_read_b128 v[172:175], v151 offset:19456
	ds_read_b128 v[176:179], v151 offset:20480
	ds_read_b128 v[180:183], v151 offset:21504
	ds_read_b128 v[184:187], v151 offset:22528
	global_load_lds_dwordx4 v136, s[100:101]
	s_mov_b32 m0, s23
	ds_read_b128 v[190:193], v151 offset:23552
	global_load_lds_dwordx4 v132, s[100:101]
	s_waitcnt vmcnt(10)
	s_barrier
	s_waitcnt lgkmcnt(0)
	v_mfma_f32_16x16x32_bf16 v[62:65], v[142:145], v[160:163], v[62:65]
	v_mfma_f32_16x16x32_bf16 v[58:61], v[152:155], v[160:163], v[58:61]
	v_mfma_f32_16x16x32_bf16 v[46:49], v[142:145], v[168:171], v[46:49]
	v_mfma_f32_16x16x32_bf16 v[42:45], v[152:155], v[168:171], v[42:45]
	v_mfma_f32_16x16x32_bf16 v[30:33], v[142:145], v[176:179], v[30:33]
	v_mfma_f32_16x16x32_bf16 v[26:29], v[152:155], v[176:179], v[26:29]
	v_mfma_f32_16x16x32_bf16 v[14:17], v[142:145], v[184:187], v[14:17]
	v_mfma_f32_16x16x32_bf16 v[10:13], v[152:155], v[184:187], v[10:13]
	v_mfma_f32_16x16x32_bf16 v[62:65], v[146:149], v[164:167], v[62:65]
	v_mfma_f32_16x16x32_bf16 v[58:61], v[156:159], v[164:167], v[58:61]
	v_mfma_f32_16x16x32_bf16 v[46:49], v[146:149], v[172:175], v[46:49]
	v_mfma_f32_16x16x32_bf16 v[42:45], v[156:159], v[172:175], v[42:45]
	v_mfma_f32_16x16x32_bf16 v[30:33], v[146:149], v[180:183], v[30:33]
	v_mfma_f32_16x16x32_bf16 v[26:29], v[156:159], v[180:183], v[26:29]
	v_mfma_f32_16x16x32_bf16 v[14:17], v[146:149], v[190:193], v[14:17]
	v_mfma_f32_16x16x32_bf16 v[10:13], v[156:159], v[190:193], v[10:13]
	s_barrier
	s_add_u32 s86, s12, 0x40000
	s_addc_u32 s87, s13, 0
	s_add_i32 m0, s22, 0x14000
	s_nop 0
	global_load_lds_dwordx4 v134, s[86:87]
	s_add_i32 m0, s22, 0x16000
	s_nop 0
	global_load_lds_dwordx4 v130, s[86:87]
	ds_read_b128 v[142:145], v189 offset:32768
	ds_read_b128 v[146:149], v189 offset:33792
	ds_read_b128 v[152:155], v189 offset:34816
	ds_read_b128 v[156:159], v189 offset:35840
	s_waitcnt vmcnt(6)
	s_barrier
	v_mfma_f32_16x16x32_bf16 v[54:57], v[194:197], v[160:163], v[54:57]
	v_mfma_f32_16x16x32_bf16 v[50:53], v[202:205], v[160:163], v[50:53]
	v_mfma_f32_16x16x32_bf16 v[38:41], v[194:197], v[168:171], v[38:41]
	v_mfma_f32_16x16x32_bf16 v[34:37], v[202:205], v[168:171], v[34:37]
	v_mfma_f32_16x16x32_bf16 v[22:25], v[194:197], v[176:179], v[22:25]
	v_mfma_f32_16x16x32_bf16 v[18:21], v[202:205], v[176:179], v[18:21]
	v_mfma_f32_16x16x32_bf16 v[6:9], v[194:197], v[184:187], v[6:9]
	v_mfma_f32_16x16x32_bf16 v[2:5], v[202:205], v[184:187], v[2:5]
	v_mfma_f32_16x16x32_bf16 v[54:57], v[198:201], v[164:167], v[54:57]
	v_mfma_f32_16x16x32_bf16 v[50:53], v[206:209], v[164:167], v[50:53]
	v_mfma_f32_16x16x32_bf16 v[38:41], v[198:201], v[172:175], v[38:41]
	v_mfma_f32_16x16x32_bf16 v[34:37], v[206:209], v[172:175], v[34:37]
	v_mfma_f32_16x16x32_bf16 v[22:25], v[198:201], v[180:183], v[22:25]
	v_mfma_f32_16x16x32_bf16 v[18:21], v[206:209], v[180:183], v[18:21]
	v_mfma_f32_16x16x32_bf16 v[6:9], v[198:201], v[190:193], v[6:9]
	v_mfma_f32_16x16x32_bf16 v[2:5], v[206:209], v[190:193], v[2:5]
	s_barrier
	s_add_u32 s14, s14, 0x40000
	s_addc_u32 s15, s15, 0
	s_mov_b32 m0, s28
	ds_read_b128 v[160:163], v151 offset:32768
	ds_read_b128 v[164:167], v151 offset:33792
	ds_read_b128 v[168:171], v151 offset:34816
	ds_read_b128 v[172:175], v151 offset:35840
	ds_read_b128 v[176:179], v151 offset:36864
	ds_read_b128 v[180:183], v151 offset:37888
	ds_read_b128 v[184:187], v151 offset:38912
	global_load_lds_dwordx4 v136, s[14:15]
	s_mov_b32 m0, s29
	ds_read_b128 v[190:193], v151 offset:39936
	global_load_lds_dwordx4 v132, s[14:15]
	s_waitcnt lgkmcnt(8)
	s_barrier
	s_waitcnt lgkmcnt(0)
	v_mfma_f32_16x16x32_bf16 v[126:129], v[142:145], v[160:163], v[126:129]
	v_mfma_f32_16x16x32_bf16 v[122:125], v[152:155], v[160:163], v[122:125]
	v_mfma_f32_16x16x32_bf16 v[110:113], v[142:145], v[168:171], v[110:113]
	v_mfma_f32_16x16x32_bf16 v[106:109], v[152:155], v[168:171], v[106:109]
	v_mfma_f32_16x16x32_bf16 v[94:97], v[142:145], v[176:179], v[94:97]
	v_mfma_f32_16x16x32_bf16 v[90:93], v[152:155], v[176:179], v[90:93]
	v_mfma_f32_16x16x32_bf16 v[78:81], v[142:145], v[184:187], v[78:81]
	v_mfma_f32_16x16x32_bf16 v[74:77], v[152:155], v[184:187], v[74:77]
	v_mfma_f32_16x16x32_bf16 v[126:129], v[146:149], v[164:167], v[126:129]
	v_mfma_f32_16x16x32_bf16 v[122:125], v[156:159], v[164:167], v[122:125]
	v_mfma_f32_16x16x32_bf16 v[110:113], v[146:149], v[172:175], v[110:113]
	v_mfma_f32_16x16x32_bf16 v[106:109], v[156:159], v[172:175], v[106:109]
	v_mfma_f32_16x16x32_bf16 v[94:97], v[146:149], v[180:183], v[94:97]
	v_mfma_f32_16x16x32_bf16 v[90:93], v[156:159], v[180:183], v[90:93]
	v_mfma_f32_16x16x32_bf16 v[78:81], v[146:149], v[190:193], v[78:81]
	v_mfma_f32_16x16x32_bf16 v[74:77], v[156:159], v[190:193], v[74:77]
	s_barrier
	s_add_i32 m0, s22, 0x18000
	ds_read_b128 v[194:197], v189 offset:49152
	ds_read_b128 v[198:201], v189 offset:50176
	ds_read_b128 v[202:205], v189 offset:51200
	ds_read_b128 v[206:209], v189 offset:52224
	s_add_u32 s98, s12, s40
	s_addc_u32 s99, s13, s41
	global_load_lds_dwordx4 v134, s[98:99]
	s_add_i32 m0, s22, 0x1a000
	s_nop 0
	global_load_lds_dwordx4 v130, s[98:99]
	s_barrier
	s_waitcnt lgkmcnt(0)
	v_mfma_f32_16x16x32_bf16 v[118:121], v[194:197], v[160:163], v[118:121]
	v_mfma_f32_16x16x32_bf16 v[114:117], v[202:205], v[160:163], v[114:117]
	v_mfma_f32_16x16x32_bf16 v[102:105], v[194:197], v[168:171], v[102:105]
	v_mfma_f32_16x16x32_bf16 v[98:101], v[202:205], v[168:171], v[98:101]
	v_mfma_f32_16x16x32_bf16 v[86:89], v[194:197], v[176:179], v[86:89]
	v_mfma_f32_16x16x32_bf16 v[82:85], v[202:205], v[176:179], v[82:85]
	v_mfma_f32_16x16x32_bf16 v[70:73], v[194:197], v[184:187], v[70:73]
	v_mfma_f32_16x16x32_bf16 v[66:69], v[202:205], v[184:187], v[66:69]
	v_mfma_f32_16x16x32_bf16 v[118:121], v[198:201], v[164:167], v[118:121]
	v_mfma_f32_16x16x32_bf16 v[114:117], v[206:209], v[164:167], v[114:117]
	v_mfma_f32_16x16x32_bf16 v[102:105], v[198:201], v[172:175], v[102:105]
	v_mfma_f32_16x16x32_bf16 v[98:101], v[206:209], v[172:175], v[98:101]
	v_mfma_f32_16x16x32_bf16 v[86:89], v[198:201], v[180:183], v[86:89]
	v_mfma_f32_16x16x32_bf16 v[82:85], v[206:209], v[180:183], v[82:85]
	v_mfma_f32_16x16x32_bf16 v[70:73], v[198:201], v[190:193], v[70:73]
	v_mfma_f32_16x16x32_bf16 v[66:69], v[206:209], v[190:193], v[66:69]
	s_mov_b32 m0, s38
	s_barrier
	ds_read_b128 v[160:163], v151 offset:49152
	ds_read_b128 v[164:167], v151 offset:50176
	ds_read_b128 v[168:171], v151 offset:51200
	ds_read_b128 v[172:175], v151 offset:52224
	ds_read_b128 v[176:179], v151 offset:53248
	ds_read_b128 v[180:183], v151 offset:54272
	ds_read_b128 v[184:187], v151 offset:55296
	ds_read_b128 v[190:193], v151 offset:56320
	s_add_u32 s98, s100, s40
	s_addc_u32 s99, s101, s41
	global_load_lds_dwordx4 v136, s[98:99]
	s_mov_b32 m0, s39
	s_nop 0
	global_load_lds_dwordx4 v132, s[98:99]
	s_waitcnt vmcnt(10)
	s_barrier
	s_waitcnt lgkmcnt(0)
	v_mfma_f32_16x16x32_bf16 v[62:65], v[142:145], v[160:163], v[62:65]
	v_mfma_f32_16x16x32_bf16 v[58:61], v[152:155], v[160:163], v[58:61]
	v_mfma_f32_16x16x32_bf16 v[46:49], v[142:145], v[168:171], v[46:49]
	v_mfma_f32_16x16x32_bf16 v[42:45], v[152:155], v[168:171], v[42:45]
	v_mfma_f32_16x16x32_bf16 v[30:33], v[142:145], v[176:179], v[30:33]
	v_mfma_f32_16x16x32_bf16 v[26:29], v[152:155], v[176:179], v[26:29]
	v_mfma_f32_16x16x32_bf16 v[14:17], v[142:145], v[184:187], v[14:17]
	v_mfma_f32_16x16x32_bf16 v[10:13], v[152:155], v[184:187], v[10:13]
	v_mfma_f32_16x16x32_bf16 v[62:65], v[146:149], v[164:167], v[62:65]
	v_mfma_f32_16x16x32_bf16 v[58:61], v[156:159], v[164:167], v[58:61]
	v_mfma_f32_16x16x32_bf16 v[46:49], v[146:149], v[172:175], v[46:49]
	v_mfma_f32_16x16x32_bf16 v[42:45], v[156:159], v[172:175], v[42:45]
	v_mfma_f32_16x16x32_bf16 v[30:33], v[146:149], v[180:183], v[30:33]
	v_mfma_f32_16x16x32_bf16 v[26:29], v[156:159], v[180:183], v[26:29]
	v_mfma_f32_16x16x32_bf16 v[14:17], v[146:149], v[190:193], v[14:17]
	v_mfma_f32_16x16x32_bf16 v[10:13], v[156:159], v[190:193], v[10:13]
	s_barrier
	s_add_u32 s12, s12, 0x40080
	s_addc_u32 s13, s13, 0
	s_add_i32 m0, s22, 0x1c000
	s_nop 0
	global_load_lds_dwordx4 v134, s[12:13]
	s_add_i32 m0, s22, 0x1e000
	s_nop 0
	global_load_lds_dwordx4 v130, s[12:13]
	ds_read_b128 v[142:145], v189
	ds_read_b128 v[146:149], v189 offset:1024
	ds_read_b128 v[152:155], v189 offset:2048
	ds_read_b128 v[156:159], v189 offset:3072
	s_waitcnt vmcnt(6)
	s_barrier
	v_mfma_f32_16x16x32_bf16 v[54:57], v[194:197], v[160:163], v[54:57]
	v_mfma_f32_16x16x32_bf16 v[50:53], v[202:205], v[160:163], v[50:53]
	v_mfma_f32_16x16x32_bf16 v[38:41], v[194:197], v[168:171], v[38:41]
	v_mfma_f32_16x16x32_bf16 v[34:37], v[202:205], v[168:171], v[34:37]
	v_mfma_f32_16x16x32_bf16 v[22:25], v[194:197], v[176:179], v[22:25]
	v_mfma_f32_16x16x32_bf16 v[18:21], v[202:205], v[176:179], v[18:21]
	v_mfma_f32_16x16x32_bf16 v[6:9], v[194:197], v[184:187], v[6:9]
	v_mfma_f32_16x16x32_bf16 v[2:5], v[202:205], v[184:187], v[2:5]
	v_mfma_f32_16x16x32_bf16 v[54:57], v[198:201], v[164:167], v[54:57]
	v_mfma_f32_16x16x32_bf16 v[50:53], v[206:209], v[164:167], v[50:53]
	v_mfma_f32_16x16x32_bf16 v[38:41], v[198:201], v[172:175], v[38:41]
	v_mfma_f32_16x16x32_bf16 v[34:37], v[206:209], v[172:175], v[34:37]
	v_mfma_f32_16x16x32_bf16 v[22:25], v[198:201], v[180:183], v[22:25]
	v_mfma_f32_16x16x32_bf16 v[18:21], v[206:209], v[180:183], v[18:21]
	v_mfma_f32_16x16x32_bf16 v[6:9], v[198:201], v[190:193], v[6:9]
	v_mfma_f32_16x16x32_bf16 v[2:5], v[206:209], v[190:193], v[2:5]
	s_add_i32 s85, s85, 2
	s_add_u32 s4, s4, 0x100
	s_addc_u32 s5, s5, 0
	s_add_u32 s78, s78, 0x100
	s_addc_u32 s79, s79, 0
	s_add_u32 s12, s4, 0xfffc0080
	s_addc_u32 s13, s5, -1
	s_cmp_eq_u32 s85, 12
	s_cselect_b32 s15, s44, s13
	s_cselect_b32 s14, s45, s12
	s_cselect_b32 s13, s47, s79
	s_cselect_b32 s12, s55, s78
	s_cmp_gt_u32 s85, 13
	s_barrier
	s_cbranch_scc0 .LBB0_267
	s_waitcnt lgkmcnt(0)
	v_mov_b32_e32 v156, v252
	s_mov_b64 s[4:5], -1
	v_and_b32_e32 v154, 63, v156
	s_andn2_b64 vcc, exec, s[2:3]
	v_lshlrev_b32_e32 v142, 2, v154
	s_cbranch_vccnz .LBB0_270
	v_lshlrev_b32_e32 v155, 2, v154
	s_mov_b64 s[4:5], 0

.LBB0_837:
	s_ashr_i32 s15, s14, 31
	s_lshl_b64 s[78:79], s[14:15], 19
	s_add_u32 s84, s36, s78
	s_addc_u32 s85, s37, s79
	s_and_b64 s[4:5], s[4:5], exec
	s_cselect_b32 s15, s85, s91
	s_cselect_b32 s23, s84, s90
	s_add_u32 s34, s90, 0x100
	s_addc_u32 s75, s91, 0
	s_mov_b32 s78, -2
	s_waitcnt lgkmcnt(0)
	s_add_i32 s79, 0, 0x10000
	v_add_u32_e32 v142, s79, v212
	v_add_u32_e32 v189, 0x10000, v212
	ds_read_b128 v[130:133], v142
	ds_read_b128 v[134:137], v142 offset:1024
	ds_read_b128 v[138:141], v142 offset:2048
	ds_read_b128 v[142:145], v142 offset:3072
	s_add_u32 s4, s88, 0x100
	s_addc_u32 s5, s89, 0
	s_cmp_eq_u32 s78, 12
	s_cselect_b32 s93, s17, s5
	s_cselect_b32 s92, s16, s4
	s_cselect_b32 s91, s15, s75
	s_cselect_b32 s90, s23, s34
	v_lshl_add_u64 v[178:179], s[88:89], 0, v[196:197]
	s_add_i32 m0, s39, 0xc000
	ds_read_b128 v[146:149], v213
	ds_read_b128 v[150:153], v213 offset:1024
	ds_read_b128 v[154:157], v213 offset:2048
	ds_read_b128 v[158:161], v213 offset:3072
	ds_read_b128 v[162:165], v213 offset:4096
	ds_read_b128 v[166:169], v213 offset:5120
	ds_read_b128 v[170:173], v213 offset:6144
	ds_read_b128 v[174:177], v213 offset:7168
	global_load_lds_dwordx4 v[178:179], off
	s_add_i32 m0, s39, 0xe000
	v_lshl_add_u64 v[178:179], s[88:89], 0, v[198:199]
	global_load_lds_dwordx4 v[178:179], off
	s_waitcnt lgkmcnt(8)
	s_barrier
	s_waitcnt lgkmcnt(0)
	v_mfma_f32_16x16x32_bf16 v[126:129], v[130:133], v[146:149], 0
	v_mfma_f32_16x16x32_bf16 v[122:125], v[138:141], v[146:149], 0
	v_mfma_f32_16x16x32_bf16 v[110:113], v[130:133], v[154:157], 0
	v_mfma_f32_16x16x32_bf16 v[106:109], v[138:141], v[154:157], 0
	v_mfma_f32_16x16x32_bf16 v[94:97], v[130:133], v[162:165], 0
	v_mfma_f32_16x16x32_bf16 v[90:93], v[138:141], v[162:165], 0
	v_mfma_f32_16x16x32_bf16 v[78:81], v[130:133], v[170:173], 0
	v_mfma_f32_16x16x32_bf16 v[74:77], v[138:141], v[170:173], 0
	v_mfma_f32_16x16x32_bf16 v[126:129], v[134:137], v[150:153], v[126:129]
	v_mfma_f32_16x16x32_bf16 v[122:125], v[142:145], v[150:153], v[122:125]
	v_mfma_f32_16x16x32_bf16 v[110:113], v[134:137], v[158:161], v[110:113]
	v_mfma_f32_16x16x32_bf16 v[106:109], v[142:145], v[158:161], v[106:109]
	v_mfma_f32_16x16x32_bf16 v[94:97], v[134:137], v[166:169], v[94:97]
	v_mfma_f32_16x16x32_bf16 v[90:93], v[142:145], v[166:169], v[90:93]
	v_mfma_f32_16x16x32_bf16 v[78:81], v[134:137], v[174:177], v[78:81]
	v_mfma_f32_16x16x32_bf16 v[74:77], v[142:145], v[174:177], v[74:77]
	s_barrier
	ds_read_b128 v[178:181], v189 offset:16384
	ds_read_b128 v[182:185], v189 offset:17408
	ds_read_b128 v[200:203], v189 offset:18432
	ds_read_b128 v[204:207], v189 offset:19456
	s_add_i32 m0, s38, 0x10000
	s_nop 0
	global_load_lds_dwordx4 v0, s[90:91]
	s_add_i32 m0, s38, 0x12000
	s_nop 0
	global_load_lds_dwordx4 v194, s[90:91]
	s_barrier
	s_waitcnt lgkmcnt(0)
	v_mfma_f32_16x16x32_bf16 v[118:121], v[178:181], v[146:149], 0
	v_mfma_f32_16x16x32_bf16 v[114:117], v[200:203], v[146:149], 0
	v_mfma_f32_16x16x32_bf16 v[102:105], v[178:181], v[154:157], 0
	v_mfma_f32_16x16x32_bf16 v[98:101], v[200:203], v[154:157], 0
	v_mfma_f32_16x16x32_bf16 v[86:89], v[178:181], v[162:165], 0
	v_mfma_f32_16x16x32_bf16 v[82:85], v[200:203], v[162:165], 0
	v_mfma_f32_16x16x32_bf16 v[70:73], v[178:181], v[170:173], 0
	v_mfma_f32_16x16x32_bf16 v[66:69], v[200:203], v[170:173], 0
	v_mfma_f32_16x16x32_bf16 v[118:121], v[182:185], v[150:153], v[118:121]
	v_mfma_f32_16x16x32_bf16 v[114:117], v[204:207], v[150:153], v[114:117]
	v_mfma_f32_16x16x32_bf16 v[102:105], v[182:185], v[158:161], v[102:105]
	v_mfma_f32_16x16x32_bf16 v[98:101], v[204:207], v[158:161], v[98:101]
	v_mfma_f32_16x16x32_bf16 v[86:89], v[182:185], v[166:169], v[86:89]
	v_mfma_f32_16x16x32_bf16 v[82:85], v[204:207], v[166:169], v[82:85]
	v_mfma_f32_16x16x32_bf16 v[70:73], v[182:185], v[174:177], v[70:73]
	v_mfma_f32_16x16x32_bf16 v[66:69], v[204:207], v[174:177], v[66:69]
	s_mov_b32 m0, s39
	s_barrier
	ds_read_b128 v[146:149], v213 offset:16384
	ds_read_b128 v[150:153], v213 offset:17408
	ds_read_b128 v[154:157], v213 offset:18432
	ds_read_b128 v[158:161], v213 offset:19456
	ds_read_b128 v[162:165], v213 offset:20480
	ds_read_b128 v[166:169], v213 offset:21504
	ds_read_b128 v[170:173], v213 offset:22528
	global_load_lds_dwordx4 v190, s[92:93]
	s_mov_b32 m0, s42
	ds_read_b128 v[174:177], v213 offset:23552
	global_load_lds_dwordx4 v192, s[92:93]
	s_waitcnt vmcnt(10)
	s_barrier
	s_waitcnt lgkmcnt(0)
	v_mfma_f32_16x16x32_bf16 v[62:65], v[130:133], v[146:149], 0
	v_mfma_f32_16x16x32_bf16 v[58:61], v[138:141], v[146:149], 0
	v_mfma_f32_16x16x32_bf16 v[46:49], v[130:133], v[154:157], 0
	v_mfma_f32_16x16x32_bf16 v[42:45], v[138:141], v[154:157], 0
	v_mfma_f32_16x16x32_bf16 v[30:33], v[130:133], v[162:165], 0
	v_mfma_f32_16x16x32_bf16 v[26:29], v[138:141], v[162:165], 0
	v_mfma_f32_16x16x32_bf16 v[14:17], v[130:133], v[170:173], 0
	v_mfma_f32_16x16x32_bf16 v[10:13], v[138:141], v[170:173], 0
	v_mfma_f32_16x16x32_bf16 v[62:65], v[134:137], v[150:153], v[62:65]
	v_mfma_f32_16x16x32_bf16 v[58:61], v[142:145], v[150:153], v[58:61]
	v_mfma_f32_16x16x32_bf16 v[46:49], v[134:137], v[158:161], v[46:49]
	v_mfma_f32_16x16x32_bf16 v[42:45], v[142:145], v[158:161], v[42:45]
	v_mfma_f32_16x16x32_bf16 v[30:33], v[134:137], v[166:169], v[30:33]
	v_mfma_f32_16x16x32_bf16 v[26:29], v[142:145], v[166:169], v[26:29]
	v_mfma_f32_16x16x32_bf16 v[14:17], v[134:137], v[174:177], v[14:17]
	v_mfma_f32_16x16x32_bf16 v[10:13], v[142:145], v[174:177], v[10:13]
	s_barrier
	s_add_u32 s88, s90, 0x40000
	s_addc_u32 s89, s91, 0
	s_add_i32 m0, s38, 0x14000
	s_nop 0
	global_load_lds_dwordx4 v0, s[88:89]
	s_add_i32 m0, s38, 0x16000
	s_nop 0
	global_load_lds_dwordx4 v194, s[88:89]
	s_add_i32 s79, 0, 0x18000
	v_add_u32_e32 v142, s79, v212
	ds_read_b128 v[130:133], v142
	ds_read_b128 v[134:137], v142 offset:1024
	ds_read_b128 v[138:141], v142 offset:2048
	ds_read_b128 v[142:145], v142 offset:3072
	s_waitcnt vmcnt(6)
	s_barrier
	v_mfma_f32_16x16x32_bf16 v[54:57], v[178:181], v[146:149], 0
	v_mfma_f32_16x16x32_bf16 v[50:53], v[200:203], v[146:149], 0
	v_mfma_f32_16x16x32_bf16 v[38:41], v[178:181], v[154:157], 0
	v_mfma_f32_16x16x32_bf16 v[34:37], v[200:203], v[154:157], 0
	v_mfma_f32_16x16x32_bf16 v[22:25], v[178:181], v[162:165], 0
	v_mfma_f32_16x16x32_bf16 v[18:21], v[200:203], v[162:165], 0
	v_mfma_f32_16x16x32_bf16 v[6:9], v[178:181], v[170:173], 0
	v_mfma_f32_16x16x32_bf16 v[2:5], v[200:203], v[170:173], 0
	v_mfma_f32_16x16x32_bf16 v[54:57], v[182:185], v[150:153], v[54:57]
	v_mfma_f32_16x16x32_bf16 v[50:53], v[204:207], v[150:153], v[50:53]
	v_mfma_f32_16x16x32_bf16 v[38:41], v[182:185], v[158:161], v[38:41]
	v_mfma_f32_16x16x32_bf16 v[34:37], v[204:207], v[158:161], v[34:37]
	v_mfma_f32_16x16x32_bf16 v[22:25], v[182:185], v[166:169], v[22:25]
	v_mfma_f32_16x16x32_bf16 v[18:21], v[204:207], v[166:169], v[18:21]
	v_mfma_f32_16x16x32_bf16 v[6:9], v[182:185], v[174:177], v[6:9]
	v_mfma_f32_16x16x32_bf16 v[2:5], v[204:207], v[174:177], v[2:5]
	s_barrier
	s_add_u32 s88, s92, 0xc0000
	s_addc_u32 s89, s93, 0
	s_mov_b32 m0, s43
	ds_read_b128 v[146:149], v213 offset:32768
	ds_read_b128 v[150:153], v213 offset:33792
	ds_read_b128 v[154:157], v213 offset:34816
	ds_read_b128 v[158:161], v213 offset:35840
	ds_read_b128 v[162:165], v213 offset:36864
	ds_read_b128 v[166:169], v213 offset:37888
	ds_read_b128 v[170:173], v213 offset:38912
	global_load_lds_dwordx4 v190, s[88:89]
	s_mov_b32 m0, s44
	ds_read_b128 v[174:177], v213 offset:39936
	global_load_lds_dwordx4 v192, s[88:89]
	s_waitcnt lgkmcnt(8)
	s_barrier
	s_waitcnt lgkmcnt(0)
	v_mfma_f32_16x16x32_bf16 v[126:129], v[130:133], v[146:149], v[126:129]
	v_mfma_f32_16x16x32_bf16 v[122:125], v[138:141], v[146:149], v[122:125]
	v_mfma_f32_16x16x32_bf16 v[110:113], v[130:133], v[154:157], v[110:113]
	v_mfma_f32_16x16x32_bf16 v[106:109], v[138:141], v[154:157], v[106:109]
	v_mfma_f32_16x16x32_bf16 v[94:97], v[130:133], v[162:165], v[94:97]
	v_mfma_f32_16x16x32_bf16 v[90:93], v[138:141], v[162:165], v[90:93]
	v_mfma_f32_16x16x32_bf16 v[78:81], v[130:133], v[170:173], v[78:81]
	v_mfma_f32_16x16x32_bf16 v[74:77], v[138:141], v[170:173], v[74:77]
	v_mfma_f32_16x16x32_bf16 v[126:129], v[134:137], v[150:153], v[126:129]
	v_mfma_f32_16x16x32_bf16 v[122:125], v[142:145], v[150:153], v[122:125]
	v_mfma_f32_16x16x32_bf16 v[110:113], v[134:137], v[158:161], v[110:113]
	v_mfma_f32_16x16x32_bf16 v[106:109], v[142:145], v[158:161], v[106:109]
	v_mfma_f32_16x16x32_bf16 v[94:97], v[134:137], v[166:169], v[94:97]
	v_mfma_f32_16x16x32_bf16 v[90:93], v[142:145], v[166:169], v[90:93]
	v_mfma_f32_16x16x32_bf16 v[78:81], v[134:137], v[174:177], v[78:81]
	v_mfma_f32_16x16x32_bf16 v[74:77], v[142:145], v[174:177], v[74:77]
	s_barrier
	s_add_i32 s87, 0, 0x1c000
	v_add_u32_e32 v204, s87, v212
	s_add_i32 m0, s38, 0x18000
	ds_read_b128 v[178:181], v204
	ds_read_b128 v[182:185], v204 offset:1024
	ds_read_b128 v[200:203], v204 offset:2048
	ds_read_b128 v[204:207], v204 offset:3072
	s_add_u32 s98, s90, s40
	s_addc_u32 s99, s91, s41
	global_load_lds_dwordx4 v0, s[98:99]
	s_add_i32 m0, s38, 0x1a000
	s_nop 0
	global_load_lds_dwordx4 v194, s[98:99]
	s_barrier
	s_waitcnt lgkmcnt(0)
	v_mfma_f32_16x16x32_bf16 v[118:121], v[178:181], v[146:149], v[118:121]
	v_mfma_f32_16x16x32_bf16 v[114:117], v[200:203], v[146:149], v[114:117]
	v_mfma_f32_16x16x32_bf16 v[102:105], v[178:181], v[154:157], v[102:105]
	v_mfma_f32_16x16x32_bf16 v[98:101], v[200:203], v[154:157], v[98:101]
	v_mfma_f32_16x16x32_bf16 v[86:89], v[178:181], v[162:165], v[86:89]
	v_mfma_f32_16x16x32_bf16 v[82:85], v[200:203], v[162:165], v[82:85]
	v_mfma_f32_16x16x32_bf16 v[70:73], v[178:181], v[170:173], v[70:73]
	v_mfma_f32_16x16x32_bf16 v[66:69], v[200:203], v[170:173], v[66:69]
	v_mfma_f32_16x16x32_bf16 v[118:121], v[182:185], v[150:153], v[118:121]
	v_mfma_f32_16x16x32_bf16 v[114:117], v[204:207], v[150:153], v[114:117]
	v_mfma_f32_16x16x32_bf16 v[102:105], v[182:185], v[158:161], v[102:105]
	v_mfma_f32_16x16x32_bf16 v[98:101], v[204:207], v[158:161], v[98:101]
	v_mfma_f32_16x16x32_bf16 v[86:89], v[182:185], v[166:169], v[86:89]
	v_mfma_f32_16x16x32_bf16 v[82:85], v[204:207], v[166:169], v[82:85]
	v_mfma_f32_16x16x32_bf16 v[70:73], v[182:185], v[174:177], v[70:73]
	v_mfma_f32_16x16x32_bf16 v[66:69], v[204:207], v[174:177], v[66:69]
	s_mov_b32 m0, s60
	s_barrier
	ds_read_b128 v[146:149], v213 offset:49152
	ds_read_b128 v[150:153], v213 offset:50176
	ds_read_b128 v[154:157], v213 offset:51200
	ds_read_b128 v[158:161], v213 offset:52224
	ds_read_b128 v[162:165], v213 offset:53248
	ds_read_b128 v[166:169], v213 offset:54272
	ds_read_b128 v[170:173], v213 offset:55296
	ds_read_b128 v[174:177], v213 offset:56320
	s_add_u32 s98, s92, s40
	s_addc_u32 s99, s93, s41
	global_load_lds_dwordx4 v190, s[98:99]
	s_mov_b32 m0, s61
	s_nop 0
	global_load_lds_dwordx4 v192, s[98:99]
	s_waitcnt vmcnt(10)
	s_barrier
	s_waitcnt lgkmcnt(0)
	v_mfma_f32_16x16x32_bf16 v[62:65], v[130:133], v[146:149], v[62:65]
	v_mfma_f32_16x16x32_bf16 v[58:61], v[138:141], v[146:149], v[58:61]
	v_mfma_f32_16x16x32_bf16 v[46:49], v[130:133], v[154:157], v[46:49]
	v_mfma_f32_16x16x32_bf16 v[42:45], v[138:141], v[154:157], v[42:45]
	v_mfma_f32_16x16x32_bf16 v[30:33], v[130:133], v[162:165], v[30:33]
	v_mfma_f32_16x16x32_bf16 v[26:29], v[138:141], v[162:165], v[26:29]
	v_mfma_f32_16x16x32_bf16 v[14:17], v[130:133], v[170:173], v[14:17]
	v_mfma_f32_16x16x32_bf16 v[10:13], v[138:141], v[170:173], v[10:13]
	v_mfma_f32_16x16x32_bf16 v[62:65], v[134:137], v[150:153], v[62:65]
	v_mfma_f32_16x16x32_bf16 v[58:61], v[142:145], v[150:153], v[58:61]
	v_mfma_f32_16x16x32_bf16 v[46:49], v[134:137], v[158:161], v[46:49]
	v_mfma_f32_16x16x32_bf16 v[42:45], v[142:145], v[158:161], v[42:45]
	v_mfma_f32_16x16x32_bf16 v[30:33], v[134:137], v[166:169], v[30:33]
	v_mfma_f32_16x16x32_bf16 v[26:29], v[142:145], v[166:169], v[26:29]
	v_mfma_f32_16x16x32_bf16 v[14:17], v[134:137], v[174:177], v[14:17]
	v_mfma_f32_16x16x32_bf16 v[10:13], v[142:145], v[174:177], v[10:13]
	s_barrier
	s_add_u32 s88, s90, 0x40080
	s_addc_u32 s89, s91, 0
	s_add_i32 m0, s38, 0x1c000
	s_nop 0
	global_load_lds_dwordx4 v0, s[88:89]
	s_add_i32 m0, s38, 0x1e000
	s_nop 0
	global_load_lds_dwordx4 v194, s[88:89]
	ds_read_b128 v[130:133], v189
	ds_read_b128 v[134:137], v189 offset:1024
	ds_read_b128 v[138:141], v189 offset:2048
	ds_read_b128 v[142:145], v189 offset:3072
	s_waitcnt vmcnt(6)
	s_barrier
	v_mfma_f32_16x16x32_bf16 v[54:57], v[178:181], v[146:149], v[54:57]
	v_mfma_f32_16x16x32_bf16 v[50:53], v[200:203], v[146:149], v[50:53]
	v_mfma_f32_16x16x32_bf16 v[38:41], v[178:181], v[154:157], v[38:41]
	v_mfma_f32_16x16x32_bf16 v[34:37], v[200:203], v[154:157], v[34:37]
	v_mfma_f32_16x16x32_bf16 v[22:25], v[178:181], v[162:165], v[22:25]
	v_mfma_f32_16x16x32_bf16 v[18:21], v[200:203], v[162:165], v[18:21]
	v_mfma_f32_16x16x32_bf16 v[6:9], v[178:181], v[170:173], v[6:9]
	v_mfma_f32_16x16x32_bf16 v[2:5], v[200:203], v[170:173], v[2:5]
	v_mfma_f32_16x16x32_bf16 v[54:57], v[182:185], v[150:153], v[54:57]
	v_mfma_f32_16x16x32_bf16 v[50:53], v[204:207], v[150:153], v[50:53]
	v_mfma_f32_16x16x32_bf16 v[38:41], v[182:185], v[158:161], v[38:41]
	v_mfma_f32_16x16x32_bf16 v[34:37], v[204:207], v[158:161], v[34:37]
	v_mfma_f32_16x16x32_bf16 v[22:25], v[182:185], v[166:169], v[22:25]
	v_mfma_f32_16x16x32_bf16 v[18:21], v[204:207], v[166:169], v[18:21]
	v_mfma_f32_16x16x32_bf16 v[6:9], v[182:185], v[174:177], v[6:9]
	v_mfma_f32_16x16x32_bf16 v[2:5], v[204:207], v[174:177], v[2:5]
	s_add_i32 s78, s78, 2
	s_add_u32 s34, s34, 0x100
	s_addc_u32 s75, s75, 0
	s_mov_b64 s[88:89], s[4:5]
	s_add_u32 s4, s88, 0x100
	s_addc_u32 s5, s89, 0
	s_cmp_eq_u32 s78, 12
	s_cselect_b32 s93, s17, s5
	s_cselect_b32 s92, s16, s4
	s_cselect_b32 s91, s15, s75
	s_cselect_b32 s90, s23, s34
	s_cmp_gt_u32 s78, 13
	s_barrier
.LBB0_838:
	v_lshl_add_u64 v[178:179], s[88:89], 0, v[196:197]
	s_add_i32 m0, s39, 0xc000
	ds_read_b128 v[146:149], v213
	ds_read_b128 v[150:153], v213 offset:1024
	ds_read_b128 v[154:157], v213 offset:2048
	ds_read_b128 v[158:161], v213 offset:3072
	ds_read_b128 v[162:165], v213 offset:4096
	ds_read_b128 v[166:169], v213 offset:5120
	ds_read_b128 v[170:173], v213 offset:6144
	ds_read_b128 v[174:177], v213 offset:7168
	global_load_lds_dwordx4 v[178:179], off
	s_add_i32 m0, s39, 0xe000
	v_lshl_add_u64 v[178:179], s[88:89], 0, v[198:199]
	global_load_lds_dwordx4 v[178:179], off
	s_waitcnt lgkmcnt(8)
	s_barrier
	s_waitcnt lgkmcnt(0)
	v_mfma_f32_16x16x32_bf16 v[126:129], v[130:133], v[146:149], v[126:129]
	v_mfma_f32_16x16x32_bf16 v[122:125], v[138:141], v[146:149], v[122:125]
	v_mfma_f32_16x16x32_bf16 v[110:113], v[130:133], v[154:157], v[110:113]
	v_mfma_f32_16x16x32_bf16 v[106:109], v[138:141], v[154:157], v[106:109]
	v_mfma_f32_16x16x32_bf16 v[94:97], v[130:133], v[162:165], v[94:97]
	v_mfma_f32_16x16x32_bf16 v[90:93], v[138:141], v[162:165], v[90:93]
	v_mfma_f32_16x16x32_bf16 v[78:81], v[130:133], v[170:173], v[78:81]
	v_mfma_f32_16x16x32_bf16 v[74:77], v[138:141], v[170:173], v[74:77]
	v_mfma_f32_16x16x32_bf16 v[126:129], v[134:137], v[150:153], v[126:129]
	v_mfma_f32_16x16x32_bf16 v[122:125], v[142:145], v[150:153], v[122:125]
	v_mfma_f32_16x16x32_bf16 v[110:113], v[134:137], v[158:161], v[110:113]
	v_mfma_f32_16x16x32_bf16 v[106:109], v[142:145], v[158:161], v[106:109]
	v_mfma_f32_16x16x32_bf16 v[94:97], v[134:137], v[166:169], v[94:97]
	v_mfma_f32_16x16x32_bf16 v[90:93], v[142:145], v[166:169], v[90:93]
	v_mfma_f32_16x16x32_bf16 v[78:81], v[134:137], v[174:177], v[78:81]
	v_mfma_f32_16x16x32_bf16 v[74:77], v[142:145], v[174:177], v[74:77]
	s_barrier
	ds_read_b128 v[178:181], v189 offset:16384
	ds_read_b128 v[182:185], v189 offset:17408
	ds_read_b128 v[200:203], v189 offset:18432
	ds_read_b128 v[204:207], v189 offset:19456
	s_add_i32 m0, s38, 0x10000
	s_nop 0
	global_load_lds_dwordx4 v0, s[90:91]
	s_add_i32 m0, s38, 0x12000
	s_nop 0
	global_load_lds_dwordx4 v194, s[90:91]
	s_barrier
	s_waitcnt lgkmcnt(0)
	v_mfma_f32_16x16x32_bf16 v[118:121], v[178:181], v[146:149], v[118:121]
	v_mfma_f32_16x16x32_bf16 v[114:117], v[200:203], v[146:149], v[114:117]
	v_mfma_f32_16x16x32_bf16 v[102:105], v[178:181], v[154:157], v[102:105]
	v_mfma_f32_16x16x32_bf16 v[98:101], v[200:203], v[154:157], v[98:101]
	v_mfma_f32_16x16x32_bf16 v[86:89], v[178:181], v[162:165], v[86:89]
	v_mfma_f32_16x16x32_bf16 v[82:85], v[200:203], v[162:165], v[82:85]
	v_mfma_f32_16x16x32_bf16 v[70:73], v[178:181], v[170:173], v[70:73]
	v_mfma_f32_16x16x32_bf16 v[66:69], v[200:203], v[170:173], v[66:69]
	v_mfma_f32_16x16x32_bf16 v[118:121], v[182:185], v[150:153], v[118:121]
	v_mfma_f32_16x16x32_bf16 v[114:117], v[204:207], v[150:153], v[114:117]
	v_mfma_f32_16x16x32_bf16 v[102:105], v[182:185], v[158:161], v[102:105]
	v_mfma_f32_16x16x32_bf16 v[98:101], v[204:207], v[158:161], v[98:101]
	v_mfma_f32_16x16x32_bf16 v[86:89], v[182:185], v[166:169], v[86:89]
	v_mfma_f32_16x16x32_bf16 v[82:85], v[204:207], v[166:169], v[82:85]
	v_mfma_f32_16x16x32_bf16 v[70:73], v[182:185], v[174:177], v[70:73]
	v_mfma_f32_16x16x32_bf16 v[66:69], v[204:207], v[174:177], v[66:69]
	s_mov_b32 m0, s39
	s_barrier
	ds_read_b128 v[146:149], v213 offset:16384
	ds_read_b128 v[150:153], v213 offset:17408
	ds_read_b128 v[154:157], v213 offset:18432
	ds_read_b128 v[158:161], v213 offset:19456
	ds_read_b128 v[162:165], v213 offset:20480
	ds_read_b128 v[166:169], v213 offset:21504
	ds_read_b128 v[170:173], v213 offset:22528
	global_load_lds_dwordx4 v190, s[92:93]
	s_mov_b32 m0, s42
	ds_read_b128 v[174:177], v213 offset:23552
	global_load_lds_dwordx4 v192, s[92:93]
	s_waitcnt vmcnt(10)
	s_barrier
	s_waitcnt lgkmcnt(0)
	v_mfma_f32_16x16x32_bf16 v[62:65], v[130:133], v[146:149], v[62:65]
	v_mfma_f32_16x16x32_bf16 v[58:61], v[138:141], v[146:149], v[58:61]
	v_mfma_f32_16x16x32_bf16 v[46:49], v[130:133], v[154:157], v[46:49]
	v_mfma_f32_16x16x32_bf16 v[42:45], v[138:141], v[154:157], v[42:45]
	v_mfma_f32_16x16x32_bf16 v[30:33], v[130:133], v[162:165], v[30:33]
	v_mfma_f32_16x16x32_bf16 v[26:29], v[138:141], v[162:165], v[26:29]
	v_mfma_f32_16x16x32_bf16 v[14:17], v[130:133], v[170:173], v[14:17]
	v_mfma_f32_16x16x32_bf16 v[10:13], v[138:141], v[170:173], v[10:13]
	v_mfma_f32_16x16x32_bf16 v[62:65], v[134:137], v[150:153], v[62:65]
	v_mfma_f32_16x16x32_bf16 v[58:61], v[142:145], v[150:153], v[58:61]
	v_mfma_f32_16x16x32_bf16 v[46:49], v[134:137], v[158:161], v[46:49]
	v_mfma_f32_16x16x32_bf16 v[42:45], v[142:145], v[158:161], v[42:45]
	v_mfma_f32_16x16x32_bf16 v[30:33], v[134:137], v[166:169], v[30:33]
	v_mfma_f32_16x16x32_bf16 v[26:29], v[142:145], v[166:169], v[26:29]
	v_mfma_f32_16x16x32_bf16 v[14:17], v[134:137], v[174:177], v[14:17]
	v_mfma_f32_16x16x32_bf16 v[10:13], v[142:145], v[174:177], v[10:13]
	s_barrier
	s_add_u32 s88, s90, 0x40000
	s_addc_u32 s89, s91, 0
	s_add_i32 m0, s38, 0x14000
	s_nop 0
	global_load_lds_dwordx4 v0, s[88:89]
	s_add_i32 m0, s38, 0x16000
	s_nop 0
	global_load_lds_dwordx4 v194, s[88:89]
	s_add_i32 s79, 0, 0x18000
	v_add_u32_e32 v142, s79, v212
	ds_read_b128 v[130:133], v142
	ds_read_b128 v[134:137], v142 offset:1024
	ds_read_b128 v[138:141], v142 offset:2048
	ds_read_b128 v[142:145], v142 offset:3072
	s_waitcnt vmcnt(6)
	s_barrier
	v_mfma_f32_16x16x32_bf16 v[54:57], v[178:181], v[146:149], v[54:57]
	v_mfma_f32_16x16x32_bf16 v[50:53], v[200:203], v[146:149], v[50:53]
	v_mfma_f32_16x16x32_bf16 v[38:41], v[178:181], v[154:157], v[38:41]
	v_mfma_f32_16x16x32_bf16 v[34:37], v[200:203], v[154:157], v[34:37]
	v_mfma_f32_16x16x32_bf16 v[22:25], v[178:181], v[162:165], v[22:25]
	v_mfma_f32_16x16x32_bf16 v[18:21], v[200:203], v[162:165], v[18:21]
	v_mfma_f32_16x16x32_bf16 v[6:9], v[178:181], v[170:173], v[6:9]
	v_mfma_f32_16x16x32_bf16 v[2:5], v[200:203], v[170:173], v[2:5]
	v_mfma_f32_16x16x32_bf16 v[54:57], v[182:185], v[150:153], v[54:57]
	v_mfma_f32_16x16x32_bf16 v[50:53], v[204:207], v[150:153], v[50:53]
	v_mfma_f32_16x16x32_bf16 v[38:41], v[182:185], v[158:161], v[38:41]
	v_mfma_f32_16x16x32_bf16 v[34:37], v[204:207], v[158:161], v[34:37]
	v_mfma_f32_16x16x32_bf16 v[22:25], v[182:185], v[166:169], v[22:25]
	v_mfma_f32_16x16x32_bf16 v[18:21], v[204:207], v[166:169], v[18:21]
	v_mfma_f32_16x16x32_bf16 v[6:9], v[182:185], v[174:177], v[6:9]
	v_mfma_f32_16x16x32_bf16 v[2:5], v[204:207], v[174:177], v[2:5]
	s_barrier
	s_add_u32 s88, s92, 0xc0000
	s_addc_u32 s89, s93, 0
	s_mov_b32 m0, s43
	ds_read_b128 v[146:149], v213 offset:32768
	ds_read_b128 v[150:153], v213 offset:33792
	ds_read_b128 v[154:157], v213 offset:34816
	ds_read_b128 v[158:161], v213 offset:35840
	ds_read_b128 v[162:165], v213 offset:36864
	ds_read_b128 v[166:169], v213 offset:37888
	ds_read_b128 v[170:173], v213 offset:38912
	global_load_lds_dwordx4 v190, s[88:89]
	s_mov_b32 m0, s44
	ds_read_b128 v[174:177], v213 offset:39936
	global_load_lds_dwordx4 v192, s[88:89]
	s_waitcnt lgkmcnt(8)
	s_barrier
	s_waitcnt lgkmcnt(0)
	v_mfma_f32_16x16x32_bf16 v[126:129], v[130:133], v[146:149], v[126:129]
	v_mfma_f32_16x16x32_bf16 v[122:125], v[138:141], v[146:149], v[122:125]
	v_mfma_f32_16x16x32_bf16 v[110:113], v[130:133], v[154:157], v[110:113]
	v_mfma_f32_16x16x32_bf16 v[106:109], v[138:141], v[154:157], v[106:109]
	v_mfma_f32_16x16x32_bf16 v[94:97], v[130:133], v[162:165], v[94:97]
	v_mfma_f32_16x16x32_bf16 v[90:93], v[138:141], v[162:165], v[90:93]
	v_mfma_f32_16x16x32_bf16 v[78:81], v[130:133], v[170:173], v[78:81]
	v_mfma_f32_16x16x32_bf16 v[74:77], v[138:141], v[170:173], v[74:77]
	v_mfma_f32_16x16x32_bf16 v[126:129], v[134:137], v[150:153], v[126:129]
	v_mfma_f32_16x16x32_bf16 v[122:125], v[142:145], v[150:153], v[122:125]
	v_mfma_f32_16x16x32_bf16 v[110:113], v[134:137], v[158:161], v[110:113]
	v_mfma_f32_16x16x32_bf16 v[106:109], v[142:145], v[158:161], v[106:109]
	v_mfma_f32_16x16x32_bf16 v[94:97], v[134:137], v[166:169], v[94:97]
	v_mfma_f32_16x16x32_bf16 v[90:93], v[142:145], v[166:169], v[90:93]
	v_mfma_f32_16x16x32_bf16 v[78:81], v[134:137], v[174:177], v[78:81]
	v_mfma_f32_16x16x32_bf16 v[74:77], v[142:145], v[174:177], v[74:77]
	s_barrier
	s_add_i32 s87, 0, 0x1c000
	v_add_u32_e32 v204, s87, v212
	s_add_i32 m0, s38, 0x18000
	ds_read_b128 v[178:181], v204
	ds_read_b128 v[182:185], v204 offset:1024
	ds_read_b128 v[200:203], v204 offset:2048
	ds_read_b128 v[204:207], v204 offset:3072
	s_add_u32 s98, s90, s40
	s_addc_u32 s99, s91, s41
	global_load_lds_dwordx4 v0, s[98:99]
	s_add_i32 m0, s38, 0x1a000
	s_nop 0
	global_load_lds_dwordx4 v194, s[98:99]
	s_barrier
	s_waitcnt lgkmcnt(0)
	v_mfma_f32_16x16x32_bf16 v[118:121], v[178:181], v[146:149], v[118:121]
	v_mfma_f32_16x16x32_bf16 v[114:117], v[200:203], v[146:149], v[114:117]
	v_mfma_f32_16x16x32_bf16 v[102:105], v[178:181], v[154:157], v[102:105]
	v_mfma_f32_16x16x32_bf16 v[98:101], v[200:203], v[154:157], v[98:101]
	v_mfma_f32_16x16x32_bf16 v[86:89], v[178:181], v[162:165], v[86:89]
	v_mfma_f32_16x16x32_bf16 v[82:85], v[200:203], v[162:165], v[82:85]
	v_mfma_f32_16x16x32_bf16 v[70:73], v[178:181], v[170:173], v[70:73]
	v_mfma_f32_16x16x32_bf16 v[66:69], v[200:203], v[170:173], v[66:69]
	v_mfma_f32_16x16x32_bf16 v[118:121], v[182:185], v[150:153], v[118:121]
	v_mfma_f32_16x16x32_bf16 v[114:117], v[204:207], v[150:153], v[114:117]
	v_mfma_f32_16x16x32_bf16 v[102:105], v[182:185], v[158:161], v[102:105]
	v_mfma_f32_16x16x32_bf16 v[98:101], v[204:207], v[158:161], v[98:101]
	v_mfma_f32_16x16x32_bf16 v[86:89], v[182:185], v[166:169], v[86:89]
	v_mfma_f32_16x16x32_bf16 v[82:85], v[204:207], v[166:169], v[82:85]
	v_mfma_f32_16x16x32_bf16 v[70:73], v[182:185], v[174:177], v[70:73]
	v_mfma_f32_16x16x32_bf16 v[66:69], v[204:207], v[174:177], v[66:69]
	s_mov_b32 m0, s60
	s_barrier
	ds_read_b128 v[146:149], v213 offset:49152
	ds_read_b128 v[150:153], v213 offset:50176
	ds_read_b128 v[154:157], v213 offset:51200
	ds_read_b128 v[158:161], v213 offset:52224
	ds_read_b128 v[162:165], v213 offset:53248
	ds_read_b128 v[166:169], v213 offset:54272
	ds_read_b128 v[170:173], v213 offset:55296
	ds_read_b128 v[174:177], v213 offset:56320
	s_add_u32 s98, s92, s40
	s_addc_u32 s99, s93, s41
	global_load_lds_dwordx4 v190, s[98:99]
	s_mov_b32 m0, s61
	s_nop 0
	global_load_lds_dwordx4 v192, s[98:99]
	s_waitcnt vmcnt(10)
	s_barrier
	s_waitcnt lgkmcnt(0)
	v_mfma_f32_16x16x32_bf16 v[62:65], v[130:133], v[146:149], v[62:65]
	v_mfma_f32_16x16x32_bf16 v[58:61], v[138:141], v[146:149], v[58:61]
	v_mfma_f32_16x16x32_bf16 v[46:49], v[130:133], v[154:157], v[46:49]
	v_mfma_f32_16x16x32_bf16 v[42:45], v[138:141], v[154:157], v[42:45]
	v_mfma_f32_16x16x32_bf16 v[30:33], v[130:133], v[162:165], v[30:33]
	v_mfma_f32_16x16x32_bf16 v[26:29], v[138:141], v[162:165], v[26:29]
	v_mfma_f32_16x16x32_bf16 v[14:17], v[130:133], v[170:173], v[14:17]
	v_mfma_f32_16x16x32_bf16 v[10:13], v[138:141], v[170:173], v[10:13]
	v_mfma_f32_16x16x32_bf16 v[62:65], v[134:137], v[150:153], v[62:65]
	v_mfma_f32_16x16x32_bf16 v[58:61], v[142:145], v[150:153], v[58:61]
	v_mfma_f32_16x16x32_bf16 v[46:49], v[134:137], v[158:161], v[46:49]
	v_mfma_f32_16x16x32_bf16 v[42:45], v[142:145], v[158:161], v[42:45]
	v_mfma_f32_16x16x32_bf16 v[30:33], v[134:137], v[166:169], v[30:33]
	v_mfma_f32_16x16x32_bf16 v[26:29], v[142:145], v[166:169], v[26:29]
	v_mfma_f32_16x16x32_bf16 v[14:17], v[134:137], v[174:177], v[14:17]
	v_mfma_f32_16x16x32_bf16 v[10:13], v[142:145], v[174:177], v[10:13]
	s_barrier
	s_add_u32 s88, s90, 0x40080
	s_addc_u32 s89, s91, 0
	s_add_i32 m0, s38, 0x1c000
	s_nop 0
	global_load_lds_dwordx4 v0, s[88:89]
	s_add_i32 m0, s38, 0x1e000
	s_nop 0
	global_load_lds_dwordx4 v194, s[88:89]
	ds_read_b128 v[130:133], v189
	ds_read_b128 v[134:137], v189 offset:1024
	ds_read_b128 v[138:141], v189 offset:2048
	ds_read_b128 v[142:145], v189 offset:3072
	s_waitcnt vmcnt(6)
	s_barrier
	v_mfma_f32_16x16x32_bf16 v[54:57], v[178:181], v[146:149], v[54:57]
	v_mfma_f32_16x16x32_bf16 v[50:53], v[200:203], v[146:149], v[50:53]
	v_mfma_f32_16x16x32_bf16 v[38:41], v[178:181], v[154:157], v[38:41]
	v_mfma_f32_16x16x32_bf16 v[34:37], v[200:203], v[154:157], v[34:37]
	v_mfma_f32_16x16x32_bf16 v[22:25], v[178:181], v[162:165], v[22:25]
	v_mfma_f32_16x16x32_bf16 v[18:21], v[200:203], v[162:165], v[18:21]
	v_mfma_f32_16x16x32_bf16 v[6:9], v[178:181], v[170:173], v[6:9]
	v_mfma_f32_16x16x32_bf16 v[2:5], v[200:203], v[170:173], v[2:5]
	v_mfma_f32_16x16x32_bf16 v[54:57], v[182:185], v[150:153], v[54:57]
	v_mfma_f32_16x16x32_bf16 v[50:53], v[204:207], v[150:153], v[50:53]
	v_mfma_f32_16x16x32_bf16 v[38:41], v[182:185], v[158:161], v[38:41]
	v_mfma_f32_16x16x32_bf16 v[34:37], v[204:207], v[158:161], v[34:37]
	v_mfma_f32_16x16x32_bf16 v[22:25], v[182:185], v[166:169], v[22:25]
	v_mfma_f32_16x16x32_bf16 v[18:21], v[204:207], v[166:169], v[18:21]
	v_mfma_f32_16x16x32_bf16 v[6:9], v[182:185], v[174:177], v[6:9]
	v_mfma_f32_16x16x32_bf16 v[2:5], v[204:207], v[174:177], v[2:5]
	s_add_i32 s78, s78, 2
	s_add_u32 s34, s34, 0x100
	s_addc_u32 s75, s75, 0
	s_mov_b64 s[88:89], s[4:5]
	s_add_u32 s4, s88, 0x100
	s_addc_u32 s5, s89, 0
	s_cmp_eq_u32 s78, 12
	s_cselect_b32 s93, s17, s5
	s_cselect_b32 s92, s16, s4
	s_cselect_b32 s91, s15, s75
	s_cselect_b32 s90, s23, s34
	s_cmp_gt_u32 s78, 13
	s_barrier
	s_cbranch_scc0 .LBB0_838
	s_waitcnt lgkmcnt(0)
	s_lshl_b32 s4, s22, 8
	v_mov_b32_e32 v186, v252
	s_add_i32 s4, s4, s47
	s_nop 0
	v_and_or_b32 v202, v186, 15, s4
	s_lshl_b32 s4, s86, 8
	s_or_b32 s4, s4, s55
	v_lshrrev_b32_e32 v130, 1, v186
	v_and_or_b32 v200, v130, 24, s4
	v_ashrrev_i32_e32 v201, 31, v200
	v_ashrrev_i32_e32 v203, 31, v202
	v_lshl_add_u64 v[204:205], v[200:201], 2, s[6:7]
	v_lshlrev_b64 v[130:131], 12, v[202:203]
	v_lshl_add_u64 v[130:131], v[204:205], 0, v[130:131]
	global_load_dwordx4 v[216:219], v[130:131], off offset:16
	global_load_dwordx4 v[220:223], v[130:131], off
	global_load_dwordx4 v[178:181], v[130:131], off offset:528
	global_load_dwordx4 v[182:185], v[130:131], off offset:512
	v_or_b32_e32 v210, 16, v202
	v_ashrrev_i32_e32 v211, 31, v210
	v_lshlrev_b64 v[130:131], 12, v[210:211]
	v_or_b32_e32 v208, 32, v202
	v_lshl_add_u64 v[130:131], v[204:205], 0, v[130:131]
	v_ashrrev_i32_e32 v209, 31, v208
	global_load_dwordx4 v[170:173], v[130:131], off offset:16
	global_load_dwordx4 v[174:177], v[130:131], off
	global_load_dwordx4 v[162:165], v[130:131], off offset:528
	global_load_dwordx4 v[166:169], v[130:131], off offset:512
	v_lshlrev_b64 v[130:131], 12, v[208:209]
	v_or_b32_e32 v206, 48, v202
	v_lshl_add_u64 v[130:131], v[204:205], 0, v[130:131]
	v_ashrrev_i32_e32 v207, 31, v206
	global_load_dwordx4 v[154:157], v[130:131], off offset:16
	global_load_dwordx4 v[158:161], v[130:131], off
	global_load_dwordx4 v[138:141], v[130:131], off offset:528
	global_load_dwordx4 v[142:145], v[130:131], off offset:512
	v_lshlrev_b64 v[130:131], 12, v[206:207]
	v_lshl_add_u64 v[134:135], v[204:205], 0, v[130:131]
	global_load_dwordx4 v[146:149], v[134:135], off offset:16
	global_load_dwordx4 v[150:153], v[134:135], off
	global_load_dwordx4 v[130:133], v[134:135], off offset:528
	s_nop 0
	global_load_dwordx4 v[134:137], v[134:135], off offset:512
	v_and_b32_e32 v186, 63, v186
	v_lshlrev_b32_e32 v187, 2, v186
	v_xor_b32_e32 v215, 64, v187
	v_xor_b32_e32 v214, 0x80, v187
	v_cmp_gt_u32_e32 vcc, 16, v186
	v_lshlrev_b64 v[186:187], 10, v[202:203]
	v_lshl_add_u64 v[186:187], v[186:187], 0, v[200:201]
	s_lshl_b32 s4, s86, 2
	s_ashr_i32 s5, s4, 31
	s_waitcnt vmcnt(0)
	v_pk_add_f32 v[124:125], v[124:125], v[218:219]
	v_pk_add_f32 v[128:129], v[128:129], v[222:223]
	v_pk_add_f32 v[126:127], v[126:127], v[220:221]
	v_pk_mul_f32 v[218:219], v[128:129], v[128:129]
	v_pk_mul_f32 v[220:221], v[126:127], v[126:127]
	v_pk_add_f32 v[122:123], v[122:123], v[216:217]
	v_lshl_add_u64 v[216:217], v[186:187], 2, s[12:13]
	v_add_f32_e32 v220, v220, v221
	v_add_f32_e32 v218, v218, v219
	global_store_dwordx4 v[216:217], v[126:129], off
	global_store_dwordx4 v[216:217], v[122:125], off offset:16
	v_add_f32_e32 v222, v220, v218
	v_pk_mul_f32 v[220:221], v[122:123], v[122:123]
	v_cvt_pk_bf16_f32 v126, v126, v127
	v_cvt_pk_bf16_f32 v127, v128, v129
	v_cvt_pk_bf16_f32 v128, v122, v123
	v_cvt_pk_bf16_f32 v129, v124, v125
	v_lshl_add_u64 v[122:123], v[186:187], 1, s[8:9]
	v_pk_add_f32 v[120:121], v[120:121], v[184:185]
	v_pk_add_f32 v[118:119], v[118:119], v[182:183]
	v_pk_mul_f32 v[218:219], v[124:125], v[124:125]
	global_store_dwordx4 v[122:123], v[126:129], off
	v_pk_mul_f32 v[124:125], v[120:121], v[120:121]
	v_pk_add_f32 v[116:117], v[116:117], v[180:181]
	v_pk_mul_f32 v[126:127], v[118:119], v[118:119]
	v_pk_add_f32 v[114:115], v[114:115], v[178:179]
	v_add_f32_e32 v126, v126, v127
	v_add_f32_e32 v124, v124, v125
	v_add_f32_e32 v128, v126, v124
	v_pk_mul_f32 v[124:125], v[116:117], v[116:117]
	v_pk_mul_f32 v[126:127], v[114:115], v[114:115]
	v_add_f32_e32 v220, v220, v221
	v_add_f32_e32 v218, v218, v219
	v_add_f32_e32 v126, v126, v127
	v_add_f32_e32 v124, v124, v125
	v_add_f32_e32 v218, v220, v218
	v_add_f32_e32 v124, v126, v124
	v_add_f32_e32 v218, v222, v218
	v_add_f32_e32 v124, v128, v124
	v_add_f32_e32 v124, v218, v124
	global_store_dwordx4 v[216:217], v[118:121], off offset:512
	global_store_dwordx4 v[216:217], v[114:117], off offset:528
	s_nop 0
	v_cvt_pk_bf16_f32 v118, v118, v119
	v_cvt_pk_bf16_f32 v119, v120, v121
	v_cvt_pk_bf16_f32 v120, v114, v115
	ds_bpermute_b32 v114, v215, v124
	v_cvt_pk_bf16_f32 v121, v116, v117
	global_store_dwordx4 v[122:123], v[118:121], off offset:256
	s_waitcnt lgkmcnt(0)
	v_add_f32_e32 v114, v124, v114
	ds_bpermute_b32 v115, v214, v114
	s_and_saveexec_b64 s[22:23], vcc
	s_cbranch_execz .LBB0_841
	v_lshlrev_b64 v[116:117], 6, v[202:203]
	v_lshl_add_u64 v[116:117], s[10:11], 0, v[116:117]
	v_lshl_add_u64 v[116:117], s[4:5], 2, v[116:117]
	s_lshl_b32 s34, s45, 2
	v_lshl_add_u64 v[116:117], v[116:117], 0, s[34:35]
	s_waitcnt lgkmcnt(0)
	v_add_f32_e32 v114, v114, v115
	global_store_dword v[116:117], v114, off

.LBB0_918:
	s_ashr_i32 s17, s16, 31
	s_lshl_b64 s[22:23], s[16:17], 19
	v_mov_b64_e32 v[2:3], 0xb00
	s_add_u32 s84, s8, s22
	v_cmp_lt_i64_e32 vcc, s[28:29], v[2:3]
	s_addc_u32 s85, s9, s23
	s_and_b64 s[22:23], vcc, exec
	s_cselect_b32 s17, s85, s7
	s_cselect_b32 s22, s84, s6
	s_ashr_i32 s15, s14, 31
	s_lshl_b64 s[28:29], s[14:15], 19
	s_add_u32 s86, s37, s28
	s_addc_u32 s87, s38, s29
	s_and_b64 s[28:29], vcc, exec
	s_cselect_b32 s15, s87, s89
	s_cselect_b32 s23, s86, s88
	s_add_u32 s28, s88, 0x100
	s_addc_u32 s29, s89, 0
	s_mov_b32 s45, -2
	s_add_i32 vcc_lo, 0, 0x10000
	v_add_u32_e32 v0, vcc_lo, v254
	v_add_u32_e32 v189, 0x10000, v254
	ds_read_b128 v[130:133], v0
	ds_read_b128 v[134:137], v0 offset:1024
	ds_read_b128 v[138:141], v0 offset:2048
	ds_read_b128 v[142:145], v0 offset:3072
	s_add_u32 s88, s6, 0x100
	s_addc_u32 s89, s7, 0
	s_cmp_eq_u32 s45, 12
	s_cselect_b32 s93, s17, s89
	s_cselect_b32 s92, s22, s88
	s_cselect_b32 s91, s15, s29
	s_cselect_b32 s90, s23, s28
	s_add_i32 m0, s43, 0xc000
	ds_read_b128 v[146:149], v253
	ds_read_b128 v[150:153], v253 offset:1024
	ds_read_b128 v[168:171], v253 offset:2048
	ds_read_b128 v[172:175], v253 offset:3072
	ds_read_b128 v[176:179], v253 offset:4096
	ds_read_b128 v[180:183], v253 offset:5120
	ds_read_b128 v[184:187], v253 offset:6144
	ds_read_b128 v[190:193], v253 offset:7168
	global_load_lds_dwordx4 v164, s[6:7]
	s_add_i32 m0, s43, 0xe000
	v_lshl_add_u64 v[154:155], s[6:7], 0, v[166:167]
	global_load_lds_dwordx4 v[154:155], off
	s_waitcnt lgkmcnt(8)
	s_barrier
	s_waitcnt lgkmcnt(0)
	v_mfma_f32_16x16x32_bf16 v[126:129], v[130:133], v[146:149], 0
	v_mfma_f32_16x16x32_bf16 v[70:73], v[138:141], v[146:149], 0
	v_mfma_f32_16x16x32_bf16 v[122:125], v[130:133], v[168:171], 0
	v_mfma_f32_16x16x32_bf16 v[74:77], v[138:141], v[168:171], 0
	v_mfma_f32_16x16x32_bf16 v[114:117], v[130:133], v[176:179], 0
	v_mfma_f32_16x16x32_bf16 v[66:69], v[138:141], v[176:179], 0
	v_mfma_f32_16x16x32_bf16 v[110:113], v[130:133], v[184:187], 0
	v_mfma_f32_16x16x32_bf16 v[78:81], v[138:141], v[184:187], 0
	v_mfma_f32_16x16x32_bf16 v[126:129], v[134:137], v[150:153], v[126:129]
	v_mfma_f32_16x16x32_bf16 v[70:73], v[142:145], v[150:153], v[70:73]
	v_mfma_f32_16x16x32_bf16 v[122:125], v[134:137], v[172:175], v[122:125]
	v_mfma_f32_16x16x32_bf16 v[74:77], v[142:145], v[172:175], v[74:77]
	v_mfma_f32_16x16x32_bf16 v[114:117], v[134:137], v[180:183], v[114:117]
	v_mfma_f32_16x16x32_bf16 v[66:69], v[142:145], v[180:183], v[66:69]
	v_mfma_f32_16x16x32_bf16 v[110:113], v[134:137], v[190:193], v[110:113]
	v_mfma_f32_16x16x32_bf16 v[78:81], v[142:145], v[190:193], v[78:81]
	s_barrier
	s_add_i32 m0, s39, 0x10000
	ds_read_b128 v[194:197], v189 offset:16384
	ds_read_b128 v[198:201], v189 offset:17408
	ds_read_b128 v[202:205], v189 offset:18432
	global_load_lds_dwordx4 v160, s[90:91]
	s_add_i32 m0, s39, 0x12000
	ds_read_b128 v[206:209], v189 offset:19456
	global_load_lds_dwordx4 v156, s[90:91]
	s_barrier
	s_waitcnt lgkmcnt(0)
	v_mfma_f32_16x16x32_bf16 v[118:121], v[194:197], v[146:149], 0
	v_mfma_f32_16x16x32_bf16 v[94:97], v[202:205], v[146:149], 0
	v_mfma_f32_16x16x32_bf16 v[106:109], v[194:197], v[168:171], 0
	v_mfma_f32_16x16x32_bf16 v[90:93], v[202:205], v[168:171], 0
	v_mfma_f32_16x16x32_bf16 v[102:105], v[194:197], v[176:179], 0
	v_mfma_f32_16x16x32_bf16 v[82:85], v[202:205], v[176:179], 0
	v_mfma_f32_16x16x32_bf16 v[98:101], v[194:197], v[184:187], 0
	v_mfma_f32_16x16x32_bf16 v[86:89], v[202:205], v[184:187], 0
	v_mfma_f32_16x16x32_bf16 v[118:121], v[198:201], v[150:153], v[118:121]
	v_mfma_f32_16x16x32_bf16 v[94:97], v[206:209], v[150:153], v[94:97]
	v_mfma_f32_16x16x32_bf16 v[106:109], v[198:201], v[172:175], v[106:109]
	v_mfma_f32_16x16x32_bf16 v[90:93], v[206:209], v[172:175], v[90:93]
	v_mfma_f32_16x16x32_bf16 v[102:105], v[198:201], v[180:183], v[102:105]
	v_mfma_f32_16x16x32_bf16 v[82:85], v[206:209], v[180:183], v[82:85]
	v_mfma_f32_16x16x32_bf16 v[98:101], v[198:201], v[190:193], v[98:101]
	v_mfma_f32_16x16x32_bf16 v[86:89], v[206:209], v[190:193], v[86:89]
	s_mov_b32 m0, s43
	s_mov_b64 s[100:101], s[92:93]
	s_barrier
	ds_read_b128 v[146:149], v253 offset:16384
	ds_read_b128 v[150:153], v253 offset:17408
	ds_read_b128 v[168:171], v253 offset:18432
	ds_read_b128 v[172:175], v253 offset:19456
	ds_read_b128 v[176:179], v253 offset:20480
	ds_read_b128 v[180:183], v253 offset:21504
	ds_read_b128 v[184:187], v253 offset:22528
	global_load_lds_dwordx4 v162, s[100:101]
	s_mov_b32 m0, s60
	ds_read_b128 v[190:193], v253 offset:23552
	global_load_lds_dwordx4 v158, s[100:101]
	s_waitcnt vmcnt(10)
	s_barrier
	s_waitcnt lgkmcnt(0)
	v_mfma_f32_16x16x32_bf16 v[62:65], v[130:133], v[146:149], 0
	v_mfma_f32_16x16x32_bf16 v[10:13], v[138:141], v[146:149], 0
	v_mfma_f32_16x16x32_bf16 v[58:61], v[130:133], v[168:171], 0
	v_mfma_f32_16x16x32_bf16 v[14:17], v[138:141], v[168:171], 0
	v_mfma_f32_16x16x32_bf16 v[54:57], v[130:133], v[176:179], 0
	v_mfma_f32_16x16x32_bf16 v[6:9], v[138:141], v[176:179], 0
	v_mfma_f32_16x16x32_bf16 v[42:45], v[130:133], v[184:187], 0
	v_mfma_f32_16x16x32_bf16 v[2:5], v[138:141], v[184:187], 0
	v_mfma_f32_16x16x32_bf16 v[62:65], v[134:137], v[150:153], v[62:65]
	v_mfma_f32_16x16x32_bf16 v[10:13], v[142:145], v[150:153], v[10:13]
	v_mfma_f32_16x16x32_bf16 v[58:61], v[134:137], v[172:175], v[58:61]
	v_mfma_f32_16x16x32_bf16 v[14:17], v[142:145], v[172:175], v[14:17]
	v_mfma_f32_16x16x32_bf16 v[54:57], v[134:137], v[180:183], v[54:57]
	v_mfma_f32_16x16x32_bf16 v[6:9], v[142:145], v[180:183], v[6:9]
	v_mfma_f32_16x16x32_bf16 v[42:45], v[134:137], v[190:193], v[42:45]
	v_mfma_f32_16x16x32_bf16 v[2:5], v[142:145], v[190:193], v[2:5]
	s_barrier
	s_add_u32 s6, s90, 0x40000
	s_addc_u32 s7, s91, 0
	s_add_i32 m0, s39, 0x14000
	s_nop 0
	global_load_lds_dwordx4 v160, s[6:7]
	s_add_i32 m0, s39, 0x16000
	s_nop 0
	global_load_lds_dwordx4 v156, s[6:7]
	ds_read_b128 v[130:133], v189 offset:32768
	ds_read_b128 v[134:137], v189 offset:33792
	ds_read_b128 v[138:141], v189 offset:34816
	ds_read_b128 v[142:145], v189 offset:35840
	s_waitcnt vmcnt(6)
	s_barrier
	v_mfma_f32_16x16x32_bf16 v[50:53], v[194:197], v[146:149], 0
	v_mfma_f32_16x16x32_bf16 v[26:29], v[202:205], v[146:149], 0
	v_mfma_f32_16x16x32_bf16 v[46:49], v[194:197], v[168:171], 0
	v_mfma_f32_16x16x32_bf16 v[30:33], v[202:205], v[168:171], 0
	v_mfma_f32_16x16x32_bf16 v[38:41], v[194:197], v[176:179], 0
	v_mfma_f32_16x16x32_bf16 v[22:25], v[202:205], v[176:179], 0
	v_mfma_f32_16x16x32_bf16 v[34:37], v[194:197], v[184:187], 0
	v_mfma_f32_16x16x32_bf16 v[18:21], v[202:205], v[184:187], 0
	v_mfma_f32_16x16x32_bf16 v[50:53], v[198:201], v[150:153], v[50:53]
	v_mfma_f32_16x16x32_bf16 v[26:29], v[206:209], v[150:153], v[26:29]
	v_mfma_f32_16x16x32_bf16 v[46:49], v[198:201], v[172:175], v[46:49]
	v_mfma_f32_16x16x32_bf16 v[30:33], v[206:209], v[172:175], v[30:33]
	v_mfma_f32_16x16x32_bf16 v[38:41], v[198:201], v[180:183], v[38:41]
	v_mfma_f32_16x16x32_bf16 v[22:25], v[206:209], v[180:183], v[22:25]
	v_mfma_f32_16x16x32_bf16 v[34:37], v[198:201], v[190:193], v[34:37]
	v_mfma_f32_16x16x32_bf16 v[18:21], v[206:209], v[190:193], v[18:21]
	s_barrier
	s_add_u32 s6, s92, 0x40000
	s_addc_u32 s7, s93, 0
	s_mov_b32 m0, s61
	ds_read_b128 v[146:149], v253 offset:32768
	ds_read_b128 v[150:153], v253 offset:33792
	ds_read_b128 v[168:171], v253 offset:34816
	ds_read_b128 v[172:175], v253 offset:35840
	ds_read_b128 v[176:179], v253 offset:36864
	ds_read_b128 v[180:183], v253 offset:37888
	ds_read_b128 v[184:187], v253 offset:38912
	global_load_lds_dwordx4 v162, s[6:7]
	s_mov_b32 m0, s72
	ds_read_b128 v[190:193], v253 offset:39936
	global_load_lds_dwordx4 v158, s[6:7]
	s_waitcnt lgkmcnt(8)
	s_barrier
	s_waitcnt lgkmcnt(0)
	v_mfma_f32_16x16x32_bf16 v[126:129], v[130:133], v[146:149], v[126:129]
	v_mfma_f32_16x16x32_bf16 v[70:73], v[138:141], v[146:149], v[70:73]
	v_mfma_f32_16x16x32_bf16 v[122:125], v[130:133], v[168:171], v[122:125]
	v_mfma_f32_16x16x32_bf16 v[74:77], v[138:141], v[168:171], v[74:77]
	v_mfma_f32_16x16x32_bf16 v[114:117], v[130:133], v[176:179], v[114:117]
	v_mfma_f32_16x16x32_bf16 v[66:69], v[138:141], v[176:179], v[66:69]
	v_mfma_f32_16x16x32_bf16 v[110:113], v[130:133], v[184:187], v[110:113]
	v_mfma_f32_16x16x32_bf16 v[78:81], v[138:141], v[184:187], v[78:81]
	v_mfma_f32_16x16x32_bf16 v[126:129], v[134:137], v[150:153], v[126:129]
	v_mfma_f32_16x16x32_bf16 v[70:73], v[142:145], v[150:153], v[70:73]
	v_mfma_f32_16x16x32_bf16 v[122:125], v[134:137], v[172:175], v[122:125]
	v_mfma_f32_16x16x32_bf16 v[74:77], v[142:145], v[172:175], v[74:77]
	v_mfma_f32_16x16x32_bf16 v[114:117], v[134:137], v[180:183], v[114:117]
	v_mfma_f32_16x16x32_bf16 v[66:69], v[142:145], v[180:183], v[66:69]
	v_mfma_f32_16x16x32_bf16 v[110:113], v[134:137], v[190:193], v[110:113]
	v_mfma_f32_16x16x32_bf16 v[78:81], v[142:145], v[190:193], v[78:81]
	s_barrier
	s_add_i32 m0, s39, 0x18000
	ds_read_b128 v[194:197], v189 offset:49152
	ds_read_b128 v[198:201], v189 offset:50176
	ds_read_b128 v[202:205], v189 offset:51200
	ds_read_b128 v[206:209], v189 offset:52224
	s_add_u32 s98, s90, s40
	s_addc_u32 s99, s91, s41
	global_load_lds_dwordx4 v160, s[98:99]
	s_add_i32 m0, s39, 0x1a000
	s_nop 0
	global_load_lds_dwordx4 v156, s[98:99]
	s_barrier
	s_waitcnt lgkmcnt(0)
	v_mfma_f32_16x16x32_bf16 v[118:121], v[194:197], v[146:149], v[118:121]
	v_mfma_f32_16x16x32_bf16 v[94:97], v[202:205], v[146:149], v[94:97]
	v_mfma_f32_16x16x32_bf16 v[106:109], v[194:197], v[168:171], v[106:109]
	v_mfma_f32_16x16x32_bf16 v[90:93], v[202:205], v[168:171], v[90:93]
	v_mfma_f32_16x16x32_bf16 v[102:105], v[194:197], v[176:179], v[102:105]
	v_mfma_f32_16x16x32_bf16 v[82:85], v[202:205], v[176:179], v[82:85]
	v_mfma_f32_16x16x32_bf16 v[98:101], v[194:197], v[184:187], v[98:101]
	v_mfma_f32_16x16x32_bf16 v[86:89], v[202:205], v[184:187], v[86:89]
	v_mfma_f32_16x16x32_bf16 v[118:121], v[198:201], v[150:153], v[118:121]
	v_mfma_f32_16x16x32_bf16 v[94:97], v[206:209], v[150:153], v[94:97]
	v_mfma_f32_16x16x32_bf16 v[106:109], v[198:201], v[172:175], v[106:109]
	v_mfma_f32_16x16x32_bf16 v[90:93], v[206:209], v[172:175], v[90:93]
	v_mfma_f32_16x16x32_bf16 v[102:105], v[198:201], v[180:183], v[102:105]
	v_mfma_f32_16x16x32_bf16 v[82:85], v[206:209], v[180:183], v[82:85]
	v_mfma_f32_16x16x32_bf16 v[98:101], v[198:201], v[190:193], v[98:101]
	v_mfma_f32_16x16x32_bf16 v[86:89], v[206:209], v[190:193], v[86:89]
	s_mov_b32 m0, s95
	s_barrier
	ds_read_b128 v[146:149], v253 offset:49152
	ds_read_b128 v[150:153], v253 offset:50176
	ds_read_b128 v[168:171], v253 offset:51200
	ds_read_b128 v[172:175], v253 offset:52224
	ds_read_b128 v[176:179], v253 offset:53248
	ds_read_b128 v[180:183], v253 offset:54272
	ds_read_b128 v[184:187], v253 offset:55296
	ds_read_b128 v[190:193], v253 offset:56320
	s_add_u32 s98, s100, s40
	s_addc_u32 s99, s101, s41
	global_load_lds_dwordx4 v162, s[98:99]
	s_mov_b32 m0, s96
	s_nop 0
	global_load_lds_dwordx4 v158, s[98:99]
	s_waitcnt vmcnt(10)
	s_barrier
	s_waitcnt lgkmcnt(0)
	v_mfma_f32_16x16x32_bf16 v[62:65], v[130:133], v[146:149], v[62:65]
	v_mfma_f32_16x16x32_bf16 v[10:13], v[138:141], v[146:149], v[10:13]
	v_mfma_f32_16x16x32_bf16 v[58:61], v[130:133], v[168:171], v[58:61]
	v_mfma_f32_16x16x32_bf16 v[14:17], v[138:141], v[168:171], v[14:17]
	v_mfma_f32_16x16x32_bf16 v[54:57], v[130:133], v[176:179], v[54:57]
	v_mfma_f32_16x16x32_bf16 v[6:9], v[138:141], v[176:179], v[6:9]
	v_mfma_f32_16x16x32_bf16 v[42:45], v[130:133], v[184:187], v[42:45]
	v_mfma_f32_16x16x32_bf16 v[2:5], v[138:141], v[184:187], v[2:5]
	v_mfma_f32_16x16x32_bf16 v[62:65], v[134:137], v[150:153], v[62:65]
	v_mfma_f32_16x16x32_bf16 v[10:13], v[142:145], v[150:153], v[10:13]
	v_mfma_f32_16x16x32_bf16 v[58:61], v[134:137], v[172:175], v[58:61]
	v_mfma_f32_16x16x32_bf16 v[14:17], v[142:145], v[172:175], v[14:17]
	v_mfma_f32_16x16x32_bf16 v[54:57], v[134:137], v[180:183], v[54:57]
	v_mfma_f32_16x16x32_bf16 v[6:9], v[142:145], v[180:183], v[6:9]
	v_mfma_f32_16x16x32_bf16 v[42:45], v[134:137], v[190:193], v[42:45]
	v_mfma_f32_16x16x32_bf16 v[2:5], v[142:145], v[190:193], v[2:5]
	s_barrier
	s_add_u32 s6, s90, 0x40080
	s_addc_u32 s7, s91, 0
	s_add_i32 m0, s39, 0x1c000
	s_nop 0
	global_load_lds_dwordx4 v160, s[6:7]
	s_add_i32 m0, s39, 0x1e000
	s_nop 0
	global_load_lds_dwordx4 v156, s[6:7]
	ds_read_b128 v[130:133], v189
	ds_read_b128 v[134:137], v189 offset:1024
	ds_read_b128 v[138:141], v189 offset:2048
	ds_read_b128 v[142:145], v189 offset:3072
	s_waitcnt vmcnt(6)
	s_barrier
	v_mfma_f32_16x16x32_bf16 v[50:53], v[194:197], v[146:149], v[50:53]
	v_mfma_f32_16x16x32_bf16 v[26:29], v[202:205], v[146:149], v[26:29]
	v_mfma_f32_16x16x32_bf16 v[46:49], v[194:197], v[168:171], v[46:49]
	v_mfma_f32_16x16x32_bf16 v[30:33], v[202:205], v[168:171], v[30:33]
	v_mfma_f32_16x16x32_bf16 v[38:41], v[194:197], v[176:179], v[38:41]
	v_mfma_f32_16x16x32_bf16 v[22:25], v[202:205], v[176:179], v[22:25]
	v_mfma_f32_16x16x32_bf16 v[34:37], v[194:197], v[184:187], v[34:37]
	v_mfma_f32_16x16x32_bf16 v[18:21], v[202:205], v[184:187], v[18:21]
	v_mfma_f32_16x16x32_bf16 v[50:53], v[198:201], v[150:153], v[50:53]
	v_mfma_f32_16x16x32_bf16 v[26:29], v[206:209], v[150:153], v[26:29]
	v_mfma_f32_16x16x32_bf16 v[46:49], v[198:201], v[172:175], v[46:49]
	v_mfma_f32_16x16x32_bf16 v[30:33], v[206:209], v[172:175], v[30:33]
	v_mfma_f32_16x16x32_bf16 v[38:41], v[198:201], v[180:183], v[38:41]
	v_mfma_f32_16x16x32_bf16 v[22:25], v[206:209], v[180:183], v[22:25]
	v_mfma_f32_16x16x32_bf16 v[34:37], v[198:201], v[190:193], v[34:37]
	v_mfma_f32_16x16x32_bf16 v[18:21], v[206:209], v[190:193], v[18:21]
	s_add_i32 s45, s45, 2
	s_add_u32 s28, s28, 0x100
	s_addc_u32 s29, s29, 0
	s_mov_b64 s[6:7], s[88:89]
	s_add_u32 s88, s6, 0x100
	s_addc_u32 s89, s7, 0
	s_cmp_eq_u32 s45, 12
	s_cselect_b32 s93, s17, s89
	s_cselect_b32 s92, s22, s88
	s_cselect_b32 s91, s15, s29
	s_cselect_b32 s90, s23, s28
	s_cmp_gt_u32 s45, 13
	s_barrier
.LBB0_919:
	s_add_i32 m0, s43, 0xc000
	ds_read_b128 v[146:149], v253
	ds_read_b128 v[150:153], v253 offset:1024
	ds_read_b128 v[168:171], v253 offset:2048
	ds_read_b128 v[172:175], v253 offset:3072
	ds_read_b128 v[176:179], v253 offset:4096
	ds_read_b128 v[180:183], v253 offset:5120
	ds_read_b128 v[184:187], v253 offset:6144
	ds_read_b128 v[190:193], v253 offset:7168
	global_load_lds_dwordx4 v164, s[6:7]
	s_add_i32 m0, s43, 0xe000
	v_lshl_add_u64 v[154:155], s[6:7], 0, v[166:167]
	global_load_lds_dwordx4 v[154:155], off
	s_waitcnt lgkmcnt(8)
	s_barrier
	s_waitcnt lgkmcnt(0)
	v_mfma_f32_16x16x32_bf16 v[126:129], v[130:133], v[146:149], v[126:129]
	v_mfma_f32_16x16x32_bf16 v[70:73], v[138:141], v[146:149], v[70:73]
	v_mfma_f32_16x16x32_bf16 v[122:125], v[130:133], v[168:171], v[122:125]
	v_mfma_f32_16x16x32_bf16 v[74:77], v[138:141], v[168:171], v[74:77]
	v_mfma_f32_16x16x32_bf16 v[114:117], v[130:133], v[176:179], v[114:117]
	v_mfma_f32_16x16x32_bf16 v[66:69], v[138:141], v[176:179], v[66:69]
	v_mfma_f32_16x16x32_bf16 v[110:113], v[130:133], v[184:187], v[110:113]
	v_mfma_f32_16x16x32_bf16 v[78:81], v[138:141], v[184:187], v[78:81]
	v_mfma_f32_16x16x32_bf16 v[126:129], v[134:137], v[150:153], v[126:129]
	v_mfma_f32_16x16x32_bf16 v[70:73], v[142:145], v[150:153], v[70:73]
	v_mfma_f32_16x16x32_bf16 v[122:125], v[134:137], v[172:175], v[122:125]
	v_mfma_f32_16x16x32_bf16 v[74:77], v[142:145], v[172:175], v[74:77]
	v_mfma_f32_16x16x32_bf16 v[114:117], v[134:137], v[180:183], v[114:117]
	v_mfma_f32_16x16x32_bf16 v[66:69], v[142:145], v[180:183], v[66:69]
	v_mfma_f32_16x16x32_bf16 v[110:113], v[134:137], v[190:193], v[110:113]
	v_mfma_f32_16x16x32_bf16 v[78:81], v[142:145], v[190:193], v[78:81]
	s_barrier
	s_add_i32 m0, s39, 0x10000
	ds_read_b128 v[194:197], v189 offset:16384
	ds_read_b128 v[198:201], v189 offset:17408
	ds_read_b128 v[202:205], v189 offset:18432
	global_load_lds_dwordx4 v160, s[90:91]
	s_add_i32 m0, s39, 0x12000
	ds_read_b128 v[206:209], v189 offset:19456
	global_load_lds_dwordx4 v156, s[90:91]
	s_barrier
	s_waitcnt lgkmcnt(0)
	v_mfma_f32_16x16x32_bf16 v[118:121], v[194:197], v[146:149], v[118:121]
	v_mfma_f32_16x16x32_bf16 v[94:97], v[202:205], v[146:149], v[94:97]
	v_mfma_f32_16x16x32_bf16 v[106:109], v[194:197], v[168:171], v[106:109]
	v_mfma_f32_16x16x32_bf16 v[90:93], v[202:205], v[168:171], v[90:93]
	v_mfma_f32_16x16x32_bf16 v[102:105], v[194:197], v[176:179], v[102:105]
	v_mfma_f32_16x16x32_bf16 v[82:85], v[202:205], v[176:179], v[82:85]
	v_mfma_f32_16x16x32_bf16 v[98:101], v[194:197], v[184:187], v[98:101]
	v_mfma_f32_16x16x32_bf16 v[86:89], v[202:205], v[184:187], v[86:89]
	v_mfma_f32_16x16x32_bf16 v[118:121], v[198:201], v[150:153], v[118:121]
	v_mfma_f32_16x16x32_bf16 v[94:97], v[206:209], v[150:153], v[94:97]
	v_mfma_f32_16x16x32_bf16 v[106:109], v[198:201], v[172:175], v[106:109]
	v_mfma_f32_16x16x32_bf16 v[90:93], v[206:209], v[172:175], v[90:93]
	v_mfma_f32_16x16x32_bf16 v[102:105], v[198:201], v[180:183], v[102:105]
	v_mfma_f32_16x16x32_bf16 v[82:85], v[206:209], v[180:183], v[82:85]
	v_mfma_f32_16x16x32_bf16 v[98:101], v[198:201], v[190:193], v[98:101]
	v_mfma_f32_16x16x32_bf16 v[86:89], v[206:209], v[190:193], v[86:89]
	s_mov_b32 m0, s43
	s_mov_b64 s[100:101], s[92:93]
	s_barrier
	ds_read_b128 v[146:149], v253 offset:16384
	ds_read_b128 v[150:153], v253 offset:17408
	ds_read_b128 v[168:171], v253 offset:18432
	ds_read_b128 v[172:175], v253 offset:19456
	ds_read_b128 v[176:179], v253 offset:20480
	ds_read_b128 v[180:183], v253 offset:21504
	ds_read_b128 v[184:187], v253 offset:22528
	global_load_lds_dwordx4 v162, s[100:101]
	s_mov_b32 m0, s60
	ds_read_b128 v[190:193], v253 offset:23552
	global_load_lds_dwordx4 v158, s[100:101]
	s_waitcnt vmcnt(10)
	s_barrier
	s_waitcnt lgkmcnt(0)
	v_mfma_f32_16x16x32_bf16 v[62:65], v[130:133], v[146:149], v[62:65]
	v_mfma_f32_16x16x32_bf16 v[10:13], v[138:141], v[146:149], v[10:13]
	v_mfma_f32_16x16x32_bf16 v[58:61], v[130:133], v[168:171], v[58:61]
	v_mfma_f32_16x16x32_bf16 v[14:17], v[138:141], v[168:171], v[14:17]
	v_mfma_f32_16x16x32_bf16 v[54:57], v[130:133], v[176:179], v[54:57]
	v_mfma_f32_16x16x32_bf16 v[6:9], v[138:141], v[176:179], v[6:9]
	v_mfma_f32_16x16x32_bf16 v[42:45], v[130:133], v[184:187], v[42:45]
	v_mfma_f32_16x16x32_bf16 v[2:5], v[138:141], v[184:187], v[2:5]
	v_mfma_f32_16x16x32_bf16 v[62:65], v[134:137], v[150:153], v[62:65]
	v_mfma_f32_16x16x32_bf16 v[10:13], v[142:145], v[150:153], v[10:13]
	v_mfma_f32_16x16x32_bf16 v[58:61], v[134:137], v[172:175], v[58:61]
	v_mfma_f32_16x16x32_bf16 v[14:17], v[142:145], v[172:175], v[14:17]
	v_mfma_f32_16x16x32_bf16 v[54:57], v[134:137], v[180:183], v[54:57]
	v_mfma_f32_16x16x32_bf16 v[6:9], v[142:145], v[180:183], v[6:9]
	v_mfma_f32_16x16x32_bf16 v[42:45], v[134:137], v[190:193], v[42:45]
	v_mfma_f32_16x16x32_bf16 v[2:5], v[142:145], v[190:193], v[2:5]
	s_barrier
	s_add_u32 s6, s90, 0x40000
	s_addc_u32 s7, s91, 0
	s_add_i32 m0, s39, 0x14000
	s_nop 0
	global_load_lds_dwordx4 v160, s[6:7]
	s_add_i32 m0, s39, 0x16000
	s_nop 0
	global_load_lds_dwordx4 v156, s[6:7]
	ds_read_b128 v[130:133], v189 offset:32768
	ds_read_b128 v[134:137], v189 offset:33792
	ds_read_b128 v[138:141], v189 offset:34816
	ds_read_b128 v[142:145], v189 offset:35840
	s_waitcnt vmcnt(6)
	s_barrier
	v_mfma_f32_16x16x32_bf16 v[50:53], v[194:197], v[146:149], v[50:53]
	v_mfma_f32_16x16x32_bf16 v[26:29], v[202:205], v[146:149], v[26:29]
	v_mfma_f32_16x16x32_bf16 v[46:49], v[194:197], v[168:171], v[46:49]
	v_mfma_f32_16x16x32_bf16 v[30:33], v[202:205], v[168:171], v[30:33]
	v_mfma_f32_16x16x32_bf16 v[38:41], v[194:197], v[176:179], v[38:41]
	v_mfma_f32_16x16x32_bf16 v[22:25], v[202:205], v[176:179], v[22:25]
	v_mfma_f32_16x16x32_bf16 v[34:37], v[194:197], v[184:187], v[34:37]
	v_mfma_f32_16x16x32_bf16 v[18:21], v[202:205], v[184:187], v[18:21]
	v_mfma_f32_16x16x32_bf16 v[50:53], v[198:201], v[150:153], v[50:53]
	v_mfma_f32_16x16x32_bf16 v[26:29], v[206:209], v[150:153], v[26:29]
	v_mfma_f32_16x16x32_bf16 v[46:49], v[198:201], v[172:175], v[46:49]
	v_mfma_f32_16x16x32_bf16 v[30:33], v[206:209], v[172:175], v[30:33]
	v_mfma_f32_16x16x32_bf16 v[38:41], v[198:201], v[180:183], v[38:41]
	v_mfma_f32_16x16x32_bf16 v[22:25], v[206:209], v[180:183], v[22:25]
	v_mfma_f32_16x16x32_bf16 v[34:37], v[198:201], v[190:193], v[34:37]
	v_mfma_f32_16x16x32_bf16 v[18:21], v[206:209], v[190:193], v[18:21]
	s_barrier
	s_add_u32 s6, s92, 0x40000
	s_addc_u32 s7, s93, 0
	s_mov_b32 m0, s61
	ds_read_b128 v[146:149], v253 offset:32768
	ds_read_b128 v[150:153], v253 offset:33792
	ds_read_b128 v[168:171], v253 offset:34816
	ds_read_b128 v[172:175], v253 offset:35840
	ds_read_b128 v[176:179], v253 offset:36864
	ds_read_b128 v[180:183], v253 offset:37888
	ds_read_b128 v[184:187], v253 offset:38912
	global_load_lds_dwordx4 v162, s[6:7]
	s_mov_b32 m0, s72
	ds_read_b128 v[190:193], v253 offset:39936
	global_load_lds_dwordx4 v158, s[6:7]
	s_waitcnt lgkmcnt(8)
	s_barrier
	s_waitcnt lgkmcnt(0)
	v_mfma_f32_16x16x32_bf16 v[126:129], v[130:133], v[146:149], v[126:129]
	v_mfma_f32_16x16x32_bf16 v[70:73], v[138:141], v[146:149], v[70:73]
	v_mfma_f32_16x16x32_bf16 v[122:125], v[130:133], v[168:171], v[122:125]
	v_mfma_f32_16x16x32_bf16 v[74:77], v[138:141], v[168:171], v[74:77]
	v_mfma_f32_16x16x32_bf16 v[114:117], v[130:133], v[176:179], v[114:117]
	v_mfma_f32_16x16x32_bf16 v[66:69], v[138:141], v[176:179], v[66:69]
	v_mfma_f32_16x16x32_bf16 v[110:113], v[130:133], v[184:187], v[110:113]
	v_mfma_f32_16x16x32_bf16 v[78:81], v[138:141], v[184:187], v[78:81]
	v_mfma_f32_16x16x32_bf16 v[126:129], v[134:137], v[150:153], v[126:129]
	v_mfma_f32_16x16x32_bf16 v[70:73], v[142:145], v[150:153], v[70:73]
	v_mfma_f32_16x16x32_bf16 v[122:125], v[134:137], v[172:175], v[122:125]
	v_mfma_f32_16x16x32_bf16 v[74:77], v[142:145], v[172:175], v[74:77]
	v_mfma_f32_16x16x32_bf16 v[114:117], v[134:137], v[180:183], v[114:117]
	v_mfma_f32_16x16x32_bf16 v[66:69], v[142:145], v[180:183], v[66:69]
	v_mfma_f32_16x16x32_bf16 v[110:113], v[134:137], v[190:193], v[110:113]
	v_mfma_f32_16x16x32_bf16 v[78:81], v[142:145], v[190:193], v[78:81]
	s_barrier
	s_add_i32 m0, s39, 0x18000
	ds_read_b128 v[194:197], v189 offset:49152
	ds_read_b128 v[198:201], v189 offset:50176
	ds_read_b128 v[202:205], v189 offset:51200
	ds_read_b128 v[206:209], v189 offset:52224
	s_add_u32 s98, s90, s40
	s_addc_u32 s99, s91, s41
	global_load_lds_dwordx4 v160, s[98:99]
	s_add_i32 m0, s39, 0x1a000
	s_nop 0
	global_load_lds_dwordx4 v156, s[98:99]
	s_barrier
	s_waitcnt lgkmcnt(0)
	v_mfma_f32_16x16x32_bf16 v[118:121], v[194:197], v[146:149], v[118:121]
	v_mfma_f32_16x16x32_bf16 v[94:97], v[202:205], v[146:149], v[94:97]
	v_mfma_f32_16x16x32_bf16 v[106:109], v[194:197], v[168:171], v[106:109]
	v_mfma_f32_16x16x32_bf16 v[90:93], v[202:205], v[168:171], v[90:93]
	v_mfma_f32_16x16x32_bf16 v[102:105], v[194:197], v[176:179], v[102:105]
	v_mfma_f32_16x16x32_bf16 v[82:85], v[202:205], v[176:179], v[82:85]
	v_mfma_f32_16x16x32_bf16 v[98:101], v[194:197], v[184:187], v[98:101]
	v_mfma_f32_16x16x32_bf16 v[86:89], v[202:205], v[184:187], v[86:89]
	v_mfma_f32_16x16x32_bf16 v[118:121], v[198:201], v[150:153], v[118:121]
	v_mfma_f32_16x16x32_bf16 v[94:97], v[206:209], v[150:153], v[94:97]
	v_mfma_f32_16x16x32_bf16 v[106:109], v[198:201], v[172:175], v[106:109]
	v_mfma_f32_16x16x32_bf16 v[90:93], v[206:209], v[172:175], v[90:93]
	v_mfma_f32_16x16x32_bf16 v[102:105], v[198:201], v[180:183], v[102:105]
	v_mfma_f32_16x16x32_bf16 v[82:85], v[206:209], v[180:183], v[82:85]
	v_mfma_f32_16x16x32_bf16 v[98:101], v[198:201], v[190:193], v[98:101]
	v_mfma_f32_16x16x32_bf16 v[86:89], v[206:209], v[190:193], v[86:89]
	s_mov_b32 m0, s95
	s_barrier
	ds_read_b128 v[146:149], v253 offset:49152
	ds_read_b128 v[150:153], v253 offset:50176
	ds_read_b128 v[168:171], v253 offset:51200
	ds_read_b128 v[172:175], v253 offset:52224
	ds_read_b128 v[176:179], v253 offset:53248
	ds_read_b128 v[180:183], v253 offset:54272
	ds_read_b128 v[184:187], v253 offset:55296
	ds_read_b128 v[190:193], v253 offset:56320
	s_add_u32 s98, s100, s40
	s_addc_u32 s99, s101, s41
	global_load_lds_dwordx4 v162, s[98:99]
	s_mov_b32 m0, s96
	s_nop 0
	global_load_lds_dwordx4 v158, s[98:99]
	s_waitcnt vmcnt(10)
	s_barrier
	s_waitcnt lgkmcnt(0)
	v_mfma_f32_16x16x32_bf16 v[62:65], v[130:133], v[146:149], v[62:65]
	v_mfma_f32_16x16x32_bf16 v[10:13], v[138:141], v[146:149], v[10:13]
	v_mfma_f32_16x16x32_bf16 v[58:61], v[130:133], v[168:171], v[58:61]
	v_mfma_f32_16x16x32_bf16 v[14:17], v[138:141], v[168:171], v[14:17]
	v_mfma_f32_16x16x32_bf16 v[54:57], v[130:133], v[176:179], v[54:57]
	v_mfma_f32_16x16x32_bf16 v[6:9], v[138:141], v[176:179], v[6:9]
	v_mfma_f32_16x16x32_bf16 v[42:45], v[130:133], v[184:187], v[42:45]
	v_mfma_f32_16x16x32_bf16 v[2:5], v[138:141], v[184:187], v[2:5]
	v_mfma_f32_16x16x32_bf16 v[62:65], v[134:137], v[150:153], v[62:65]
	v_mfma_f32_16x16x32_bf16 v[10:13], v[142:145], v[150:153], v[10:13]
	v_mfma_f32_16x16x32_bf16 v[58:61], v[134:137], v[172:175], v[58:61]
	v_mfma_f32_16x16x32_bf16 v[14:17], v[142:145], v[172:175], v[14:17]
	v_mfma_f32_16x16x32_bf16 v[54:57], v[134:137], v[180:183], v[54:57]
	v_mfma_f32_16x16x32_bf16 v[6:9], v[142:145], v[180:183], v[6:9]
	v_mfma_f32_16x16x32_bf16 v[42:45], v[134:137], v[190:193], v[42:45]
	v_mfma_f32_16x16x32_bf16 v[2:5], v[142:145], v[190:193], v[2:5]
	s_barrier
	s_add_u32 s6, s90, 0x40080
	s_addc_u32 s7, s91, 0
	s_add_i32 m0, s39, 0x1c000
	s_nop 0
	global_load_lds_dwordx4 v160, s[6:7]
	s_add_i32 m0, s39, 0x1e000
	s_nop 0
	global_load_lds_dwordx4 v156, s[6:7]
	ds_read_b128 v[130:133], v189
	ds_read_b128 v[134:137], v189 offset:1024
	ds_read_b128 v[138:141], v189 offset:2048
	ds_read_b128 v[142:145], v189 offset:3072
	s_waitcnt vmcnt(6)
	s_barrier
	v_mfma_f32_16x16x32_bf16 v[50:53], v[194:197], v[146:149], v[50:53]
	v_mfma_f32_16x16x32_bf16 v[26:29], v[202:205], v[146:149], v[26:29]
	v_mfma_f32_16x16x32_bf16 v[46:49], v[194:197], v[168:171], v[46:49]
	v_mfma_f32_16x16x32_bf16 v[30:33], v[202:205], v[168:171], v[30:33]
	v_mfma_f32_16x16x32_bf16 v[38:41], v[194:197], v[176:179], v[38:41]
	v_mfma_f32_16x16x32_bf16 v[22:25], v[202:205], v[176:179], v[22:25]
	v_mfma_f32_16x16x32_bf16 v[34:37], v[194:197], v[184:187], v[34:37]
	v_mfma_f32_16x16x32_bf16 v[18:21], v[202:205], v[184:187], v[18:21]
	v_mfma_f32_16x16x32_bf16 v[50:53], v[198:201], v[150:153], v[50:53]
	v_mfma_f32_16x16x32_bf16 v[26:29], v[206:209], v[150:153], v[26:29]
	v_mfma_f32_16x16x32_bf16 v[46:49], v[198:201], v[172:175], v[46:49]
	v_mfma_f32_16x16x32_bf16 v[30:33], v[206:209], v[172:175], v[30:33]
	v_mfma_f32_16x16x32_bf16 v[38:41], v[198:201], v[180:183], v[38:41]
	v_mfma_f32_16x16x32_bf16 v[22:25], v[206:209], v[180:183], v[22:25]
	v_mfma_f32_16x16x32_bf16 v[34:37], v[198:201], v[190:193], v[34:37]
	v_mfma_f32_16x16x32_bf16 v[18:21], v[206:209], v[190:193], v[18:21]
	s_add_i32 s45, s45, 2
	s_add_u32 s28, s28, 0x100
	s_addc_u32 s29, s29, 0
	s_mov_b64 s[6:7], s[88:89]
	s_add_u32 s88, s6, 0x100
	s_addc_u32 s89, s7, 0
	s_cmp_eq_u32 s45, 12
	s_cselect_b32 s93, s17, s89
	s_cselect_b32 s92, s22, s88
	s_cselect_b32 s91, s15, s29
	s_cselect_b32 s90, s23, s28
	s_cmp_gt_u32 s45, 13
	s_barrier
	s_cbranch_scc0 .LBB0_919
	s_waitcnt lgkmcnt(0)
	v_mov_b32_e32 v131, v252
	s_lshl_b32 s88, s5, 7
	v_bfe_u32 v130, v131, 4, 2
	v_and_b32_e32 v134, 15, v131
	v_lshlrev_b32_e32 v0, 4, v130
	s_ashr_i32 s89, s88, 31
	s_lshl_b32 s15, s4, 8
	v_or3_b32 v135, v0, s97, v134
	s_lshl_b64 s[4:5], s[88:89], 2
	v_lshrrev_b32_e32 v140, 1, v135
	s_add_u32 s4, s73, s4
	s_addc_u32 s5, s74, s5
	v_lshlrev_b32_e32 v0, 2, v140
	v_and_b32_e32 v144, 1, v131
	v_lshl_add_u64 v[132:133], s[4:5], 0, v[0:1]
	v_cmp_eq_u32_e32 vcc, 1, v144
	v_mov_b32_e32 v0, 0xb00
	s_movk_i32 s4, 0x5000
	v_cndmask_b32_e32 v141, 0, v0, vcc
	v_lshlrev_b32_e32 v0, 2, v141
	v_lshl_add_u64 v[132:133], v[132:133], 0, v[0:1]
	v_add_co_u32_e32 v138, vcc, s4, v132
	s_mov_b32 s4, 0xb000
	s_nop 0
	v_addc_co_u32_e32 v139, vcc, 0, v133, vcc
	global_load_dword v136, v[132:133], off
	global_load_dword v137, v[138:139], off offset:2048
	v_add_co_u32_e32 v132, vcc, s4, v132
	v_add_u32_e32 v0, s88, v141
	s_nop 0
	v_addc_co_u32_e32 v133, vcc, 0, v133, vcc
	global_load_dword v138, v[132:133], off
	v_or_b32_e32 v132, v140, v0
	v_ashrrev_i32_e32 v133, 31, v132
	v_lshl_add_u64 v[132:133], v[132:133], 2, s[12:13]
	global_load_dword v139, v[132:133], off
	v_lshl_add_u32 v152, v135, 4, s78
	v_and_b32_e32 v135, 63, v131
	v_cmp_eq_u32_e32 vcc, 0, v144
	v_or_b32_e32 v0, s97, v135
	v_lshrrev_b32_e32 v0, 1, v0
	v_and_or_b32 v131, v0, 63, s55
	v_add_u32_e32 v132, s15, v131
	v_ashrrev_i32_e32 v133, 31, v132
	v_lshlrev_b64 v[132:133], 6, v[132:133]
	v_lshl_add_u64 v[132:133], s[10:11], 0, v[132:133]
	v_lshlrev_b32_e32 v0, 5, v144
	v_lshl_add_u64 v[132:133], v[132:133], 0, v[0:1]
	global_load_dwordx4 v[148:151], v[132:133], off offset:16
	global_load_dwordx4 v[140:143], v[132:133], off
	s_waitcnt vmcnt(2)
	ds_write_b128 v152, v[136:139]
	s_waitcnt vmcnt(0)
	v_add_f32_e32 v133, v150, v151
	v_add_f32_e32 v0, v140, v141
	v_add_f32_e32 v132, v142, v143
	v_add_f32_e32 v0, v0, v132
	v_add_f32_e32 v132, v148, v149
	v_add_f32_e32 v132, v132, v133
	v_add_f32_e32 v0, v0, v132
	v_lshlrev_b32_e32 v132, 2, v135
	v_xor_b32_e32 v132, 4, v132
	ds_bpermute_b32 v132, v132, v0
	s_and_saveexec_b64 s[4:5], vcc
	s_cbranch_execz .LBB0_922
	s_waitcnt lgkmcnt(0)
	v_add_f32_e32 v0, v0, v132
	v_mov_b32_e32 v132, 0x358637bd
	v_fmamk_f32 v0, v0, 0x3a800000, v132
	s_mov_b32 s6, 0x800000
	v_mul_f32_e32 v132, 0x4b800000, v0
	v_cmp_gt_f32_e32 vcc, s6, v0
	v_lshl_add_u32 v131, v131, 2, 0
	v_add_u32_e32 v131, 0x20000, v131
	v_cndmask_b32_e32 v0, v0, v132, vcc
	v_rsq_f32_e32 v0, v0
	s_nop 0
	v_mul_f32_e32 v132, 0x45800000, v0
	v_cndmask_b32_e32 v0, v0, v132, vcc
	ds_write_b32 v131, v0

.LBB0_1089:
	s_add_u32 s34, s84, 0x100
	s_addc_u32 s78, s85, 0
	s_mov_b32 s79, -2
	s_waitcnt lgkmcnt(0)
	s_add_i32 s90, 0, 0x10000
	v_add_u32_e32 v142, s90, v212
	v_add_u32_e32 v189, 0x10000, v212
	ds_read_b128 v[130:133], v142
	ds_read_b128 v[134:137], v142 offset:1024
	ds_read_b128 v[138:141], v142 offset:2048
	ds_read_b128 v[142:145], v142 offset:3072
	s_add_u32 s84, s16, 0x100
	s_addc_u32 s85, s17, 0
	s_cmp_eq_u32 s79, 40
	s_cselect_b32 s89, s5, s85
	s_cselect_b32 s88, s4, s84
	s_cselect_b32 s87, s7, s78
	s_cselect_b32 s86, s6, s34
	v_lshl_add_u64 v[178:179], s[16:17], 0, v[196:197]
	s_add_i32 m0, s39, 0xc000
	ds_read_b128 v[146:149], v213
	ds_read_b128 v[150:153], v213 offset:1024
	ds_read_b128 v[154:157], v213 offset:2048
	ds_read_b128 v[158:161], v213 offset:3072
	ds_read_b128 v[162:165], v213 offset:4096
	ds_read_b128 v[166:169], v213 offset:5120
	ds_read_b128 v[170:173], v213 offset:6144
	ds_read_b128 v[174:177], v213 offset:7168
	global_load_lds_dwordx4 v[178:179], off
	s_add_i32 m0, s39, 0xe000
	v_lshl_add_u64 v[178:179], s[16:17], 0, v[198:199]
	global_load_lds_dwordx4 v[178:179], off
	s_waitcnt lgkmcnt(8)
	s_barrier
	s_waitcnt lgkmcnt(0)
	v_mfma_f32_16x16x32_bf16 v[126:129], v[130:133], v[146:149], 0
	v_mfma_f32_16x16x32_bf16 v[122:125], v[138:141], v[146:149], 0
	v_mfma_f32_16x16x32_bf16 v[110:113], v[130:133], v[154:157], 0
	v_mfma_f32_16x16x32_bf16 v[106:109], v[138:141], v[154:157], 0
	v_mfma_f32_16x16x32_bf16 v[94:97], v[130:133], v[162:165], 0
	v_mfma_f32_16x16x32_bf16 v[90:93], v[138:141], v[162:165], 0
	v_mfma_f32_16x16x32_bf16 v[78:81], v[130:133], v[170:173], 0
	v_mfma_f32_16x16x32_bf16 v[74:77], v[138:141], v[170:173], 0
	v_mfma_f32_16x16x32_bf16 v[126:129], v[134:137], v[150:153], v[126:129]
	v_mfma_f32_16x16x32_bf16 v[122:125], v[142:145], v[150:153], v[122:125]
	v_mfma_f32_16x16x32_bf16 v[110:113], v[134:137], v[158:161], v[110:113]
	v_mfma_f32_16x16x32_bf16 v[106:109], v[142:145], v[158:161], v[106:109]
	v_mfma_f32_16x16x32_bf16 v[94:97], v[134:137], v[166:169], v[94:97]
	v_mfma_f32_16x16x32_bf16 v[90:93], v[142:145], v[166:169], v[90:93]
	v_mfma_f32_16x16x32_bf16 v[78:81], v[134:137], v[174:177], v[78:81]
	v_mfma_f32_16x16x32_bf16 v[74:77], v[142:145], v[174:177], v[74:77]
	s_barrier
	ds_read_b128 v[178:181], v189 offset:16384
	ds_read_b128 v[182:185], v189 offset:17408
	ds_read_b128 v[200:203], v189 offset:18432
	ds_read_b128 v[204:207], v189 offset:19456
	s_add_i32 m0, s38, 0x10000
	s_nop 0
	global_load_lds_dwordx4 v0, s[86:87]
	s_add_i32 m0, s38, 0x12000
	s_nop 0
	global_load_lds_dwordx4 v194, s[86:87]
	s_barrier
	s_waitcnt lgkmcnt(0)
	v_mfma_f32_16x16x32_bf16 v[118:121], v[178:181], v[146:149], 0
	v_mfma_f32_16x16x32_bf16 v[114:117], v[200:203], v[146:149], 0
	v_mfma_f32_16x16x32_bf16 v[102:105], v[178:181], v[154:157], 0
	v_mfma_f32_16x16x32_bf16 v[98:101], v[200:203], v[154:157], 0
	v_mfma_f32_16x16x32_bf16 v[86:89], v[178:181], v[162:165], 0
	v_mfma_f32_16x16x32_bf16 v[82:85], v[200:203], v[162:165], 0
	v_mfma_f32_16x16x32_bf16 v[70:73], v[178:181], v[170:173], 0
	v_mfma_f32_16x16x32_bf16 v[66:69], v[200:203], v[170:173], 0
	v_mfma_f32_16x16x32_bf16 v[118:121], v[182:185], v[150:153], v[118:121]
	v_mfma_f32_16x16x32_bf16 v[114:117], v[204:207], v[150:153], v[114:117]
	v_mfma_f32_16x16x32_bf16 v[102:105], v[182:185], v[158:161], v[102:105]
	v_mfma_f32_16x16x32_bf16 v[98:101], v[204:207], v[158:161], v[98:101]
	v_mfma_f32_16x16x32_bf16 v[86:89], v[182:185], v[166:169], v[86:89]
	v_mfma_f32_16x16x32_bf16 v[82:85], v[204:207], v[166:169], v[82:85]
	v_mfma_f32_16x16x32_bf16 v[70:73], v[182:185], v[174:177], v[70:73]
	v_mfma_f32_16x16x32_bf16 v[66:69], v[204:207], v[174:177], v[66:69]
	s_mov_b32 m0, s39
	s_mov_b64 s[100:101], s[88:89]
	s_barrier
	ds_read_b128 v[146:149], v213 offset:16384
	ds_read_b128 v[150:153], v213 offset:17408
	ds_read_b128 v[154:157], v213 offset:18432
	ds_read_b128 v[158:161], v213 offset:19456
	ds_read_b128 v[162:165], v213 offset:20480
	ds_read_b128 v[166:169], v213 offset:21504
	ds_read_b128 v[170:173], v213 offset:22528
	global_load_lds_dwordx4 v190, s[100:101]
	s_mov_b32 m0, s42
	ds_read_b128 v[174:177], v213 offset:23552
	global_load_lds_dwordx4 v192, s[100:101]
	s_waitcnt vmcnt(10)
	s_barrier
	s_waitcnt lgkmcnt(0)
	v_mfma_f32_16x16x32_bf16 v[62:65], v[130:133], v[146:149], 0
	v_mfma_f32_16x16x32_bf16 v[58:61], v[138:141], v[146:149], 0
	v_mfma_f32_16x16x32_bf16 v[46:49], v[130:133], v[154:157], 0
	v_mfma_f32_16x16x32_bf16 v[42:45], v[138:141], v[154:157], 0
	v_mfma_f32_16x16x32_bf16 v[30:33], v[130:133], v[162:165], 0
	v_mfma_f32_16x16x32_bf16 v[26:29], v[138:141], v[162:165], 0
	v_mfma_f32_16x16x32_bf16 v[14:17], v[130:133], v[170:173], 0
	v_mfma_f32_16x16x32_bf16 v[10:13], v[138:141], v[170:173], 0
	v_mfma_f32_16x16x32_bf16 v[62:65], v[134:137], v[150:153], v[62:65]
	v_mfma_f32_16x16x32_bf16 v[58:61], v[142:145], v[150:153], v[58:61]
	v_mfma_f32_16x16x32_bf16 v[46:49], v[134:137], v[158:161], v[46:49]
	v_mfma_f32_16x16x32_bf16 v[42:45], v[142:145], v[158:161], v[42:45]
	v_mfma_f32_16x16x32_bf16 v[30:33], v[134:137], v[166:169], v[30:33]
	v_mfma_f32_16x16x32_bf16 v[26:29], v[142:145], v[166:169], v[26:29]
	v_mfma_f32_16x16x32_bf16 v[14:17], v[134:137], v[174:177], v[14:17]
	v_mfma_f32_16x16x32_bf16 v[10:13], v[142:145], v[174:177], v[10:13]
	s_barrier
	s_add_u32 s16, s86, 0xb0000
	s_addc_u32 s17, s87, 0
	s_add_i32 m0, s38, 0x14000
	s_nop 0
	global_load_lds_dwordx4 v0, s[16:17]
	s_add_i32 m0, s38, 0x16000
	s_nop 0
	global_load_lds_dwordx4 v194, s[16:17]
	s_add_i32 s90, 0, 0x18000
	v_add_u32_e32 v142, s90, v212
	ds_read_b128 v[130:133], v142
	ds_read_b128 v[134:137], v142 offset:1024
	ds_read_b128 v[138:141], v142 offset:2048
	ds_read_b128 v[142:145], v142 offset:3072
	s_waitcnt vmcnt(6)
	s_barrier
	v_mfma_f32_16x16x32_bf16 v[54:57], v[178:181], v[146:149], 0
	v_mfma_f32_16x16x32_bf16 v[50:53], v[200:203], v[146:149], 0
	v_mfma_f32_16x16x32_bf16 v[38:41], v[178:181], v[154:157], 0
	v_mfma_f32_16x16x32_bf16 v[34:37], v[200:203], v[154:157], 0
	v_mfma_f32_16x16x32_bf16 v[22:25], v[178:181], v[162:165], 0
	v_mfma_f32_16x16x32_bf16 v[18:21], v[200:203], v[162:165], 0
	v_mfma_f32_16x16x32_bf16 v[6:9], v[178:181], v[170:173], 0
	v_mfma_f32_16x16x32_bf16 v[2:5], v[200:203], v[170:173], 0
	v_mfma_f32_16x16x32_bf16 v[54:57], v[182:185], v[150:153], v[54:57]
	v_mfma_f32_16x16x32_bf16 v[50:53], v[204:207], v[150:153], v[50:53]
	v_mfma_f32_16x16x32_bf16 v[38:41], v[182:185], v[158:161], v[38:41]
	v_mfma_f32_16x16x32_bf16 v[34:37], v[204:207], v[158:161], v[34:37]
	v_mfma_f32_16x16x32_bf16 v[22:25], v[182:185], v[166:169], v[22:25]
	v_mfma_f32_16x16x32_bf16 v[18:21], v[204:207], v[166:169], v[18:21]
	v_mfma_f32_16x16x32_bf16 v[6:9], v[182:185], v[174:177], v[6:9]
	v_mfma_f32_16x16x32_bf16 v[2:5], v[204:207], v[174:177], v[2:5]
	s_barrier
	s_add_u32 s16, s88, 0xb0000
	s_addc_u32 s17, s89, 0
	s_mov_b32 m0, s43
	ds_read_b128 v[146:149], v213 offset:32768
	ds_read_b128 v[150:153], v213 offset:33792
	ds_read_b128 v[154:157], v213 offset:34816
	ds_read_b128 v[158:161], v213 offset:35840
	ds_read_b128 v[162:165], v213 offset:36864
	ds_read_b128 v[166:169], v213 offset:37888
	ds_read_b128 v[170:173], v213 offset:38912
	global_load_lds_dwordx4 v190, s[16:17]
	s_mov_b32 m0, s44
	ds_read_b128 v[174:177], v213 offset:39936
	global_load_lds_dwordx4 v192, s[16:17]
	s_waitcnt lgkmcnt(8)
	s_barrier
	s_waitcnt lgkmcnt(0)
	v_mfma_f32_16x16x32_bf16 v[126:129], v[130:133], v[146:149], v[126:129]
	v_mfma_f32_16x16x32_bf16 v[122:125], v[138:141], v[146:149], v[122:125]
	v_mfma_f32_16x16x32_bf16 v[110:113], v[130:133], v[154:157], v[110:113]
	v_mfma_f32_16x16x32_bf16 v[106:109], v[138:141], v[154:157], v[106:109]
	v_mfma_f32_16x16x32_bf16 v[94:97], v[130:133], v[162:165], v[94:97]
	v_mfma_f32_16x16x32_bf16 v[90:93], v[138:141], v[162:165], v[90:93]
	v_mfma_f32_16x16x32_bf16 v[78:81], v[130:133], v[170:173], v[78:81]
	v_mfma_f32_16x16x32_bf16 v[74:77], v[138:141], v[170:173], v[74:77]
	v_mfma_f32_16x16x32_bf16 v[126:129], v[134:137], v[150:153], v[126:129]
	v_mfma_f32_16x16x32_bf16 v[122:125], v[142:145], v[150:153], v[122:125]
	v_mfma_f32_16x16x32_bf16 v[110:113], v[134:137], v[158:161], v[110:113]
	v_mfma_f32_16x16x32_bf16 v[106:109], v[142:145], v[158:161], v[106:109]
	v_mfma_f32_16x16x32_bf16 v[94:97], v[134:137], v[166:169], v[94:97]
	v_mfma_f32_16x16x32_bf16 v[90:93], v[142:145], v[166:169], v[90:93]
	v_mfma_f32_16x16x32_bf16 v[78:81], v[134:137], v[174:177], v[78:81]
	v_mfma_f32_16x16x32_bf16 v[74:77], v[142:145], v[174:177], v[74:77]
	s_barrier
	s_add_i32 s88, 0, 0x1c000
	v_add_u32_e32 v204, s88, v212
	s_add_i32 m0, s38, 0x18000
	ds_read_b128 v[178:181], v204
	ds_read_b128 v[182:185], v204 offset:1024
	ds_read_b128 v[200:203], v204 offset:2048
	ds_read_b128 v[204:207], v204 offset:3072
	s_add_u32 s98, s86, s40
	s_addc_u32 s99, s87, s41
	global_load_lds_dwordx4 v0, s[98:99]
	s_add_i32 m0, s38, 0x1a000
	s_nop 0
	global_load_lds_dwordx4 v194, s[98:99]
	s_barrier
	s_waitcnt lgkmcnt(0)
	v_mfma_f32_16x16x32_bf16 v[118:121], v[178:181], v[146:149], v[118:121]
	v_mfma_f32_16x16x32_bf16 v[114:117], v[200:203], v[146:149], v[114:117]
	v_mfma_f32_16x16x32_bf16 v[102:105], v[178:181], v[154:157], v[102:105]
	v_mfma_f32_16x16x32_bf16 v[98:101], v[200:203], v[154:157], v[98:101]
	v_mfma_f32_16x16x32_bf16 v[86:89], v[178:181], v[162:165], v[86:89]
	v_mfma_f32_16x16x32_bf16 v[82:85], v[200:203], v[162:165], v[82:85]
	v_mfma_f32_16x16x32_bf16 v[70:73], v[178:181], v[170:173], v[70:73]
	v_mfma_f32_16x16x32_bf16 v[66:69], v[200:203], v[170:173], v[66:69]
	v_mfma_f32_16x16x32_bf16 v[118:121], v[182:185], v[150:153], v[118:121]
	v_mfma_f32_16x16x32_bf16 v[114:117], v[204:207], v[150:153], v[114:117]
	v_mfma_f32_16x16x32_bf16 v[102:105], v[182:185], v[158:161], v[102:105]
	v_mfma_f32_16x16x32_bf16 v[98:101], v[204:207], v[158:161], v[98:101]
	v_mfma_f32_16x16x32_bf16 v[86:89], v[182:185], v[166:169], v[86:89]
	v_mfma_f32_16x16x32_bf16 v[82:85], v[204:207], v[166:169], v[82:85]
	v_mfma_f32_16x16x32_bf16 v[70:73], v[182:185], v[174:177], v[70:73]
	v_mfma_f32_16x16x32_bf16 v[66:69], v[204:207], v[174:177], v[66:69]
	s_mov_b32 m0, s60
	s_barrier
	ds_read_b128 v[146:149], v213 offset:49152
	ds_read_b128 v[150:153], v213 offset:50176
	ds_read_b128 v[154:157], v213 offset:51200
	ds_read_b128 v[158:161], v213 offset:52224
	ds_read_b128 v[162:165], v213 offset:53248
	ds_read_b128 v[166:169], v213 offset:54272
	ds_read_b128 v[170:173], v213 offset:55296
	ds_read_b128 v[174:177], v213 offset:56320
	s_add_u32 s98, s100, s40
	s_addc_u32 s99, s101, s41
	global_load_lds_dwordx4 v190, s[98:99]
	s_mov_b32 m0, s61
	s_nop 0
	global_load_lds_dwordx4 v192, s[98:99]
	s_waitcnt vmcnt(10)
	s_barrier
	s_waitcnt lgkmcnt(0)
	v_mfma_f32_16x16x32_bf16 v[62:65], v[130:133], v[146:149], v[62:65]
	v_mfma_f32_16x16x32_bf16 v[58:61], v[138:141], v[146:149], v[58:61]
	v_mfma_f32_16x16x32_bf16 v[46:49], v[130:133], v[154:157], v[46:49]
	v_mfma_f32_16x16x32_bf16 v[42:45], v[138:141], v[154:157], v[42:45]
	v_mfma_f32_16x16x32_bf16 v[30:33], v[130:133], v[162:165], v[30:33]
	v_mfma_f32_16x16x32_bf16 v[26:29], v[138:141], v[162:165], v[26:29]
	v_mfma_f32_16x16x32_bf16 v[14:17], v[130:133], v[170:173], v[14:17]
	v_mfma_f32_16x16x32_bf16 v[10:13], v[138:141], v[170:173], v[10:13]
	v_mfma_f32_16x16x32_bf16 v[62:65], v[134:137], v[150:153], v[62:65]
	v_mfma_f32_16x16x32_bf16 v[58:61], v[142:145], v[150:153], v[58:61]
	v_mfma_f32_16x16x32_bf16 v[46:49], v[134:137], v[158:161], v[46:49]
	v_mfma_f32_16x16x32_bf16 v[42:45], v[142:145], v[158:161], v[42:45]
	v_mfma_f32_16x16x32_bf16 v[30:33], v[134:137], v[166:169], v[30:33]
	v_mfma_f32_16x16x32_bf16 v[26:29], v[142:145], v[166:169], v[26:29]
	v_mfma_f32_16x16x32_bf16 v[14:17], v[134:137], v[174:177], v[14:17]
	v_mfma_f32_16x16x32_bf16 v[10:13], v[142:145], v[174:177], v[10:13]
	s_barrier
	s_add_u32 s16, s86, 0xb0080
	s_addc_u32 s17, s87, 0
	s_add_i32 m0, s38, 0x1c000
	s_nop 0
	global_load_lds_dwordx4 v0, s[16:17]
	s_add_i32 m0, s38, 0x1e000
	s_nop 0
	global_load_lds_dwordx4 v194, s[16:17]
	ds_read_b128 v[130:133], v189
	ds_read_b128 v[134:137], v189 offset:1024
	ds_read_b128 v[138:141], v189 offset:2048
	ds_read_b128 v[142:145], v189 offset:3072
	s_waitcnt vmcnt(6)
	s_barrier
	v_mfma_f32_16x16x32_bf16 v[54:57], v[178:181], v[146:149], v[54:57]
	v_mfma_f32_16x16x32_bf16 v[50:53], v[200:203], v[146:149], v[50:53]
	v_mfma_f32_16x16x32_bf16 v[38:41], v[178:181], v[154:157], v[38:41]
	v_mfma_f32_16x16x32_bf16 v[34:37], v[200:203], v[154:157], v[34:37]
	v_mfma_f32_16x16x32_bf16 v[22:25], v[178:181], v[162:165], v[22:25]
	v_mfma_f32_16x16x32_bf16 v[18:21], v[200:203], v[162:165], v[18:21]
	v_mfma_f32_16x16x32_bf16 v[6:9], v[178:181], v[170:173], v[6:9]
	v_mfma_f32_16x16x32_bf16 v[2:5], v[200:203], v[170:173], v[2:5]
	v_mfma_f32_16x16x32_bf16 v[54:57], v[182:185], v[150:153], v[54:57]
	v_mfma_f32_16x16x32_bf16 v[50:53], v[204:207], v[150:153], v[50:53]
	v_mfma_f32_16x16x32_bf16 v[38:41], v[182:185], v[158:161], v[38:41]
	v_mfma_f32_16x16x32_bf16 v[34:37], v[204:207], v[158:161], v[34:37]
	v_mfma_f32_16x16x32_bf16 v[22:25], v[182:185], v[166:169], v[22:25]
	v_mfma_f32_16x16x32_bf16 v[18:21], v[204:207], v[166:169], v[18:21]
	v_mfma_f32_16x16x32_bf16 v[6:9], v[182:185], v[174:177], v[6:9]
	v_mfma_f32_16x16x32_bf16 v[2:5], v[204:207], v[174:177], v[2:5]
	s_add_i32 s79, s79, 2
	s_add_u32 s34, s34, 0x100
	s_addc_u32 s78, s78, 0
	s_mov_b64 s[16:17], s[84:85]
	s_add_u32 s84, s16, 0x100
	s_addc_u32 s85, s17, 0
	s_cmp_eq_u32 s79, 40
	s_cselect_b32 s89, s5, s85
	s_cselect_b32 s88, s4, s84
	s_cselect_b32 s87, s7, s78
	s_cselect_b32 s86, s6, s34
	s_cmp_gt_u32 s79, 41
	s_barrier
.LBB0_1090:
	v_lshl_add_u64 v[178:179], s[16:17], 0, v[196:197]
	s_add_i32 m0, s39, 0xc000
	ds_read_b128 v[146:149], v213
	ds_read_b128 v[150:153], v213 offset:1024
	ds_read_b128 v[154:157], v213 offset:2048
	ds_read_b128 v[158:161], v213 offset:3072
	ds_read_b128 v[162:165], v213 offset:4096
	ds_read_b128 v[166:169], v213 offset:5120
	ds_read_b128 v[170:173], v213 offset:6144
	ds_read_b128 v[174:177], v213 offset:7168
	global_load_lds_dwordx4 v[178:179], off
	s_add_i32 m0, s39, 0xe000
	v_lshl_add_u64 v[178:179], s[16:17], 0, v[198:199]
	global_load_lds_dwordx4 v[178:179], off
	s_waitcnt lgkmcnt(8)
	s_barrier
	s_waitcnt lgkmcnt(0)
	v_mfma_f32_16x16x32_bf16 v[126:129], v[130:133], v[146:149], v[126:129]
	v_mfma_f32_16x16x32_bf16 v[122:125], v[138:141], v[146:149], v[122:125]
	v_mfma_f32_16x16x32_bf16 v[110:113], v[130:133], v[154:157], v[110:113]
	v_mfma_f32_16x16x32_bf16 v[106:109], v[138:141], v[154:157], v[106:109]
	v_mfma_f32_16x16x32_bf16 v[94:97], v[130:133], v[162:165], v[94:97]
	v_mfma_f32_16x16x32_bf16 v[90:93], v[138:141], v[162:165], v[90:93]
	v_mfma_f32_16x16x32_bf16 v[78:81], v[130:133], v[170:173], v[78:81]
	v_mfma_f32_16x16x32_bf16 v[74:77], v[138:141], v[170:173], v[74:77]
	v_mfma_f32_16x16x32_bf16 v[126:129], v[134:137], v[150:153], v[126:129]
	v_mfma_f32_16x16x32_bf16 v[122:125], v[142:145], v[150:153], v[122:125]
	v_mfma_f32_16x16x32_bf16 v[110:113], v[134:137], v[158:161], v[110:113]
	v_mfma_f32_16x16x32_bf16 v[106:109], v[142:145], v[158:161], v[106:109]
	v_mfma_f32_16x16x32_bf16 v[94:97], v[134:137], v[166:169], v[94:97]
	v_mfma_f32_16x16x32_bf16 v[90:93], v[142:145], v[166:169], v[90:93]
	v_mfma_f32_16x16x32_bf16 v[78:81], v[134:137], v[174:177], v[78:81]
	v_mfma_f32_16x16x32_bf16 v[74:77], v[142:145], v[174:177], v[74:77]
	s_barrier
	ds_read_b128 v[178:181], v189 offset:16384
	ds_read_b128 v[182:185], v189 offset:17408
	ds_read_b128 v[200:203], v189 offset:18432
	ds_read_b128 v[204:207], v189 offset:19456
	s_add_i32 m0, s38, 0x10000
	s_nop 0
	global_load_lds_dwordx4 v0, s[86:87]
	s_add_i32 m0, s38, 0x12000
	s_nop 0
	global_load_lds_dwordx4 v194, s[86:87]
	s_barrier
	s_waitcnt lgkmcnt(0)
	v_mfma_f32_16x16x32_bf16 v[118:121], v[178:181], v[146:149], v[118:121]
	v_mfma_f32_16x16x32_bf16 v[114:117], v[200:203], v[146:149], v[114:117]
	v_mfma_f32_16x16x32_bf16 v[102:105], v[178:181], v[154:157], v[102:105]
	v_mfma_f32_16x16x32_bf16 v[98:101], v[200:203], v[154:157], v[98:101]
	v_mfma_f32_16x16x32_bf16 v[86:89], v[178:181], v[162:165], v[86:89]
	v_mfma_f32_16x16x32_bf16 v[82:85], v[200:203], v[162:165], v[82:85]
	v_mfma_f32_16x16x32_bf16 v[70:73], v[178:181], v[170:173], v[70:73]
	v_mfma_f32_16x16x32_bf16 v[66:69], v[200:203], v[170:173], v[66:69]
	v_mfma_f32_16x16x32_bf16 v[118:121], v[182:185], v[150:153], v[118:121]
	v_mfma_f32_16x16x32_bf16 v[114:117], v[204:207], v[150:153], v[114:117]
	v_mfma_f32_16x16x32_bf16 v[102:105], v[182:185], v[158:161], v[102:105]
	v_mfma_f32_16x16x32_bf16 v[98:101], v[204:207], v[158:161], v[98:101]
	v_mfma_f32_16x16x32_bf16 v[86:89], v[182:185], v[166:169], v[86:89]
	v_mfma_f32_16x16x32_bf16 v[82:85], v[204:207], v[166:169], v[82:85]
	v_mfma_f32_16x16x32_bf16 v[70:73], v[182:185], v[174:177], v[70:73]
	v_mfma_f32_16x16x32_bf16 v[66:69], v[204:207], v[174:177], v[66:69]
	s_mov_b32 m0, s39
	s_mov_b64 s[100:101], s[88:89]
	s_barrier
	ds_read_b128 v[146:149], v213 offset:16384
	ds_read_b128 v[150:153], v213 offset:17408
	ds_read_b128 v[154:157], v213 offset:18432
	ds_read_b128 v[158:161], v213 offset:19456
	ds_read_b128 v[162:165], v213 offset:20480
	ds_read_b128 v[166:169], v213 offset:21504
	ds_read_b128 v[170:173], v213 offset:22528
	global_load_lds_dwordx4 v190, s[100:101]
	s_mov_b32 m0, s42
	ds_read_b128 v[174:177], v213 offset:23552
	global_load_lds_dwordx4 v192, s[100:101]
	s_waitcnt vmcnt(10)
	s_barrier
	s_waitcnt lgkmcnt(0)
	v_mfma_f32_16x16x32_bf16 v[62:65], v[130:133], v[146:149], v[62:65]
	v_mfma_f32_16x16x32_bf16 v[58:61], v[138:141], v[146:149], v[58:61]
	v_mfma_f32_16x16x32_bf16 v[46:49], v[130:133], v[154:157], v[46:49]
	v_mfma_f32_16x16x32_bf16 v[42:45], v[138:141], v[154:157], v[42:45]
	v_mfma_f32_16x16x32_bf16 v[30:33], v[130:133], v[162:165], v[30:33]
	v_mfma_f32_16x16x32_bf16 v[26:29], v[138:141], v[162:165], v[26:29]
	v_mfma_f32_16x16x32_bf16 v[14:17], v[130:133], v[170:173], v[14:17]
	v_mfma_f32_16x16x32_bf16 v[10:13], v[138:141], v[170:173], v[10:13]
	v_mfma_f32_16x16x32_bf16 v[62:65], v[134:137], v[150:153], v[62:65]
	v_mfma_f32_16x16x32_bf16 v[58:61], v[142:145], v[150:153], v[58:61]
	v_mfma_f32_16x16x32_bf16 v[46:49], v[134:137], v[158:161], v[46:49]
	v_mfma_f32_16x16x32_bf16 v[42:45], v[142:145], v[158:161], v[42:45]
	v_mfma_f32_16x16x32_bf16 v[30:33], v[134:137], v[166:169], v[30:33]
	v_mfma_f32_16x16x32_bf16 v[26:29], v[142:145], v[166:169], v[26:29]
	v_mfma_f32_16x16x32_bf16 v[14:17], v[134:137], v[174:177], v[14:17]
	v_mfma_f32_16x16x32_bf16 v[10:13], v[142:145], v[174:177], v[10:13]
	s_barrier
	s_add_u32 s16, s86, 0xb0000
	s_addc_u32 s17, s87, 0
	s_add_i32 m0, s38, 0x14000
	s_nop 0
	global_load_lds_dwordx4 v0, s[16:17]
	s_add_i32 m0, s38, 0x16000
	s_nop 0
	global_load_lds_dwordx4 v194, s[16:17]
	s_add_i32 s90, 0, 0x18000
	v_add_u32_e32 v142, s90, v212
	ds_read_b128 v[130:133], v142
	ds_read_b128 v[134:137], v142 offset:1024
	ds_read_b128 v[138:141], v142 offset:2048
	ds_read_b128 v[142:145], v142 offset:3072
	s_waitcnt vmcnt(6)
	s_barrier
	v_mfma_f32_16x16x32_bf16 v[54:57], v[178:181], v[146:149], v[54:57]
	v_mfma_f32_16x16x32_bf16 v[50:53], v[200:203], v[146:149], v[50:53]
	v_mfma_f32_16x16x32_bf16 v[38:41], v[178:181], v[154:157], v[38:41]
	v_mfma_f32_16x16x32_bf16 v[34:37], v[200:203], v[154:157], v[34:37]
	v_mfma_f32_16x16x32_bf16 v[22:25], v[178:181], v[162:165], v[22:25]
	v_mfma_f32_16x16x32_bf16 v[18:21], v[200:203], v[162:165], v[18:21]
	v_mfma_f32_16x16x32_bf16 v[6:9], v[178:181], v[170:173], v[6:9]
	v_mfma_f32_16x16x32_bf16 v[2:5], v[200:203], v[170:173], v[2:5]
	v_mfma_f32_16x16x32_bf16 v[54:57], v[182:185], v[150:153], v[54:57]
	v_mfma_f32_16x16x32_bf16 v[50:53], v[204:207], v[150:153], v[50:53]
	v_mfma_f32_16x16x32_bf16 v[38:41], v[182:185], v[158:161], v[38:41]
	v_mfma_f32_16x16x32_bf16 v[34:37], v[204:207], v[158:161], v[34:37]
	v_mfma_f32_16x16x32_bf16 v[22:25], v[182:185], v[166:169], v[22:25]
	v_mfma_f32_16x16x32_bf16 v[18:21], v[204:207], v[166:169], v[18:21]
	v_mfma_f32_16x16x32_bf16 v[6:9], v[182:185], v[174:177], v[6:9]
	v_mfma_f32_16x16x32_bf16 v[2:5], v[204:207], v[174:177], v[2:5]
	s_barrier
	s_add_u32 s16, s88, 0xb0000
	s_addc_u32 s17, s89, 0
	s_mov_b32 m0, s43
	ds_read_b128 v[146:149], v213 offset:32768
	ds_read_b128 v[150:153], v213 offset:33792
	ds_read_b128 v[154:157], v213 offset:34816
	ds_read_b128 v[158:161], v213 offset:35840
	ds_read_b128 v[162:165], v213 offset:36864
	ds_read_b128 v[166:169], v213 offset:37888
	ds_read_b128 v[170:173], v213 offset:38912
	global_load_lds_dwordx4 v190, s[16:17]
	s_mov_b32 m0, s44
	ds_read_b128 v[174:177], v213 offset:39936
	global_load_lds_dwordx4 v192, s[16:17]
	s_waitcnt lgkmcnt(8)
	s_barrier
	s_waitcnt lgkmcnt(0)
	v_mfma_f32_16x16x32_bf16 v[126:129], v[130:133], v[146:149], v[126:129]
	v_mfma_f32_16x16x32_bf16 v[122:125], v[138:141], v[146:149], v[122:125]
	v_mfma_f32_16x16x32_bf16 v[110:113], v[130:133], v[154:157], v[110:113]
	v_mfma_f32_16x16x32_bf16 v[106:109], v[138:141], v[154:157], v[106:109]
	v_mfma_f32_16x16x32_bf16 v[94:97], v[130:133], v[162:165], v[94:97]
	v_mfma_f32_16x16x32_bf16 v[90:93], v[138:141], v[162:165], v[90:93]
	v_mfma_f32_16x16x32_bf16 v[78:81], v[130:133], v[170:173], v[78:81]
	v_mfma_f32_16x16x32_bf16 v[74:77], v[138:141], v[170:173], v[74:77]
	v_mfma_f32_16x16x32_bf16 v[126:129], v[134:137], v[150:153], v[126:129]
	v_mfma_f32_16x16x32_bf16 v[122:125], v[142:145], v[150:153], v[122:125]
	v_mfma_f32_16x16x32_bf16 v[110:113], v[134:137], v[158:161], v[110:113]
	v_mfma_f32_16x16x32_bf16 v[106:109], v[142:145], v[158:161], v[106:109]
	v_mfma_f32_16x16x32_bf16 v[94:97], v[134:137], v[166:169], v[94:97]
	v_mfma_f32_16x16x32_bf16 v[90:93], v[142:145], v[166:169], v[90:93]
	v_mfma_f32_16x16x32_bf16 v[78:81], v[134:137], v[174:177], v[78:81]
	v_mfma_f32_16x16x32_bf16 v[74:77], v[142:145], v[174:177], v[74:77]
	s_barrier
	s_add_i32 s88, 0, 0x1c000
	v_add_u32_e32 v204, s88, v212
	s_add_i32 m0, s38, 0x18000
	ds_read_b128 v[178:181], v204
	ds_read_b128 v[182:185], v204 offset:1024
	ds_read_b128 v[200:203], v204 offset:2048
	ds_read_b128 v[204:207], v204 offset:3072
	s_add_u32 s98, s86, s40
	s_addc_u32 s99, s87, s41
	global_load_lds_dwordx4 v0, s[98:99]
	s_add_i32 m0, s38, 0x1a000
	s_nop 0
	global_load_lds_dwordx4 v194, s[98:99]
	s_barrier
	s_waitcnt lgkmcnt(0)
	v_mfma_f32_16x16x32_bf16 v[118:121], v[178:181], v[146:149], v[118:121]
	v_mfma_f32_16x16x32_bf16 v[114:117], v[200:203], v[146:149], v[114:117]
	v_mfma_f32_16x16x32_bf16 v[102:105], v[178:181], v[154:157], v[102:105]
	v_mfma_f32_16x16x32_bf16 v[98:101], v[200:203], v[154:157], v[98:101]
	v_mfma_f32_16x16x32_bf16 v[86:89], v[178:181], v[162:165], v[86:89]
	v_mfma_f32_16x16x32_bf16 v[82:85], v[200:203], v[162:165], v[82:85]
	v_mfma_f32_16x16x32_bf16 v[70:73], v[178:181], v[170:173], v[70:73]
	v_mfma_f32_16x16x32_bf16 v[66:69], v[200:203], v[170:173], v[66:69]
	v_mfma_f32_16x16x32_bf16 v[118:121], v[182:185], v[150:153], v[118:121]
	v_mfma_f32_16x16x32_bf16 v[114:117], v[204:207], v[150:153], v[114:117]
	v_mfma_f32_16x16x32_bf16 v[102:105], v[182:185], v[158:161], v[102:105]
	v_mfma_f32_16x16x32_bf16 v[98:101], v[204:207], v[158:161], v[98:101]
	v_mfma_f32_16x16x32_bf16 v[86:89], v[182:185], v[166:169], v[86:89]
	v_mfma_f32_16x16x32_bf16 v[82:85], v[204:207], v[166:169], v[82:85]
	v_mfma_f32_16x16x32_bf16 v[70:73], v[182:185], v[174:177], v[70:73]
	v_mfma_f32_16x16x32_bf16 v[66:69], v[204:207], v[174:177], v[66:69]
	s_mov_b32 m0, s60
	s_barrier
	ds_read_b128 v[146:149], v213 offset:49152
	ds_read_b128 v[150:153], v213 offset:50176
	ds_read_b128 v[154:157], v213 offset:51200
	ds_read_b128 v[158:161], v213 offset:52224
	ds_read_b128 v[162:165], v213 offset:53248
	ds_read_b128 v[166:169], v213 offset:54272
	ds_read_b128 v[170:173], v213 offset:55296
	ds_read_b128 v[174:177], v213 offset:56320
	s_add_u32 s98, s100, s40
	s_addc_u32 s99, s101, s41
	global_load_lds_dwordx4 v190, s[98:99]
	s_mov_b32 m0, s61
	s_nop 0
	global_load_lds_dwordx4 v192, s[98:99]
	s_waitcnt vmcnt(10)
	s_barrier
	s_waitcnt lgkmcnt(0)
	v_mfma_f32_16x16x32_bf16 v[62:65], v[130:133], v[146:149], v[62:65]
	v_mfma_f32_16x16x32_bf16 v[58:61], v[138:141], v[146:149], v[58:61]
	v_mfma_f32_16x16x32_bf16 v[46:49], v[130:133], v[154:157], v[46:49]
	v_mfma_f32_16x16x32_bf16 v[42:45], v[138:141], v[154:157], v[42:45]
	v_mfma_f32_16x16x32_bf16 v[30:33], v[130:133], v[162:165], v[30:33]
	v_mfma_f32_16x16x32_bf16 v[26:29], v[138:141], v[162:165], v[26:29]
	v_mfma_f32_16x16x32_bf16 v[14:17], v[130:133], v[170:173], v[14:17]
	v_mfma_f32_16x16x32_bf16 v[10:13], v[138:141], v[170:173], v[10:13]
	v_mfma_f32_16x16x32_bf16 v[62:65], v[134:137], v[150:153], v[62:65]
	v_mfma_f32_16x16x32_bf16 v[58:61], v[142:145], v[150:153], v[58:61]
	v_mfma_f32_16x16x32_bf16 v[46:49], v[134:137], v[158:161], v[46:49]
	v_mfma_f32_16x16x32_bf16 v[42:45], v[142:145], v[158:161], v[42:45]
	v_mfma_f32_16x16x32_bf16 v[30:33], v[134:137], v[166:169], v[30:33]
	v_mfma_f32_16x16x32_bf16 v[26:29], v[142:145], v[166:169], v[26:29]
	v_mfma_f32_16x16x32_bf16 v[14:17], v[134:137], v[174:177], v[14:17]
	v_mfma_f32_16x16x32_bf16 v[10:13], v[142:145], v[174:177], v[10:13]
	s_barrier
	s_add_u32 s16, s86, 0xb0080
	s_addc_u32 s17, s87, 0
	s_add_i32 m0, s38, 0x1c000
	s_nop 0
	global_load_lds_dwordx4 v0, s[16:17]
	s_add_i32 m0, s38, 0x1e000
	s_nop 0
	global_load_lds_dwordx4 v194, s[16:17]
	ds_read_b128 v[130:133], v189
	ds_read_b128 v[134:137], v189 offset:1024
	ds_read_b128 v[138:141], v189 offset:2048
	ds_read_b128 v[142:145], v189 offset:3072
	s_waitcnt vmcnt(6)
	s_barrier
	v_mfma_f32_16x16x32_bf16 v[54:57], v[178:181], v[146:149], v[54:57]
	v_mfma_f32_16x16x32_bf16 v[50:53], v[200:203], v[146:149], v[50:53]
	v_mfma_f32_16x16x32_bf16 v[38:41], v[178:181], v[154:157], v[38:41]
	v_mfma_f32_16x16x32_bf16 v[34:37], v[200:203], v[154:157], v[34:37]
	v_mfma_f32_16x16x32_bf16 v[22:25], v[178:181], v[162:165], v[22:25]
	v_mfma_f32_16x16x32_bf16 v[18:21], v[200:203], v[162:165], v[18:21]
	v_mfma_f32_16x16x32_bf16 v[6:9], v[178:181], v[170:173], v[6:9]
	v_mfma_f32_16x16x32_bf16 v[2:5], v[200:203], v[170:173], v[2:5]
	v_mfma_f32_16x16x32_bf16 v[54:57], v[182:185], v[150:153], v[54:57]
	v_mfma_f32_16x16x32_bf16 v[50:53], v[204:207], v[150:153], v[50:53]
	v_mfma_f32_16x16x32_bf16 v[38:41], v[182:185], v[158:161], v[38:41]
	v_mfma_f32_16x16x32_bf16 v[34:37], v[204:207], v[158:161], v[34:37]
	v_mfma_f32_16x16x32_bf16 v[22:25], v[182:185], v[166:169], v[22:25]
	v_mfma_f32_16x16x32_bf16 v[18:21], v[204:207], v[166:169], v[18:21]
	v_mfma_f32_16x16x32_bf16 v[6:9], v[182:185], v[174:177], v[6:9]
	v_mfma_f32_16x16x32_bf16 v[2:5], v[204:207], v[174:177], v[2:5]
	s_add_i32 s79, s79, 2
	s_add_u32 s34, s34, 0x100
	s_addc_u32 s78, s78, 0
	s_mov_b64 s[16:17], s[84:85]
	s_add_u32 s84, s16, 0x100
	s_addc_u32 s85, s17, 0
	s_cmp_eq_u32 s79, 40
	s_cselect_b32 s89, s5, s85
	s_cselect_b32 s88, s4, s84
	s_cselect_b32 s87, s7, s78
	s_cselect_b32 s86, s6, s34
	s_cmp_gt_u32 s79, 41
	s_barrier
	s_cbranch_scc0 .LBB0_1090
	s_waitcnt lgkmcnt(0)
	s_lshl_b32 s16, s23, 8
	v_mov_b32_e32 v186, v252
	s_add_i32 s16, s16, s47
	s_nop 0
	v_and_or_b32 v202, v186, 15, s16
	s_lshl_b32 s16, s22, 8
	s_or_b32 s16, s16, s55
	v_lshrrev_b32_e32 v130, 1, v186
	v_and_or_b32 v200, v130, 24, s16
	v_ashrrev_i32_e32 v201, 31, v200
	v_ashrrev_i32_e32 v203, 31, v202
	v_lshl_add_u64 v[204:205], v[200:201], 2, s[12:13]
	v_lshlrev_b64 v[130:131], 12, v[202:203]
	v_lshl_add_u64 v[130:131], v[204:205], 0, v[130:131]
	global_load_dwordx4 v[216:219], v[130:131], off offset:16
	global_load_dwordx4 v[220:223], v[130:131], off
	global_load_dwordx4 v[178:181], v[130:131], off offset:528
	global_load_dwordx4 v[182:185], v[130:131], off offset:512
	v_or_b32_e32 v210, 16, v202
	v_ashrrev_i32_e32 v211, 31, v210
	v_lshlrev_b64 v[130:131], 12, v[210:211]
	v_or_b32_e32 v208, 32, v202
	v_lshl_add_u64 v[130:131], v[204:205], 0, v[130:131]
	v_ashrrev_i32_e32 v209, 31, v208
	global_load_dwordx4 v[170:173], v[130:131], off offset:16
	global_load_dwordx4 v[174:177], v[130:131], off
	global_load_dwordx4 v[162:165], v[130:131], off offset:528
	global_load_dwordx4 v[166:169], v[130:131], off offset:512
	v_lshlrev_b64 v[130:131], 12, v[208:209]
	v_or_b32_e32 v206, 48, v202
	v_lshl_add_u64 v[130:131], v[204:205], 0, v[130:131]
	v_ashrrev_i32_e32 v207, 31, v206
	global_load_dwordx4 v[154:157], v[130:131], off offset:16
	global_load_dwordx4 v[158:161], v[130:131], off
	global_load_dwordx4 v[138:141], v[130:131], off offset:528
	global_load_dwordx4 v[142:145], v[130:131], off offset:512
	v_lshlrev_b64 v[130:131], 12, v[206:207]
	v_lshl_add_u64 v[134:135], v[204:205], 0, v[130:131]
	global_load_dwordx4 v[146:149], v[134:135], off offset:16
	global_load_dwordx4 v[150:153], v[134:135], off
	global_load_dwordx4 v[130:133], v[134:135], off offset:528
	s_nop 0
	global_load_dwordx4 v[134:137], v[134:135], off offset:512
	v_and_b32_e32 v186, 63, v186
	v_lshlrev_b32_e32 v187, 2, v186
	v_xor_b32_e32 v215, 64, v187
	v_xor_b32_e32 v214, 0x80, v187
	v_cmp_gt_u32_e32 vcc, 16, v186
	v_lshlrev_b64 v[186:187], 10, v[202:203]
	v_lshl_add_u64 v[186:187], v[186:187], 0, v[200:201]
	s_lshl_b32 s16, s22, 2
	s_ashr_i32 s17, s16, 31
	s_waitcnt vmcnt(0)
	v_pk_add_f32 v[124:125], v[124:125], v[218:219]
	v_pk_add_f32 v[128:129], v[128:129], v[222:223]
	v_pk_add_f32 v[126:127], v[126:127], v[220:221]
	v_pk_mul_f32 v[218:219], v[128:129], v[128:129]
	v_pk_mul_f32 v[220:221], v[126:127], v[126:127]
	v_pk_add_f32 v[122:123], v[122:123], v[216:217]
	v_lshl_add_u64 v[216:217], v[186:187], 2, s[14:15]
	v_add_f32_e32 v220, v220, v221
	v_add_f32_e32 v218, v218, v219
	global_store_dwordx4 v[216:217], v[126:129], off
	global_store_dwordx4 v[216:217], v[122:125], off offset:16
	v_add_f32_e32 v222, v220, v218
	v_pk_mul_f32 v[220:221], v[122:123], v[122:123]
	v_cvt_pk_bf16_f32 v126, v126, v127
	v_cvt_pk_bf16_f32 v127, v128, v129
	v_cvt_pk_bf16_f32 v128, v122, v123
	v_cvt_pk_bf16_f32 v129, v124, v125
	v_lshl_add_u64 v[122:123], v[186:187], 1, s[80:81]
	v_pk_add_f32 v[120:121], v[120:121], v[184:185]
	v_pk_add_f32 v[118:119], v[118:119], v[182:183]
	v_pk_mul_f32 v[218:219], v[124:125], v[124:125]
	global_store_dwordx4 v[122:123], v[126:129], off
	v_pk_mul_f32 v[124:125], v[120:121], v[120:121]
	v_pk_add_f32 v[116:117], v[116:117], v[180:181]
	v_pk_mul_f32 v[126:127], v[118:119], v[118:119]
	v_pk_add_f32 v[114:115], v[114:115], v[178:179]
	v_add_f32_e32 v126, v126, v127
	v_add_f32_e32 v124, v124, v125
	v_add_f32_e32 v128, v126, v124
	v_pk_mul_f32 v[124:125], v[116:117], v[116:117]
	v_pk_mul_f32 v[126:127], v[114:115], v[114:115]
	v_add_f32_e32 v220, v220, v221
	v_add_f32_e32 v218, v218, v219
	v_add_f32_e32 v126, v126, v127
	v_add_f32_e32 v124, v124, v125
	v_add_f32_e32 v218, v220, v218
	v_add_f32_e32 v124, v126, v124
	v_add_f32_e32 v218, v222, v218
	v_add_f32_e32 v124, v128, v124
	v_add_f32_e32 v124, v218, v124
	global_store_dwordx4 v[216:217], v[118:121], off offset:512
	global_store_dwordx4 v[216:217], v[114:117], off offset:528
	s_nop 0
	v_cvt_pk_bf16_f32 v118, v118, v119
	v_cvt_pk_bf16_f32 v119, v120, v121
	v_cvt_pk_bf16_f32 v120, v114, v115
	ds_bpermute_b32 v114, v215, v124
	v_cvt_pk_bf16_f32 v121, v116, v117
	global_store_dwordx4 v[122:123], v[118:121], off offset:256
	s_waitcnt lgkmcnt(0)
	v_add_f32_e32 v114, v124, v114
	ds_bpermute_b32 v115, v214, v114
	s_and_saveexec_b64 s[22:23], vcc
	s_cbranch_execz .LBB0_1093
	v_lshlrev_b64 v[116:117], 6, v[202:203]
	v_lshl_add_u64 v[116:117], s[82:83], 0, v[116:117]
	v_lshl_add_u64 v[116:117], s[16:17], 2, v[116:117]
	s_lshl_b32 s34, s45, 2
	v_lshl_add_u64 v[116:117], v[116:117], 0, s[34:35]
	s_waitcnt lgkmcnt(0)
	v_add_f32_e32 v114, v114, v115
	global_store_dword v[116:117], v114, off

.LBB0_1208:
	s_ashr_i32 s13, s12, 31
	v_cmp_lt_i64_e32 vcc, s[14:15], v[230:231]
	s_lshl_b64 s[14:15], s[12:13], 19
	s_add_u32 s14, s80, s14
	s_addc_u32 s15, s81, s15
	s_and_b64 s[16:17], vcc, exec
	s_cselect_b32 s13, s15, s89
	s_cselect_b32 s22, s14, s88
	s_ashr_i32 s7, s6, 31
	s_lshl_b64 s[16:17], s[6:7], 19
	s_add_u32 s16, s36, s16
	s_addc_u32 s17, s37, s17
	s_and_b64 s[92:93], vcc, exec
	s_cselect_b32 s7, s17, s91
	s_cselect_b32 s23, s16, s90
	s_add_u32 s88, s88, 0x40080
	s_addc_u32 s89, s89, 0
	s_add_u32 s34, s90, 0x100
	s_addc_u32 s79, s91, 0
	s_mov_b32 s85, -2
	s_waitcnt lgkmcnt(0)
	s_add_i32 s94, 0, 0x10000
	v_add_u32_e32 v0, s94, v170
	v_add_u32_e32 v189, 0x10000, v170
	ds_read_b128 v[130:133], v0
	ds_read_b128 v[134:137], v0 offset:1024
	ds_read_b128 v[138:141], v0 offset:2048
	ds_read_b128 v[142:145], v0 offset:3072
	s_add_u32 s87, s88, 0xfffc0080
	s_addc_u32 s90, s89, -1
	s_cmp_eq_u32 s85, 12
	s_cselect_b32 s93, s13, s90
	s_cselect_b32 s92, s22, s87
	s_cselect_b32 s91, s7, s79
	s_cselect_b32 s90, s23, s34
	s_waitcnt lgkmcnt(0)
	s_add_i32 m0, s39, 0xc000
	ds_read_b128 v[158:161], v171
	ds_read_b128 v[162:165], v171 offset:1024
	ds_read_b128 v[166:169], v171 offset:2048
	ds_read_b128 v[172:175], v171 offset:3072
	ds_read_b128 v[176:179], v171 offset:4096
	ds_read_b128 v[180:183], v171 offset:5120
	ds_read_b128 v[184:187], v171 offset:6144
	global_load_lds_dwordx4 v154, s[88:89]
	s_add_i32 m0, s39, 0xe000
	ds_read_b128 v[190:193], v171 offset:7168
	global_load_lds_dwordx4 v156, s[88:89]
	s_waitcnt lgkmcnt(8)
	s_barrier
	s_waitcnt lgkmcnt(0)
	v_mfma_f32_16x16x32_bf16 v[126:129], v[130:133], v[158:161], 0
	v_mfma_f32_16x16x32_bf16 v[122:125], v[138:141], v[158:161], 0
	v_mfma_f32_16x16x32_bf16 v[110:113], v[130:133], v[166:169], 0
	v_mfma_f32_16x16x32_bf16 v[106:109], v[138:141], v[166:169], 0
	v_mfma_f32_16x16x32_bf16 v[94:97], v[130:133], v[176:179], 0
	v_mfma_f32_16x16x32_bf16 v[90:93], v[138:141], v[176:179], 0
	v_mfma_f32_16x16x32_bf16 v[78:81], v[130:133], v[184:187], 0
	v_mfma_f32_16x16x32_bf16 v[74:77], v[138:141], v[184:187], 0
	v_mfma_f32_16x16x32_bf16 v[126:129], v[134:137], v[162:165], v[126:129]
	v_mfma_f32_16x16x32_bf16 v[122:125], v[142:145], v[162:165], v[122:125]
	v_mfma_f32_16x16x32_bf16 v[110:113], v[134:137], v[172:175], v[110:113]
	v_mfma_f32_16x16x32_bf16 v[106:109], v[142:145], v[172:175], v[106:109]
	v_mfma_f32_16x16x32_bf16 v[94:97], v[134:137], v[180:183], v[94:97]
	v_mfma_f32_16x16x32_bf16 v[90:93], v[142:145], v[180:183], v[90:93]
	v_mfma_f32_16x16x32_bf16 v[78:81], v[134:137], v[190:193], v[78:81]
	v_mfma_f32_16x16x32_bf16 v[74:77], v[142:145], v[190:193], v[74:77]
	s_barrier
	s_add_i32 m0, s38, 0x10000
	ds_read_b128 v[194:197], v189 offset:16384
	ds_read_b128 v[198:201], v189 offset:17408
	ds_read_b128 v[202:205], v189 offset:18432
	global_load_lds_dwordx4 v148, s[90:91]
	s_add_i32 m0, s38, 0x12000
	ds_read_b128 v[206:209], v189 offset:19456
	global_load_lds_dwordx4 v152, s[90:91]
	s_barrier
	s_waitcnt lgkmcnt(0)
	v_mfma_f32_16x16x32_bf16 v[118:121], v[194:197], v[158:161], 0
	v_mfma_f32_16x16x32_bf16 v[114:117], v[202:205], v[158:161], 0
	v_mfma_f32_16x16x32_bf16 v[102:105], v[194:197], v[166:169], 0
	v_mfma_f32_16x16x32_bf16 v[98:101], v[202:205], v[166:169], 0
	v_mfma_f32_16x16x32_bf16 v[86:89], v[194:197], v[176:179], 0
	v_mfma_f32_16x16x32_bf16 v[82:85], v[202:205], v[176:179], 0
	v_mfma_f32_16x16x32_bf16 v[70:73], v[194:197], v[184:187], 0
	v_mfma_f32_16x16x32_bf16 v[66:69], v[202:205], v[184:187], 0
	v_mfma_f32_16x16x32_bf16 v[118:121], v[198:201], v[162:165], v[118:121]
	v_mfma_f32_16x16x32_bf16 v[114:117], v[206:209], v[162:165], v[114:117]
	v_mfma_f32_16x16x32_bf16 v[102:105], v[198:201], v[172:175], v[102:105]
	v_mfma_f32_16x16x32_bf16 v[98:101], v[206:209], v[172:175], v[98:101]
	v_mfma_f32_16x16x32_bf16 v[86:89], v[198:201], v[180:183], v[86:89]
	v_mfma_f32_16x16x32_bf16 v[82:85], v[206:209], v[180:183], v[82:85]
	v_mfma_f32_16x16x32_bf16 v[70:73], v[198:201], v[190:193], v[70:73]
	v_mfma_f32_16x16x32_bf16 v[66:69], v[206:209], v[190:193], v[66:69]
	s_mov_b32 m0, s39
	s_mov_b64 s[100:101], s[92:93]
	s_barrier
	ds_read_b128 v[158:161], v171 offset:16384
	ds_read_b128 v[162:165], v171 offset:17408
	ds_read_b128 v[166:169], v171 offset:18432
	ds_read_b128 v[172:175], v171 offset:19456
	ds_read_b128 v[176:179], v171 offset:20480
	ds_read_b128 v[180:183], v171 offset:21504
	ds_read_b128 v[184:187], v171 offset:22528
	global_load_lds_dwordx4 v146, s[100:101]
	s_mov_b32 m0, s42
	ds_read_b128 v[190:193], v171 offset:23552
	global_load_lds_dwordx4 v150, s[100:101]
	s_waitcnt vmcnt(10)
	s_barrier
	s_waitcnt lgkmcnt(0)
	v_mfma_f32_16x16x32_bf16 v[62:65], v[130:133], v[158:161], 0
	v_mfma_f32_16x16x32_bf16 v[58:61], v[138:141], v[158:161], 0
	v_mfma_f32_16x16x32_bf16 v[46:49], v[130:133], v[166:169], 0
	v_mfma_f32_16x16x32_bf16 v[42:45], v[138:141], v[166:169], 0
	v_mfma_f32_16x16x32_bf16 v[30:33], v[130:133], v[176:179], 0
	v_mfma_f32_16x16x32_bf16 v[26:29], v[138:141], v[176:179], 0
	v_mfma_f32_16x16x32_bf16 v[14:17], v[130:133], v[184:187], 0
	v_mfma_f32_16x16x32_bf16 v[10:13], v[138:141], v[184:187], 0
	v_mfma_f32_16x16x32_bf16 v[62:65], v[134:137], v[162:165], v[62:65]
	v_mfma_f32_16x16x32_bf16 v[58:61], v[142:145], v[162:165], v[58:61]
	v_mfma_f32_16x16x32_bf16 v[46:49], v[134:137], v[172:175], v[46:49]
	v_mfma_f32_16x16x32_bf16 v[42:45], v[142:145], v[172:175], v[42:45]
	v_mfma_f32_16x16x32_bf16 v[30:33], v[134:137], v[180:183], v[30:33]
	v_mfma_f32_16x16x32_bf16 v[26:29], v[142:145], v[180:183], v[26:29]
	v_mfma_f32_16x16x32_bf16 v[14:17], v[134:137], v[190:193], v[14:17]
	v_mfma_f32_16x16x32_bf16 v[10:13], v[142:145], v[190:193], v[10:13]
	s_barrier
	s_add_u32 s94, s90, 0x40000
	s_addc_u32 s95, s91, 0
	s_add_i32 m0, s38, 0x14000
	s_nop 0
	global_load_lds_dwordx4 v148, s[94:95]
	s_add_i32 m0, s38, 0x16000
	s_nop 0
	global_load_lds_dwordx4 v152, s[94:95]
	ds_read_b128 v[130:133], v189 offset:32768
	ds_read_b128 v[134:137], v189 offset:33792
	ds_read_b128 v[138:141], v189 offset:34816
	ds_read_b128 v[142:145], v189 offset:35840
	s_waitcnt vmcnt(6)
	s_barrier
	v_mfma_f32_16x16x32_bf16 v[54:57], v[194:197], v[158:161], 0
	v_mfma_f32_16x16x32_bf16 v[50:53], v[202:205], v[158:161], 0
	v_mfma_f32_16x16x32_bf16 v[38:41], v[194:197], v[166:169], 0
	v_mfma_f32_16x16x32_bf16 v[34:37], v[202:205], v[166:169], 0
	v_mfma_f32_16x16x32_bf16 v[22:25], v[194:197], v[176:179], 0
	v_mfma_f32_16x16x32_bf16 v[18:21], v[202:205], v[176:179], 0
	v_mfma_f32_16x16x32_bf16 v[6:9], v[194:197], v[184:187], 0
	v_mfma_f32_16x16x32_bf16 v[2:5], v[202:205], v[184:187], 0
	v_mfma_f32_16x16x32_bf16 v[54:57], v[198:201], v[162:165], v[54:57]
	v_mfma_f32_16x16x32_bf16 v[50:53], v[206:209], v[162:165], v[50:53]
	v_mfma_f32_16x16x32_bf16 v[38:41], v[198:201], v[172:175], v[38:41]
	v_mfma_f32_16x16x32_bf16 v[34:37], v[206:209], v[172:175], v[34:37]
	v_mfma_f32_16x16x32_bf16 v[22:25], v[198:201], v[180:183], v[22:25]
	v_mfma_f32_16x16x32_bf16 v[18:21], v[206:209], v[180:183], v[18:21]
	v_mfma_f32_16x16x32_bf16 v[6:9], v[198:201], v[190:193], v[6:9]
	v_mfma_f32_16x16x32_bf16 v[2:5], v[206:209], v[190:193], v[2:5]
	s_barrier
	s_add_u32 s92, s92, 0x40000
	s_addc_u32 s93, s93, 0
	s_mov_b32 m0, s43
	ds_read_b128 v[158:161], v171 offset:32768
	ds_read_b128 v[162:165], v171 offset:33792
	ds_read_b128 v[166:169], v171 offset:34816
	ds_read_b128 v[172:175], v171 offset:35840
	ds_read_b128 v[176:179], v171 offset:36864
	ds_read_b128 v[180:183], v171 offset:37888
	ds_read_b128 v[184:187], v171 offset:38912
	global_load_lds_dwordx4 v146, s[92:93]
	s_mov_b32 m0, s44
	ds_read_b128 v[190:193], v171 offset:39936
	global_load_lds_dwordx4 v150, s[92:93]
	s_waitcnt lgkmcnt(8)
	s_barrier
	s_waitcnt lgkmcnt(0)
	v_mfma_f32_16x16x32_bf16 v[126:129], v[130:133], v[158:161], v[126:129]
	v_mfma_f32_16x16x32_bf16 v[122:125], v[138:141], v[158:161], v[122:125]
	v_mfma_f32_16x16x32_bf16 v[110:113], v[130:133], v[166:169], v[110:113]
	v_mfma_f32_16x16x32_bf16 v[106:109], v[138:141], v[166:169], v[106:109]
	v_mfma_f32_16x16x32_bf16 v[94:97], v[130:133], v[176:179], v[94:97]
	v_mfma_f32_16x16x32_bf16 v[90:93], v[138:141], v[176:179], v[90:93]
	v_mfma_f32_16x16x32_bf16 v[78:81], v[130:133], v[184:187], v[78:81]
	v_mfma_f32_16x16x32_bf16 v[74:77], v[138:141], v[184:187], v[74:77]
	v_mfma_f32_16x16x32_bf16 v[126:129], v[134:137], v[162:165], v[126:129]
	v_mfma_f32_16x16x32_bf16 v[122:125], v[142:145], v[162:165], v[122:125]
	v_mfma_f32_16x16x32_bf16 v[110:113], v[134:137], v[172:175], v[110:113]
	v_mfma_f32_16x16x32_bf16 v[106:109], v[142:145], v[172:175], v[106:109]
	v_mfma_f32_16x16x32_bf16 v[94:97], v[134:137], v[180:183], v[94:97]
	v_mfma_f32_16x16x32_bf16 v[90:93], v[142:145], v[180:183], v[90:93]
	v_mfma_f32_16x16x32_bf16 v[78:81], v[134:137], v[190:193], v[78:81]
	v_mfma_f32_16x16x32_bf16 v[74:77], v[142:145], v[190:193], v[74:77]
	s_barrier
	s_add_i32 m0, s38, 0x18000
	ds_read_b128 v[194:197], v189 offset:49152
	ds_read_b128 v[198:201], v189 offset:50176
	ds_read_b128 v[202:205], v189 offset:51200
	ds_read_b128 v[206:209], v189 offset:52224
	s_add_u32 s98, s90, s40
	s_addc_u32 s99, s91, s41
	global_load_lds_dwordx4 v148, s[98:99]
	s_add_i32 m0, s38, 0x1a000
	s_nop 0
	global_load_lds_dwordx4 v152, s[98:99]
	s_barrier
	s_waitcnt lgkmcnt(0)
	v_mfma_f32_16x16x32_bf16 v[118:121], v[194:197], v[158:161], v[118:121]
	v_mfma_f32_16x16x32_bf16 v[114:117], v[202:205], v[158:161], v[114:117]
	v_mfma_f32_16x16x32_bf16 v[102:105], v[194:197], v[166:169], v[102:105]
	v_mfma_f32_16x16x32_bf16 v[98:101], v[202:205], v[166:169], v[98:101]
	v_mfma_f32_16x16x32_bf16 v[86:89], v[194:197], v[176:179], v[86:89]
	v_mfma_f32_16x16x32_bf16 v[82:85], v[202:205], v[176:179], v[82:85]
	v_mfma_f32_16x16x32_bf16 v[70:73], v[194:197], v[184:187], v[70:73]
	v_mfma_f32_16x16x32_bf16 v[66:69], v[202:205], v[184:187], v[66:69]
	v_mfma_f32_16x16x32_bf16 v[118:121], v[198:201], v[162:165], v[118:121]
	v_mfma_f32_16x16x32_bf16 v[114:117], v[206:209], v[162:165], v[114:117]
	v_mfma_f32_16x16x32_bf16 v[102:105], v[198:201], v[172:175], v[102:105]
	v_mfma_f32_16x16x32_bf16 v[98:101], v[206:209], v[172:175], v[98:101]
	v_mfma_f32_16x16x32_bf16 v[86:89], v[198:201], v[180:183], v[86:89]
	v_mfma_f32_16x16x32_bf16 v[82:85], v[206:209], v[180:183], v[82:85]
	v_mfma_f32_16x16x32_bf16 v[70:73], v[198:201], v[190:193], v[70:73]
	v_mfma_f32_16x16x32_bf16 v[66:69], v[206:209], v[190:193], v[66:69]
	s_mov_b32 m0, s60
	s_barrier
	ds_read_b128 v[158:161], v171 offset:49152
	ds_read_b128 v[162:165], v171 offset:50176
	ds_read_b128 v[166:169], v171 offset:51200
	ds_read_b128 v[172:175], v171 offset:52224
	ds_read_b128 v[176:179], v171 offset:53248
	ds_read_b128 v[180:183], v171 offset:54272
	ds_read_b128 v[184:187], v171 offset:55296
	ds_read_b128 v[190:193], v171 offset:56320
	s_add_u32 s98, s100, s40
	s_addc_u32 s99, s101, s41
	global_load_lds_dwordx4 v146, s[98:99]
	s_mov_b32 m0, s61
	s_nop 0
	global_load_lds_dwordx4 v150, s[98:99]
	s_waitcnt vmcnt(10)
	s_barrier
	s_waitcnt lgkmcnt(0)
	v_mfma_f32_16x16x32_bf16 v[62:65], v[130:133], v[158:161], v[62:65]
	v_mfma_f32_16x16x32_bf16 v[58:61], v[138:141], v[158:161], v[58:61]
	v_mfma_f32_16x16x32_bf16 v[46:49], v[130:133], v[166:169], v[46:49]
	v_mfma_f32_16x16x32_bf16 v[42:45], v[138:141], v[166:169], v[42:45]
	v_mfma_f32_16x16x32_bf16 v[30:33], v[130:133], v[176:179], v[30:33]
	v_mfma_f32_16x16x32_bf16 v[26:29], v[138:141], v[176:179], v[26:29]
	v_mfma_f32_16x16x32_bf16 v[14:17], v[130:133], v[184:187], v[14:17]
	v_mfma_f32_16x16x32_bf16 v[10:13], v[138:141], v[184:187], v[10:13]
	v_mfma_f32_16x16x32_bf16 v[62:65], v[134:137], v[162:165], v[62:65]
	v_mfma_f32_16x16x32_bf16 v[58:61], v[142:145], v[162:165], v[58:61]
	v_mfma_f32_16x16x32_bf16 v[46:49], v[134:137], v[172:175], v[46:49]
	v_mfma_f32_16x16x32_bf16 v[42:45], v[142:145], v[172:175], v[42:45]
	v_mfma_f32_16x16x32_bf16 v[30:33], v[134:137], v[180:183], v[30:33]
	v_mfma_f32_16x16x32_bf16 v[26:29], v[142:145], v[180:183], v[26:29]
	v_mfma_f32_16x16x32_bf16 v[14:17], v[134:137], v[190:193], v[14:17]
	v_mfma_f32_16x16x32_bf16 v[10:13], v[142:145], v[190:193], v[10:13]
	s_barrier
	s_add_u32 s90, s90, 0x40080
	s_addc_u32 s91, s91, 0
	s_add_i32 m0, s38, 0x1c000
	s_nop 0
	global_load_lds_dwordx4 v148, s[90:91]
	s_add_i32 m0, s38, 0x1e000
	s_nop 0
	global_load_lds_dwordx4 v152, s[90:91]
	ds_read_b128 v[130:133], v189
	ds_read_b128 v[134:137], v189 offset:1024
	ds_read_b128 v[138:141], v189 offset:2048
	ds_read_b128 v[142:145], v189 offset:3072
	s_waitcnt vmcnt(6)
	s_barrier
	v_mfma_f32_16x16x32_bf16 v[54:57], v[194:197], v[158:161], v[54:57]
	v_mfma_f32_16x16x32_bf16 v[50:53], v[202:205], v[158:161], v[50:53]
	v_mfma_f32_16x16x32_bf16 v[38:41], v[194:197], v[166:169], v[38:41]
	v_mfma_f32_16x16x32_bf16 v[34:37], v[202:205], v[166:169], v[34:37]
	v_mfma_f32_16x16x32_bf16 v[22:25], v[194:197], v[176:179], v[22:25]
	v_mfma_f32_16x16x32_bf16 v[18:21], v[202:205], v[176:179], v[18:21]
	v_mfma_f32_16x16x32_bf16 v[6:9], v[194:197], v[184:187], v[6:9]
	v_mfma_f32_16x16x32_bf16 v[2:5], v[202:205], v[184:187], v[2:5]
	v_mfma_f32_16x16x32_bf16 v[54:57], v[198:201], v[162:165], v[54:57]
	v_mfma_f32_16x16x32_bf16 v[50:53], v[206:209], v[162:165], v[50:53]
	v_mfma_f32_16x16x32_bf16 v[38:41], v[198:201], v[172:175], v[38:41]
	v_mfma_f32_16x16x32_bf16 v[34:37], v[206:209], v[172:175], v[34:37]
	v_mfma_f32_16x16x32_bf16 v[22:25], v[198:201], v[180:183], v[22:25]
	v_mfma_f32_16x16x32_bf16 v[18:21], v[206:209], v[180:183], v[18:21]
	v_mfma_f32_16x16x32_bf16 v[6:9], v[198:201], v[190:193], v[6:9]
	v_mfma_f32_16x16x32_bf16 v[2:5], v[206:209], v[190:193], v[2:5]
	s_add_i32 s85, s85, 2
	s_add_u32 s88, s88, 0x100
	s_addc_u32 s89, s89, 0
	s_add_u32 s34, s34, 0x100
	s_addc_u32 s79, s79, 0
	s_add_u32 s87, s88, 0xfffc0080
	s_addc_u32 s90, s89, -1
	s_cmp_eq_u32 s85, 12
	s_cselect_b32 s93, s13, s90
	s_cselect_b32 s92, s22, s87
	s_cselect_b32 s91, s7, s79
	s_cselect_b32 s90, s23, s34
	s_cmp_gt_u32 s85, 13
	s_barrier
.LBB0_1209:
	s_waitcnt lgkmcnt(0)
	s_add_i32 m0, s39, 0xc000
	ds_read_b128 v[158:161], v171
	ds_read_b128 v[162:165], v171 offset:1024
	ds_read_b128 v[166:169], v171 offset:2048
	ds_read_b128 v[172:175], v171 offset:3072
	ds_read_b128 v[176:179], v171 offset:4096
	ds_read_b128 v[180:183], v171 offset:5120
	ds_read_b128 v[184:187], v171 offset:6144
	global_load_lds_dwordx4 v154, s[88:89]
	s_add_i32 m0, s39, 0xe000
	ds_read_b128 v[190:193], v171 offset:7168
	global_load_lds_dwordx4 v156, s[88:89]
	s_waitcnt lgkmcnt(8)
	s_barrier
	s_waitcnt lgkmcnt(0)
	v_mfma_f32_16x16x32_bf16 v[126:129], v[130:133], v[158:161], v[126:129]
	v_mfma_f32_16x16x32_bf16 v[122:125], v[138:141], v[158:161], v[122:125]
	v_mfma_f32_16x16x32_bf16 v[110:113], v[130:133], v[166:169], v[110:113]
	v_mfma_f32_16x16x32_bf16 v[106:109], v[138:141], v[166:169], v[106:109]
	v_mfma_f32_16x16x32_bf16 v[94:97], v[130:133], v[176:179], v[94:97]
	v_mfma_f32_16x16x32_bf16 v[90:93], v[138:141], v[176:179], v[90:93]
	v_mfma_f32_16x16x32_bf16 v[78:81], v[130:133], v[184:187], v[78:81]
	v_mfma_f32_16x16x32_bf16 v[74:77], v[138:141], v[184:187], v[74:77]
	v_mfma_f32_16x16x32_bf16 v[126:129], v[134:137], v[162:165], v[126:129]
	v_mfma_f32_16x16x32_bf16 v[122:125], v[142:145], v[162:165], v[122:125]
	v_mfma_f32_16x16x32_bf16 v[110:113], v[134:137], v[172:175], v[110:113]
	v_mfma_f32_16x16x32_bf16 v[106:109], v[142:145], v[172:175], v[106:109]
	v_mfma_f32_16x16x32_bf16 v[94:97], v[134:137], v[180:183], v[94:97]
	v_mfma_f32_16x16x32_bf16 v[90:93], v[142:145], v[180:183], v[90:93]
	v_mfma_f32_16x16x32_bf16 v[78:81], v[134:137], v[190:193], v[78:81]
	v_mfma_f32_16x16x32_bf16 v[74:77], v[142:145], v[190:193], v[74:77]
	s_barrier
	s_add_i32 m0, s38, 0x10000
	ds_read_b128 v[194:197], v189 offset:16384
	ds_read_b128 v[198:201], v189 offset:17408
	ds_read_b128 v[202:205], v189 offset:18432
	global_load_lds_dwordx4 v148, s[90:91]
	s_add_i32 m0, s38, 0x12000
	ds_read_b128 v[206:209], v189 offset:19456
	global_load_lds_dwordx4 v152, s[90:91]
	s_barrier
	s_waitcnt lgkmcnt(0)
	v_mfma_f32_16x16x32_bf16 v[118:121], v[194:197], v[158:161], v[118:121]
	v_mfma_f32_16x16x32_bf16 v[114:117], v[202:205], v[158:161], v[114:117]
	v_mfma_f32_16x16x32_bf16 v[102:105], v[194:197], v[166:169], v[102:105]
	v_mfma_f32_16x16x32_bf16 v[98:101], v[202:205], v[166:169], v[98:101]
	v_mfma_f32_16x16x32_bf16 v[86:89], v[194:197], v[176:179], v[86:89]
	v_mfma_f32_16x16x32_bf16 v[82:85], v[202:205], v[176:179], v[82:85]
	v_mfma_f32_16x16x32_bf16 v[70:73], v[194:197], v[184:187], v[70:73]
	v_mfma_f32_16x16x32_bf16 v[66:69], v[202:205], v[184:187], v[66:69]
	v_mfma_f32_16x16x32_bf16 v[118:121], v[198:201], v[162:165], v[118:121]
	v_mfma_f32_16x16x32_bf16 v[114:117], v[206:209], v[162:165], v[114:117]
	v_mfma_f32_16x16x32_bf16 v[102:105], v[198:201], v[172:175], v[102:105]
	v_mfma_f32_16x16x32_bf16 v[98:101], v[206:209], v[172:175], v[98:101]
	v_mfma_f32_16x16x32_bf16 v[86:89], v[198:201], v[180:183], v[86:89]
	v_mfma_f32_16x16x32_bf16 v[82:85], v[206:209], v[180:183], v[82:85]
	v_mfma_f32_16x16x32_bf16 v[70:73], v[198:201], v[190:193], v[70:73]
	v_mfma_f32_16x16x32_bf16 v[66:69], v[206:209], v[190:193], v[66:69]
	s_mov_b32 m0, s39
	s_mov_b64 s[100:101], s[92:93]
	s_barrier
	ds_read_b128 v[158:161], v171 offset:16384
	ds_read_b128 v[162:165], v171 offset:17408
	ds_read_b128 v[166:169], v171 offset:18432
	ds_read_b128 v[172:175], v171 offset:19456
	ds_read_b128 v[176:179], v171 offset:20480
	ds_read_b128 v[180:183], v171 offset:21504
	ds_read_b128 v[184:187], v171 offset:22528
	global_load_lds_dwordx4 v146, s[100:101]
	s_mov_b32 m0, s42
	ds_read_b128 v[190:193], v171 offset:23552
	global_load_lds_dwordx4 v150, s[100:101]
	s_waitcnt vmcnt(10)
	s_barrier
	s_waitcnt lgkmcnt(0)
	v_mfma_f32_16x16x32_bf16 v[62:65], v[130:133], v[158:161], v[62:65]
	v_mfma_f32_16x16x32_bf16 v[58:61], v[138:141], v[158:161], v[58:61]
	v_mfma_f32_16x16x32_bf16 v[46:49], v[130:133], v[166:169], v[46:49]
	v_mfma_f32_16x16x32_bf16 v[42:45], v[138:141], v[166:169], v[42:45]
	v_mfma_f32_16x16x32_bf16 v[30:33], v[130:133], v[176:179], v[30:33]
	v_mfma_f32_16x16x32_bf16 v[26:29], v[138:141], v[176:179], v[26:29]
	v_mfma_f32_16x16x32_bf16 v[14:17], v[130:133], v[184:187], v[14:17]
	v_mfma_f32_16x16x32_bf16 v[10:13], v[138:141], v[184:187], v[10:13]
	v_mfma_f32_16x16x32_bf16 v[62:65], v[134:137], v[162:165], v[62:65]
	v_mfma_f32_16x16x32_bf16 v[58:61], v[142:145], v[162:165], v[58:61]
	v_mfma_f32_16x16x32_bf16 v[46:49], v[134:137], v[172:175], v[46:49]
	v_mfma_f32_16x16x32_bf16 v[42:45], v[142:145], v[172:175], v[42:45]
	v_mfma_f32_16x16x32_bf16 v[30:33], v[134:137], v[180:183], v[30:33]
	v_mfma_f32_16x16x32_bf16 v[26:29], v[142:145], v[180:183], v[26:29]
	v_mfma_f32_16x16x32_bf16 v[14:17], v[134:137], v[190:193], v[14:17]
	v_mfma_f32_16x16x32_bf16 v[10:13], v[142:145], v[190:193], v[10:13]
	s_barrier
	s_add_u32 s94, s90, 0x40000
	s_addc_u32 s95, s91, 0
	s_add_i32 m0, s38, 0x14000
	s_nop 0
	global_load_lds_dwordx4 v148, s[94:95]
	s_add_i32 m0, s38, 0x16000
	s_nop 0
	global_load_lds_dwordx4 v152, s[94:95]
	ds_read_b128 v[130:133], v189 offset:32768
	ds_read_b128 v[134:137], v189 offset:33792
	ds_read_b128 v[138:141], v189 offset:34816
	ds_read_b128 v[142:145], v189 offset:35840
	s_waitcnt vmcnt(6)
	s_barrier
	v_mfma_f32_16x16x32_bf16 v[54:57], v[194:197], v[158:161], v[54:57]
	v_mfma_f32_16x16x32_bf16 v[50:53], v[202:205], v[158:161], v[50:53]
	v_mfma_f32_16x16x32_bf16 v[38:41], v[194:197], v[166:169], v[38:41]
	v_mfma_f32_16x16x32_bf16 v[34:37], v[202:205], v[166:169], v[34:37]
	v_mfma_f32_16x16x32_bf16 v[22:25], v[194:197], v[176:179], v[22:25]
	v_mfma_f32_16x16x32_bf16 v[18:21], v[202:205], v[176:179], v[18:21]
	v_mfma_f32_16x16x32_bf16 v[6:9], v[194:197], v[184:187], v[6:9]
	v_mfma_f32_16x16x32_bf16 v[2:5], v[202:205], v[184:187], v[2:5]
	v_mfma_f32_16x16x32_bf16 v[54:57], v[198:201], v[162:165], v[54:57]
	v_mfma_f32_16x16x32_bf16 v[50:53], v[206:209], v[162:165], v[50:53]
	v_mfma_f32_16x16x32_bf16 v[38:41], v[198:201], v[172:175], v[38:41]
	v_mfma_f32_16x16x32_bf16 v[34:37], v[206:209], v[172:175], v[34:37]
	v_mfma_f32_16x16x32_bf16 v[22:25], v[198:201], v[180:183], v[22:25]
	v_mfma_f32_16x16x32_bf16 v[18:21], v[206:209], v[180:183], v[18:21]
	v_mfma_f32_16x16x32_bf16 v[6:9], v[198:201], v[190:193], v[6:9]
	v_mfma_f32_16x16x32_bf16 v[2:5], v[206:209], v[190:193], v[2:5]
	s_barrier
	s_add_u32 s92, s92, 0x40000
	s_addc_u32 s93, s93, 0
	s_mov_b32 m0, s43
	ds_read_b128 v[158:161], v171 offset:32768
	ds_read_b128 v[162:165], v171 offset:33792
	ds_read_b128 v[166:169], v171 offset:34816
	ds_read_b128 v[172:175], v171 offset:35840
	ds_read_b128 v[176:179], v171 offset:36864
	ds_read_b128 v[180:183], v171 offset:37888
	ds_read_b128 v[184:187], v171 offset:38912
	global_load_lds_dwordx4 v146, s[92:93]
	s_mov_b32 m0, s44
	ds_read_b128 v[190:193], v171 offset:39936
	global_load_lds_dwordx4 v150, s[92:93]
	s_waitcnt lgkmcnt(8)
	s_barrier
	s_waitcnt lgkmcnt(0)
	v_mfma_f32_16x16x32_bf16 v[126:129], v[130:133], v[158:161], v[126:129]
	v_mfma_f32_16x16x32_bf16 v[122:125], v[138:141], v[158:161], v[122:125]
	v_mfma_f32_16x16x32_bf16 v[110:113], v[130:133], v[166:169], v[110:113]
	v_mfma_f32_16x16x32_bf16 v[106:109], v[138:141], v[166:169], v[106:109]
	v_mfma_f32_16x16x32_bf16 v[94:97], v[130:133], v[176:179], v[94:97]
	v_mfma_f32_16x16x32_bf16 v[90:93], v[138:141], v[176:179], v[90:93]
	v_mfma_f32_16x16x32_bf16 v[78:81], v[130:133], v[184:187], v[78:81]
	v_mfma_f32_16x16x32_bf16 v[74:77], v[138:141], v[184:187], v[74:77]
	v_mfma_f32_16x16x32_bf16 v[126:129], v[134:137], v[162:165], v[126:129]
	v_mfma_f32_16x16x32_bf16 v[122:125], v[142:145], v[162:165], v[122:125]
	v_mfma_f32_16x16x32_bf16 v[110:113], v[134:137], v[172:175], v[110:113]
	v_mfma_f32_16x16x32_bf16 v[106:109], v[142:145], v[172:175], v[106:109]
	v_mfma_f32_16x16x32_bf16 v[94:97], v[134:137], v[180:183], v[94:97]
	v_mfma_f32_16x16x32_bf16 v[90:93], v[142:145], v[180:183], v[90:93]
	v_mfma_f32_16x16x32_bf16 v[78:81], v[134:137], v[190:193], v[78:81]
	v_mfma_f32_16x16x32_bf16 v[74:77], v[142:145], v[190:193], v[74:77]
	s_barrier
	s_add_i32 m0, s38, 0x18000
	ds_read_b128 v[194:197], v189 offset:49152
	ds_read_b128 v[198:201], v189 offset:50176
	ds_read_b128 v[202:205], v189 offset:51200
	ds_read_b128 v[206:209], v189 offset:52224
	s_add_u32 s98, s90, s40
	s_addc_u32 s99, s91, s41
	global_load_lds_dwordx4 v148, s[98:99]
	s_add_i32 m0, s38, 0x1a000
	s_nop 0
	global_load_lds_dwordx4 v152, s[98:99]
	s_barrier
	s_waitcnt lgkmcnt(0)
	v_mfma_f32_16x16x32_bf16 v[118:121], v[194:197], v[158:161], v[118:121]
	v_mfma_f32_16x16x32_bf16 v[114:117], v[202:205], v[158:161], v[114:117]
	v_mfma_f32_16x16x32_bf16 v[102:105], v[194:197], v[166:169], v[102:105]
	v_mfma_f32_16x16x32_bf16 v[98:101], v[202:205], v[166:169], v[98:101]
	v_mfma_f32_16x16x32_bf16 v[86:89], v[194:197], v[176:179], v[86:89]
	v_mfma_f32_16x16x32_bf16 v[82:85], v[202:205], v[176:179], v[82:85]
	v_mfma_f32_16x16x32_bf16 v[70:73], v[194:197], v[184:187], v[70:73]
	v_mfma_f32_16x16x32_bf16 v[66:69], v[202:205], v[184:187], v[66:69]
	v_mfma_f32_16x16x32_bf16 v[118:121], v[198:201], v[162:165], v[118:121]
	v_mfma_f32_16x16x32_bf16 v[114:117], v[206:209], v[162:165], v[114:117]
	v_mfma_f32_16x16x32_bf16 v[102:105], v[198:201], v[172:175], v[102:105]
	v_mfma_f32_16x16x32_bf16 v[98:101], v[206:209], v[172:175], v[98:101]
	v_mfma_f32_16x16x32_bf16 v[86:89], v[198:201], v[180:183], v[86:89]
	v_mfma_f32_16x16x32_bf16 v[82:85], v[206:209], v[180:183], v[82:85]
	v_mfma_f32_16x16x32_bf16 v[70:73], v[198:201], v[190:193], v[70:73]
	v_mfma_f32_16x16x32_bf16 v[66:69], v[206:209], v[190:193], v[66:69]
	s_mov_b32 m0, s60
	s_barrier
	ds_read_b128 v[158:161], v171 offset:49152
	ds_read_b128 v[162:165], v171 offset:50176
	ds_read_b128 v[166:169], v171 offset:51200
	ds_read_b128 v[172:175], v171 offset:52224
	ds_read_b128 v[176:179], v171 offset:53248
	ds_read_b128 v[180:183], v171 offset:54272
	ds_read_b128 v[184:187], v171 offset:55296
	ds_read_b128 v[190:193], v171 offset:56320
	s_add_u32 s98, s100, s40
	s_addc_u32 s99, s101, s41
	global_load_lds_dwordx4 v146, s[98:99]
	s_mov_b32 m0, s61
	s_nop 0
	global_load_lds_dwordx4 v150, s[98:99]
	s_waitcnt vmcnt(10)
	s_barrier
	s_waitcnt lgkmcnt(0)
	v_mfma_f32_16x16x32_bf16 v[62:65], v[130:133], v[158:161], v[62:65]
	v_mfma_f32_16x16x32_bf16 v[58:61], v[138:141], v[158:161], v[58:61]
	v_mfma_f32_16x16x32_bf16 v[46:49], v[130:133], v[166:169], v[46:49]
	v_mfma_f32_16x16x32_bf16 v[42:45], v[138:141], v[166:169], v[42:45]
	v_mfma_f32_16x16x32_bf16 v[30:33], v[130:133], v[176:179], v[30:33]
	v_mfma_f32_16x16x32_bf16 v[26:29], v[138:141], v[176:179], v[26:29]
	v_mfma_f32_16x16x32_bf16 v[14:17], v[130:133], v[184:187], v[14:17]
	v_mfma_f32_16x16x32_bf16 v[10:13], v[138:141], v[184:187], v[10:13]
	v_mfma_f32_16x16x32_bf16 v[62:65], v[134:137], v[162:165], v[62:65]
	v_mfma_f32_16x16x32_bf16 v[58:61], v[142:145], v[162:165], v[58:61]
	v_mfma_f32_16x16x32_bf16 v[46:49], v[134:137], v[172:175], v[46:49]
	v_mfma_f32_16x16x32_bf16 v[42:45], v[142:145], v[172:175], v[42:45]
	v_mfma_f32_16x16x32_bf16 v[30:33], v[134:137], v[180:183], v[30:33]
	v_mfma_f32_16x16x32_bf16 v[26:29], v[142:145], v[180:183], v[26:29]
	v_mfma_f32_16x16x32_bf16 v[14:17], v[134:137], v[190:193], v[14:17]
	v_mfma_f32_16x16x32_bf16 v[10:13], v[142:145], v[190:193], v[10:13]
	s_barrier
	s_add_u32 s90, s90, 0x40080
	s_addc_u32 s91, s91, 0
	s_add_i32 m0, s38, 0x1c000
	s_nop 0
	global_load_lds_dwordx4 v148, s[90:91]
	s_add_i32 m0, s38, 0x1e000
	s_nop 0
	global_load_lds_dwordx4 v152, s[90:91]
	ds_read_b128 v[130:133], v189
	ds_read_b128 v[134:137], v189 offset:1024
	ds_read_b128 v[138:141], v189 offset:2048
	ds_read_b128 v[142:145], v189 offset:3072
	s_waitcnt vmcnt(6)
	s_barrier
	v_mfma_f32_16x16x32_bf16 v[54:57], v[194:197], v[158:161], v[54:57]
	v_mfma_f32_16x16x32_bf16 v[50:53], v[202:205], v[158:161], v[50:53]
	v_mfma_f32_16x16x32_bf16 v[38:41], v[194:197], v[166:169], v[38:41]
	v_mfma_f32_16x16x32_bf16 v[34:37], v[202:205], v[166:169], v[34:37]
	v_mfma_f32_16x16x32_bf16 v[22:25], v[194:197], v[176:179], v[22:25]
	v_mfma_f32_16x16x32_bf16 v[18:21], v[202:205], v[176:179], v[18:21]
	v_mfma_f32_16x16x32_bf16 v[6:9], v[194:197], v[184:187], v[6:9]
	v_mfma_f32_16x16x32_bf16 v[2:5], v[202:205], v[184:187], v[2:5]
	v_mfma_f32_16x16x32_bf16 v[54:57], v[198:201], v[162:165], v[54:57]
	v_mfma_f32_16x16x32_bf16 v[50:53], v[206:209], v[162:165], v[50:53]
	v_mfma_f32_16x16x32_bf16 v[38:41], v[198:201], v[172:175], v[38:41]
	v_mfma_f32_16x16x32_bf16 v[34:37], v[206:209], v[172:175], v[34:37]
	v_mfma_f32_16x16x32_bf16 v[22:25], v[198:201], v[180:183], v[22:25]
	v_mfma_f32_16x16x32_bf16 v[18:21], v[206:209], v[180:183], v[18:21]
	v_mfma_f32_16x16x32_bf16 v[6:9], v[198:201], v[190:193], v[6:9]
	v_mfma_f32_16x16x32_bf16 v[2:5], v[206:209], v[190:193], v[2:5]
	s_add_i32 s85, s85, 2
	s_add_u32 s88, s88, 0x100
	s_addc_u32 s89, s89, 0
	s_add_u32 s34, s34, 0x100
	s_addc_u32 s79, s79, 0
	s_add_u32 s87, s88, 0xfffc0080
	s_addc_u32 s90, s89, -1
	s_cmp_eq_u32 s85, 12
	s_cselect_b32 s93, s13, s90
	s_cselect_b32 s92, s22, s87
	s_cselect_b32 s91, s7, s79
	s_cselect_b32 s90, s23, s34
	s_cmp_gt_u32 s85, 13
	s_barrier
	s_cbranch_scc0 .LBB0_1209
	s_waitcnt lgkmcnt(0)
	v_mov_b32_e32 v131, v252
	s_lshl_b32 s7, s86, 8
	v_and_b32_e32 v130, 63, v131
	v_or_b32_e32 v0, s72, v130
	v_lshrrev_b32_e32 v0, 1, v0
	v_and_or_b32 v132, v0, 63, s73
	v_add_u32_e32 v134, s7, v132
	v_ashrrev_i32_e32 v135, 31, v134
	v_and_b32_e32 v142, 1, v131
	v_lshlrev_b64 v[134:135], 6, v[134:135]
	v_lshl_add_u64 v[134:135], s[82:83], 0, v[134:135]
	v_lshlrev_b32_e32 v0, 5, v142
	v_lshl_add_u64 v[138:139], v[134:135], 0, v[0:1]
	global_load_dwordx4 v[134:137], v[138:139], off
	s_nop 0
	global_load_dwordx4 v[138:141], v[138:139], off offset:16
	v_lshlrev_b32_e32 v0, 2, v130
	v_cmp_eq_u32_e32 vcc, 0, v142
	s_waitcnt vmcnt(0)
	v_add_f32_e32 v133, v134, v135
	v_add_f32_e32 v134, v136, v137
	v_add_f32_e32 v135, v138, v139
	v_add_f32_e32 v136, v140, v141
	v_add_f32_e32 v133, v133, v134
	v_add_f32_e32 v134, v135, v136
	v_add_f32_e32 v133, v133, v134
	v_xor_b32_e32 v134, 4, v0
	ds_bpermute_b32 v134, v134, v133
	s_and_saveexec_b64 s[22:23], vcc
	s_cbranch_execz .LBB0_1212
	s_waitcnt lgkmcnt(0)
	v_add_f32_e32 v133, v133, v134
	v_fmamk_f32 v133, v133, 0x3a800000, v224
	s_mov_b32 s13, 0x800000
	v_mul_f32_e32 v134, 0x4b800000, v133
	v_cmp_gt_f32_e32 vcc, s13, v133
	v_lshl_add_u32 v132, v132, 2, 0
	v_add_u32_e32 v132, 0x20000, v132
	v_cndmask_b32_e32 v133, v133, v134, vcc
	v_rsq_f32_e32 v133, v133
	s_nop 0
	v_mul_f32_e32 v134, 0x45800000, v133
	v_cndmask_b32_e32 v133, v133, v134, vcc
	ds_write_b32 v132, v133
